# K-loop: next-tile pointer-select SALU block moved from phase 0's (heaviest) load segment to the head of phase 1's
# speedup vs baseline: 1.0147x; 1.0019x over previous
; #define PG8_STAGE(bufoff, gbase, voff) do { _Pragma("unroll") for (int _i = 0; _i < 2; ++_i) \
;         __builtin_amdgcn_global_load_lds((const unsigned*)((const char*)(gbase) + (voff)[_i]), (LAS unsigned*)(lds + (bufoff) + ldsw + _i * 8192), 16, 0, 0); } while (0)
; #define PG8_LDA(dst, b, h) do { _Pragma("unroll") for (int m = 0; m < 4; ++m) _Pragma("unroll") for (int k = 0; k < 2; ++k) dst[m][k] = *(const LAS bf16x8*)(lds + PG8_SA(b, h) + aoff + m * 2048 + k * 1024); } while (0)
; #define PG8_LDB(dst, b, h) do { _Pragma("unroll") for (int n = 0; n < 2; ++n) _Pragma("unroll") for (int k = 0; k < 2; ++k) dst[n][k] = *(const LAS bf16x8*)(lds + PG8_SB(b, h) + boff + n * 2048 + k * 1024); } while (0)
; #define PG8_WAIT_V(n) asm volatile("s_waitcnt vmcnt(" #n ")" ::: "memory")
; #define PG8_WAIT_L(n) asm volatile("s_waitcnt lgkmcnt(" #n ")" ::: "memory")
; #define PG8_BAR __builtin_amdgcn_s_barrier()
; #define PG8_SCHED __builtin_amdgcn_sched_barrier(0)
; template <class Epi>
; __device__ __forceinline__ void gemm_phase(LAS unsigned char* lds, const bf16_t* A, int lda, const bf16_t* Bt, int ldb, int M, int N, int K, int asel, const Epi& E, const int fixed_round = -1) {
;     ...
;         for (int t = 0; t < nt; t += 2) {
;             const bool last = (t == nt - 2);
;             const char* a1 = cA + (size_t)(t + 1) * kstep;
;             const char* a2 = last ? nA : cA + (size_t)(t + 2) * kstep; const char* b2 = last ? nB : cB + (size_t)(t + 2) * kstep;
;             const char* a3 = a2 + kstep; const char* b3 = b2 + kstep;
;             PG8_LDB(B0, 0, 0); PG8_SCHED; PG8_LDA(At, 0, 0); PG8_STAGE(PG8_SA(1, 1), a1 + hstepA, voffA);
;             PG8_WAIT_L(8); PG8_BAR; PG8_WAIT_L(0); PG8_MMA(0, 0, At, B0); PG8_BAR; PG8_SCHED;
;             PG8_LDB(B1, 0, 1); PG8_STAGE(PG8_SB(0, 0), b2, voffB);
;             PG8_BAR; PG8_WAIT_L(0); PG8_MMA(0, 1, At, B1); PG8_BAR;
;             PG8_LDA(At, 0, 1); PG8_STAGE(PG8_SA(0, 0), a2, voffA);
;             PG8_BAR; PG8_WAIT_L(0); PG8_MMA(1, 0, At, B0); PG8_BAR; PG8_SCHED;
;             PG8_STAGE(PG8_SB(0, 1), b2 + hstepB, voffB);
;             PG8_WAIT_V(6); PG8_BAR; PG8_MMA(1, 1, At, B1); PG8_BAR;
.LBB0_199:
	ds_read_b128 v[148:151], v161
	ds_read_b128 v[152:155], v161 offset:1024
	ds_read_b128 v[156:159], v161 offset:2048
	ds_read_b128 v[166:169], v161 offset:3072
	s_add_i32 m0, s39, 0xc000
	ds_read_b128 v[170:173], v162
	ds_read_b128 v[174:177], v162 offset:1024
	ds_read_b128 v[178:181], v162 offset:2048
	ds_read_b128 v[182:185], v162 offset:3072
	ds_read_b128 v[186:189], v162 offset:4096
	ds_read_b128 v[190:193], v162 offset:5120
	ds_read_b128 v[196:199], v162 offset:6144
	ds_read_b128 v[202:205], v162 offset:7168
	global_load_lds_dwordx4 v140, s[28:29]
	s_add_i32 m0, s39, 0xe000
	s_nop 0
	global_load_lds_dwordx4 v142, s[28:29]
	s_waitcnt lgkmcnt(8)
	s_barrier
	s_waitcnt lgkmcnt(0)
	s_setprio 1
	s_waitcnt lgkmcnt(0)
	v_mfma_f32_16x16x32_bf16 v[124:127], v[148:151], v[170:173], v[124:127]
	v_mfma_f32_16x16x32_bf16 v[120:123], v[156:159], v[170:173], v[120:123]
	v_mfma_f32_16x16x32_bf16 v[112:115], v[148:151], v[178:181], v[112:115]
	v_mfma_f32_16x16x32_bf16 v[108:111], v[156:159], v[178:181], v[108:111]
	v_mfma_f32_16x16x32_bf16 v[100:103], v[148:151], v[186:189], v[100:103]
	v_mfma_f32_16x16x32_bf16 v[92:95], v[156:159], v[186:189], v[92:95]
	v_mfma_f32_16x16x32_bf16 v[84:87], v[148:151], v[196:199], v[84:87]
	v_mfma_f32_16x16x32_bf16 v[76:79], v[156:159], v[196:199], v[76:79]
	v_mfma_f32_16x16x32_bf16 v[124:127], v[152:155], v[174:177], v[124:127]
	v_mfma_f32_16x16x32_bf16 v[120:123], v[166:169], v[174:177], v[120:123]
	v_mfma_f32_16x16x32_bf16 v[112:115], v[152:155], v[182:185], v[112:115]
	v_mfma_f32_16x16x32_bf16 v[108:111], v[166:169], v[182:185], v[108:111]
	v_mfma_f32_16x16x32_bf16 v[100:103], v[152:155], v[190:193], v[100:103]
	v_mfma_f32_16x16x32_bf16 v[92:95], v[166:169], v[190:193], v[92:95]
	v_mfma_f32_16x16x32_bf16 v[84:87], v[152:155], v[202:205], v[84:87]
	v_mfma_f32_16x16x32_bf16 v[76:79], v[166:169], v[202:205], v[76:79]
	s_setprio 0
	s_barrier
	s_add_u32 s30, s28, 0xfff80080
	s_addc_u32 s31, s29, -1
	s_cmp_eq_u32 s58, 28
	s_cselect_b32 s35, s4, s31
	s_cselect_b32 s34, s21, s30
	s_cselect_b32 s31, s19, s57
	s_cselect_b32 s30, s55, s56
	s_add_i32 s59, s46, s38
	s_add_u32 s98, s30, s6
	s_addc_u32 s99, s31, s7
	s_mov_b32 m0, s59
	ds_read_b128 v[206:209], v163
	ds_read_b128 v[210:213], v163 offset:1024
	ds_read_b128 v[214:217], v163 offset:2048
	ds_read_b128 v[218:221], v163 offset:3072
	global_load_lds_dwordx4 v130, s[30:31]
	s_add_i32 m0, s59, 0x2000
	s_nop 0
	global_load_lds_dwordx4 v134, s[30:31]
	s_barrier
	s_waitcnt lgkmcnt(0)
	s_setprio 1
	s_waitcnt lgkmcnt(0)
	v_mfma_f32_16x16x32_bf16 v[116:119], v[206:209], v[170:173], v[116:119]
	v_mfma_f32_16x16x32_bf16 v[104:107], v[214:217], v[170:173], v[104:107]
	v_mfma_f32_16x16x32_bf16 v[96:99], v[206:209], v[178:181], v[96:99]
	v_mfma_f32_16x16x32_bf16 v[88:91], v[214:217], v[178:181], v[88:91]
	v_mfma_f32_16x16x32_bf16 v[80:83], v[206:209], v[186:189], v[80:83]
	v_mfma_f32_16x16x32_bf16 v[72:75], v[214:217], v[186:189], v[72:75]
	v_mfma_f32_16x16x32_bf16 v[68:71], v[206:209], v[196:199], v[68:71]
	v_mfma_f32_16x16x32_bf16 v[64:67], v[214:217], v[196:199], v[64:67]
	v_mfma_f32_16x16x32_bf16 v[116:119], v[210:213], v[174:177], v[116:119]
	v_mfma_f32_16x16x32_bf16 v[104:107], v[218:221], v[174:177], v[104:107]
	v_mfma_f32_16x16x32_bf16 v[96:99], v[210:213], v[182:185], v[96:99]
	v_mfma_f32_16x16x32_bf16 v[88:91], v[218:221], v[182:185], v[88:91]
	v_mfma_f32_16x16x32_bf16 v[80:83], v[210:213], v[190:193], v[80:83]
	v_mfma_f32_16x16x32_bf16 v[72:75], v[218:221], v[190:193], v[72:75]
	v_mfma_f32_16x16x32_bf16 v[68:71], v[210:213], v[202:205], v[68:71]
	v_mfma_f32_16x16x32_bf16 v[64:67], v[218:221], v[202:205], v[64:67]
	s_setprio 0
	s_mov_b32 m0, s39
	s_add_u32 s100, s34, s6
	s_addc_u32 s101, s35, s7
	s_barrier
	ds_read_b128 v[170:173], v162 offset:16384
	ds_read_b128 v[174:177], v162 offset:17408
	ds_read_b128 v[178:181], v162 offset:18432
	ds_read_b128 v[182:185], v162 offset:19456
	ds_read_b128 v[186:189], v162 offset:20480
	ds_read_b128 v[190:193], v162 offset:21504
	ds_read_b128 v[196:199], v162 offset:22528
	ds_read_b128 v[202:205], v162 offset:23552
	global_load_lds_dwordx4 v128, s[34:35]
	s_mov_b32 m0, s40
	s_nop 0
	global_load_lds_dwordx4 v132, s[34:35]
	s_barrier
	s_waitcnt lgkmcnt(0)
	s_setprio 1
	s_waitcnt lgkmcnt(0)
	v_mfma_f32_16x16x32_bf16 v[60:63], v[148:151], v[170:173], v[60:63]
	v_mfma_f32_16x16x32_bf16 v[56:59], v[156:159], v[170:173], v[56:59]
	v_mfma_f32_16x16x32_bf16 v[52:55], v[148:151], v[178:181], v[52:55]
	v_mfma_f32_16x16x32_bf16 v[44:47], v[156:159], v[178:181], v[44:47]
	v_mfma_f32_16x16x32_bf16 v[36:39], v[148:151], v[186:189], v[36:39]
	v_mfma_f32_16x16x32_bf16 v[28:31], v[156:159], v[186:189], v[28:31]
	v_mfma_f32_16x16x32_bf16 v[20:23], v[148:151], v[196:199], v[20:23]
	v_mfma_f32_16x16x32_bf16 v[12:15], v[156:159], v[196:199], v[12:15]
	v_mfma_f32_16x16x32_bf16 v[60:63], v[152:155], v[174:177], v[60:63]
	v_mfma_f32_16x16x32_bf16 v[56:59], v[166:169], v[174:177], v[56:59]
	v_mfma_f32_16x16x32_bf16 v[52:55], v[152:155], v[182:185], v[52:55]
	v_mfma_f32_16x16x32_bf16 v[44:47], v[166:169], v[182:185], v[44:47]
	v_mfma_f32_16x16x32_bf16 v[36:39], v[152:155], v[190:193], v[36:39]
	v_mfma_f32_16x16x32_bf16 v[28:31], v[166:169], v[190:193], v[28:31]
	v_mfma_f32_16x16x32_bf16 v[20:23], v[152:155], v[202:205], v[20:23]
	v_mfma_f32_16x16x32_bf16 v[12:15], v[166:169], v[202:205], v[12:15]
	s_setprio 0
	s_barrier
	s_add_u32 s60, s30, 0x80000
	s_addc_u32 s61, s31, 0
	s_add_i32 s59, s47, s38
	s_mov_b32 m0, s59
	s_nop 0
	global_load_lds_dwordx4 v130, s[60:61]
	s_add_i32 m0, s59, 0x2000
	s_nop 0
	global_load_lds_dwordx4 v134, s[60:61]
	s_waitcnt vmcnt(6)
	s_barrier
; #define PG8_STAGE(bufoff, gbase, voff) do { _Pragma("unroll") for (int _i = 0; _i < 2; ++_i) \
;         __builtin_amdgcn_global_load_lds((const unsigned*)((const char*)(gbase) + (voff)[_i]), (LAS unsigned*)(lds + (bufoff) + ldsw + _i * 8192), 16, 0, 0); } while (0)
; #define PG8_LDA(dst, b, h) do { _Pragma("unroll") for (int m = 0; m < 4; ++m) _Pragma("unroll") for (int k = 0; k < 2; ++k) dst[m][k] = *(const LAS bf16x8*)(lds + PG8_SA(b, h) + aoff + m * 2048 + k * 1024); } while (0)
; #define PG8_LDB(dst, b, h) do { _Pragma("unroll") for (int n = 0; n < 2; ++n) _Pragma("unroll") for (int k = 0; k < 2; ++k) dst[n][k] = *(const LAS bf16x8*)(lds + PG8_SB(b, h) + boff + n * 2048 + k * 1024); } while (0)
; #define PG8_WAIT_V(n) asm volatile("s_waitcnt vmcnt(" #n ")" ::: "memory")
; #define PG8_WAIT_L(n) asm volatile("s_waitcnt lgkmcnt(" #n ")" ::: "memory")
; #define PG8_BAR __builtin_amdgcn_s_barrier()
; #define PG8_SCHED __builtin_amdgcn_sched_barrier(0)
; template <class Epi>
; __device__ __forceinline__ void gemm_phase(LAS unsigned char* lds, const bf16_t* A, int lda, const bf16_t* Bt, int ldb, int M, int N, int K, int asel, const Epi& E, const int fixed_round = -1) {
;     ...
;             PG8_WAIT_V(6); PG8_BAR; PG8_MMA(1, 1, At, B1); PG8_BAR;
;             PG8_LDB(B0, 1, 0); PG8_SCHED; PG8_LDA(At, 1, 0); PG8_STAGE(PG8_SA(0, 1), a2 + hstepA, voffA);
;             PG8_WAIT_L(8); PG8_BAR; PG8_WAIT_L(0); PG8_MMA(0, 0, At, B0); PG8_BAR; PG8_SCHED;
;             PG8_LDB(B1, 1, 1); PG8_STAGE(PG8_SB(1, 0), b3, voffB);
;             PG8_BAR; PG8_WAIT_L(0); PG8_MMA(0, 1, At, B1); PG8_BAR;
;             PG8_LDA(At, 1, 1); PG8_STAGE(PG8_SA(1, 0), a3, voffA);
;             PG8_BAR; PG8_WAIT_L(0); PG8_MMA(1, 0, At, B0); PG8_BAR; PG8_SCHED;
	s_setprio 1
	v_mfma_f32_16x16x32_bf16 v[48:51], v[206:209], v[170:173], v[48:51]
	v_mfma_f32_16x16x32_bf16 v[40:43], v[214:217], v[170:173], v[40:43]
	v_mfma_f32_16x16x32_bf16 v[32:35], v[206:209], v[178:181], v[32:35]
	v_mfma_f32_16x16x32_bf16 v[24:27], v[214:217], v[178:181], v[24:27]
	v_mfma_f32_16x16x32_bf16 v[16:19], v[206:209], v[186:189], v[16:19]
	v_mfma_f32_16x16x32_bf16 v[8:11], v[214:217], v[186:189], v[8:11]
	v_mfma_f32_16x16x32_bf16 v[4:7], v[206:209], v[196:199], v[4:7]
	v_mfma_f32_16x16x32_bf16 v[0:3], v[214:217], v[196:199], v[0:3]
	v_mfma_f32_16x16x32_bf16 v[48:51], v[210:213], v[174:177], v[48:51]
	v_mfma_f32_16x16x32_bf16 v[40:43], v[218:221], v[174:177], v[40:43]
	v_mfma_f32_16x16x32_bf16 v[32:35], v[210:213], v[182:185], v[32:35]
	v_mfma_f32_16x16x32_bf16 v[24:27], v[218:221], v[182:185], v[24:27]
	v_mfma_f32_16x16x32_bf16 v[16:19], v[210:213], v[190:193], v[16:19]
	v_mfma_f32_16x16x32_bf16 v[8:11], v[218:221], v[190:193], v[8:11]
	v_mfma_f32_16x16x32_bf16 v[4:7], v[210:213], v[202:205], v[4:7]
	v_mfma_f32_16x16x32_bf16 v[0:3], v[218:221], v[202:205], v[0:3]
	s_setprio 0
	s_add_i32 s59, 0, 0x18000
	v_add_u32_e32 v136, s59, v160
	s_barrier
	ds_read_b128 v[148:151], v136
	ds_read_b128 v[152:155], v136 offset:1024
	ds_read_b128 v[156:159], v136 offset:2048
	ds_read_b128 v[166:169], v136 offset:3072
	s_add_u32 s34, s34, 0x80000
	s_addc_u32 s35, s35, 0
	s_mov_b32 m0, s41
	ds_read_b128 v[170:173], v162 offset:32768
	ds_read_b128 v[174:177], v162 offset:33792
	ds_read_b128 v[178:181], v162 offset:34816
	ds_read_b128 v[182:185], v162 offset:35840
	ds_read_b128 v[186:189], v162 offset:36864
	ds_read_b128 v[190:193], v162 offset:37888
	ds_read_b128 v[196:199], v162 offset:38912
	ds_read_b128 v[202:205], v162 offset:39936
	global_load_lds_dwordx4 v128, s[34:35]
	s_mov_b32 m0, s42
	s_nop 0
	global_load_lds_dwordx4 v132, s[34:35]
	s_waitcnt lgkmcnt(8)
	s_barrier
	s_waitcnt lgkmcnt(0)
	s_setprio 1
	s_waitcnt lgkmcnt(0)
	v_mfma_f32_16x16x32_bf16 v[124:127], v[148:151], v[170:173], v[124:127]
	v_mfma_f32_16x16x32_bf16 v[120:123], v[156:159], v[170:173], v[120:123]
	v_mfma_f32_16x16x32_bf16 v[112:115], v[148:151], v[178:181], v[112:115]
	v_mfma_f32_16x16x32_bf16 v[108:111], v[156:159], v[178:181], v[108:111]
	v_mfma_f32_16x16x32_bf16 v[100:103], v[148:151], v[186:189], v[100:103]
	v_mfma_f32_16x16x32_bf16 v[92:95], v[156:159], v[186:189], v[92:95]
	v_mfma_f32_16x16x32_bf16 v[84:87], v[148:151], v[196:199], v[84:87]
	v_mfma_f32_16x16x32_bf16 v[76:79], v[156:159], v[196:199], v[76:79]
	v_mfma_f32_16x16x32_bf16 v[124:127], v[152:155], v[174:177], v[124:127]
	v_mfma_f32_16x16x32_bf16 v[120:123], v[166:169], v[174:177], v[120:123]
	v_mfma_f32_16x16x32_bf16 v[112:115], v[152:155], v[182:185], v[112:115]
	v_mfma_f32_16x16x32_bf16 v[108:111], v[166:169], v[182:185], v[108:111]
	v_mfma_f32_16x16x32_bf16 v[100:103], v[152:155], v[190:193], v[100:103]
	v_mfma_f32_16x16x32_bf16 v[92:95], v[166:169], v[190:193], v[92:95]
	v_mfma_f32_16x16x32_bf16 v[84:87], v[152:155], v[202:205], v[84:87]
	v_mfma_f32_16x16x32_bf16 v[76:79], v[166:169], v[202:205], v[76:79]
	s_setprio 0
	s_barrier
	s_add_i32 s34, 0, 0x1c000
	s_add_i32 s35, s59, s38
	v_add_u32_e32 v136, s34, v160
	s_mov_b32 m0, s35
	ds_read_b128 v[206:209], v136
	ds_read_b128 v[210:213], v136 offset:1024
	ds_read_b128 v[214:217], v136 offset:2048
	ds_read_b128 v[218:221], v136 offset:3072
	global_load_lds_dwordx4 v130, s[98:99]
	s_add_i32 m0, s35, 0x2000
	s_nop 0
	global_load_lds_dwordx4 v134, s[98:99]
	s_barrier
	s_waitcnt lgkmcnt(0)
	s_setprio 1
	s_waitcnt lgkmcnt(0)
	v_mfma_f32_16x16x32_bf16 v[116:119], v[206:209], v[170:173], v[116:119]
	v_mfma_f32_16x16x32_bf16 v[104:107], v[214:217], v[170:173], v[104:107]
	v_mfma_f32_16x16x32_bf16 v[96:99], v[206:209], v[178:181], v[96:99]
	v_mfma_f32_16x16x32_bf16 v[88:91], v[214:217], v[178:181], v[88:91]
	v_mfma_f32_16x16x32_bf16 v[80:83], v[206:209], v[186:189], v[80:83]
	v_mfma_f32_16x16x32_bf16 v[72:75], v[214:217], v[186:189], v[72:75]
	v_mfma_f32_16x16x32_bf16 v[68:71], v[206:209], v[196:199], v[68:71]
	v_mfma_f32_16x16x32_bf16 v[64:67], v[214:217], v[196:199], v[64:67]
	v_mfma_f32_16x16x32_bf16 v[116:119], v[210:213], v[174:177], v[116:119]
	v_mfma_f32_16x16x32_bf16 v[104:107], v[218:221], v[174:177], v[104:107]
	v_mfma_f32_16x16x32_bf16 v[96:99], v[210:213], v[182:185], v[96:99]
	v_mfma_f32_16x16x32_bf16 v[88:91], v[218:221], v[182:185], v[88:91]
	v_mfma_f32_16x16x32_bf16 v[80:83], v[210:213], v[190:193], v[80:83]
	v_mfma_f32_16x16x32_bf16 v[72:75], v[218:221], v[190:193], v[72:75]
	v_mfma_f32_16x16x32_bf16 v[68:71], v[210:213], v[202:205], v[68:71]
	v_mfma_f32_16x16x32_bf16 v[64:67], v[218:221], v[202:205], v[64:67]
	s_setprio 0
	s_mov_b32 m0, s43
	s_barrier
	ds_read_b128 v[170:173], v162 offset:49152
	ds_read_b128 v[174:177], v162 offset:50176
	ds_read_b128 v[178:181], v162 offset:51200
	ds_read_b128 v[182:185], v162 offset:52224
	ds_read_b128 v[186:189], v162 offset:53248
	ds_read_b128 v[190:193], v162 offset:54272
	ds_read_b128 v[196:199], v162 offset:55296
	ds_read_b128 v[202:205], v162 offset:56320
	global_load_lds_dwordx4 v128, s[100:101]
	s_mov_b32 m0, s44
	s_nop 0
	global_load_lds_dwordx4 v132, s[100:101]
	s_barrier
; __device__ __forceinline__ unsigned cvt_pk_bf16(float lo, float hi) { const bf16x2_t r = __builtin_convertvector((f32x2){lo, hi}, bf16x2_t); return __builtin_bit_cast(unsigned, r); }
; #define PG8_STAGE(bufoff, gbase, voff) do { _Pragma("unroll") for (int _i = 0; _i < 2; ++_i) \
;         __builtin_amdgcn_global_load_lds((const unsigned*)((const char*)(gbase) + (voff)[_i]), (LAS unsigned*)(lds + (bufoff) + ldsw + _i * 8192), 16, 0, 0); } while (0)
; #define PG8_WAIT_V(n) asm volatile("s_waitcnt vmcnt(" #n ")" ::: "memory")
; #define PG8_WAIT_L(n) asm volatile("s_waitcnt lgkmcnt(" #n ")" ::: "memory")
; #define PG8_BAR __builtin_amdgcn_s_barrier()
; #define PG8_SCHED __builtin_amdgcn_sched_barrier(0)
; template <class Epi>
; __device__ __forceinline__ void gemm_phase(LAS unsigned char* lds, const bf16_t* A, int lda, const bf16_t* Bt, int ldb, int M, int N, int K, int asel, const Epi& E, const int fixed_round = -1) {
;     ...
;             PG8_BAR; PG8_WAIT_L(0); PG8_MMA(1, 0, At, B0); PG8_BAR; PG8_SCHED;
;             PG8_STAGE(PG8_SB(1, 1), b3 + hstepB, voffB);
;             PG8_WAIT_V(6); PG8_BAR; PG8_MMA(1, 1, At, B1); PG8_BAR;
;     __device__ __forceinline__ void operator()(const AccT& acc, const Unit& u, int wr, int wc, int fr, int fq) const {
;     ...
;         if (pn < 8) {
;             bf16_t* base = pn < 4 ? Q : Kn; const int colt = (pn & 3) * BM; const float sc = pn < 4 ? 0.08838834764831845f : 1.0f;
; #pragma unroll
;             for (int ai = 0; ai < 2; ++ai)
; #pragma unroll
;                 for (int m = 0; m < 4; ++m) { bf16_t* rowp = base + (size_t)(row0 + ai * HALF + m * 16) * 1024 + colt + cl;
; #pragma unroll
;                     for (int bj = 0; bj < 2; ++bj) { const f32x4 v0 = acc[ai][bj][m][0] * sc, v1 = acc[ai][bj][m][1] * sc;
;                         u32x4 w; w.x = cvt_pk_bf16(v0[0], v0[1]); w.y = cvt_pk_bf16(v0[2], v0[3]); w.z = cvt_pk_bf16(v1[0], v1[1]); w.w = cvt_pk_bf16(v1[2], v1[3]);
;                         *(u32x4*)(rowp + bj * HALF) = w; } }
	s_waitcnt lgkmcnt(0)
	s_setprio 1
	s_waitcnt lgkmcnt(0)
	v_mfma_f32_16x16x32_bf16 v[60:63], v[148:151], v[170:173], v[60:63]
	v_mfma_f32_16x16x32_bf16 v[56:59], v[156:159], v[170:173], v[56:59]
	v_mfma_f32_16x16x32_bf16 v[52:55], v[148:151], v[178:181], v[52:55]
	v_mfma_f32_16x16x32_bf16 v[44:47], v[156:159], v[178:181], v[44:47]
	v_mfma_f32_16x16x32_bf16 v[36:39], v[148:151], v[186:189], v[36:39]
	v_mfma_f32_16x16x32_bf16 v[28:31], v[156:159], v[186:189], v[28:31]
	v_mfma_f32_16x16x32_bf16 v[20:23], v[148:151], v[196:199], v[20:23]
	v_mfma_f32_16x16x32_bf16 v[12:15], v[156:159], v[196:199], v[12:15]
	v_mfma_f32_16x16x32_bf16 v[60:63], v[152:155], v[174:177], v[60:63]
	v_mfma_f32_16x16x32_bf16 v[56:59], v[166:169], v[174:177], v[56:59]
	v_mfma_f32_16x16x32_bf16 v[52:55], v[152:155], v[182:185], v[52:55]
	v_mfma_f32_16x16x32_bf16 v[44:47], v[166:169], v[182:185], v[44:47]
	v_mfma_f32_16x16x32_bf16 v[36:39], v[152:155], v[190:193], v[36:39]
	v_mfma_f32_16x16x32_bf16 v[28:31], v[166:169], v[190:193], v[28:31]
	v_mfma_f32_16x16x32_bf16 v[20:23], v[152:155], v[202:205], v[20:23]
	v_mfma_f32_16x16x32_bf16 v[12:15], v[166:169], v[202:205], v[12:15]
	s_setprio 0
	s_barrier
	s_add_u32 s30, s30, 0x80080
	s_addc_u32 s31, s31, 0
	s_add_i32 s34, s34, s38
	s_mov_b32 m0, s34
	s_nop 0
	global_load_lds_dwordx4 v130, s[30:31]
	s_add_i32 m0, s34, 0x2000
	s_nop 0
	global_load_lds_dwordx4 v134, s[30:31]
	s_waitcnt vmcnt(6)
	s_barrier
	s_setprio 1
	v_mfma_f32_16x16x32_bf16 v[48:51], v[206:209], v[170:173], v[48:51]
	v_mfma_f32_16x16x32_bf16 v[40:43], v[214:217], v[170:173], v[40:43]
	v_mfma_f32_16x16x32_bf16 v[32:35], v[206:209], v[178:181], v[32:35]
	v_mfma_f32_16x16x32_bf16 v[24:27], v[214:217], v[178:181], v[24:27]
	v_mfma_f32_16x16x32_bf16 v[16:19], v[206:209], v[186:189], v[16:19]
	v_mfma_f32_16x16x32_bf16 v[8:11], v[214:217], v[186:189], v[8:11]
	v_mfma_f32_16x16x32_bf16 v[4:7], v[206:209], v[196:199], v[4:7]
	v_mfma_f32_16x16x32_bf16 v[0:3], v[214:217], v[196:199], v[0:3]
	v_mfma_f32_16x16x32_bf16 v[48:51], v[210:213], v[174:177], v[48:51]
	v_mfma_f32_16x16x32_bf16 v[40:43], v[218:221], v[174:177], v[40:43]
	v_mfma_f32_16x16x32_bf16 v[32:35], v[210:213], v[182:185], v[32:35]
	v_mfma_f32_16x16x32_bf16 v[24:27], v[218:221], v[182:185], v[24:27]
	v_mfma_f32_16x16x32_bf16 v[16:19], v[210:213], v[190:193], v[16:19]
	v_mfma_f32_16x16x32_bf16 v[8:11], v[218:221], v[190:193], v[8:11]
	v_mfma_f32_16x16x32_bf16 v[4:7], v[210:213], v[202:205], v[4:7]
	v_mfma_f32_16x16x32_bf16 v[0:3], v[218:221], v[202:205], v[0:3]
	s_setprio 0
	s_add_i32 s58, s58, 2
	s_add_u32 s28, s28, 0x100
	s_addc_u32 s29, s29, 0
	s_add_u32 s56, s56, 0x100
	s_addc_u32 s57, s57, 0
	s_cmp_gt_u32 s58, 29
	s_cbranch_scc0 .Lrot_1
	s_barrier
	s_lshl_b32 s19, s26, 8
	v_add_u32_e32 v154, s19, v139
	s_cmp_lt_i32 s27, 8
	v_or_b32_e32 v152, 16, v154
	v_or_b32_e32 v150, 32, v154
	v_or_b32_e32 v148, 48, v154
	s_cselect_b64 s[28:29], -1, 0
	s_cmp_gt_i32 s27, 7
	v_ashrrev_i32_e32 v155, 31, v154
	v_lshlrev_b32_e32 v136, 1, v138
	v_ashrrev_i32_e32 v153, 31, v152
	v_ashrrev_i32_e32 v151, 31, v150
	v_ashrrev_i32_e32 v149, 31, v148
	s_cbranch_scc1 .LBB0_203
	s_cmp_lt_i32 s27, 4
	s_cselect_b64 vcc, -1, 0
	s_and_b64 s[30:31], vcc, exec
	s_cselect_b32 s4, s89, s81
	s_cselect_b32 s21, s88, s91
	s_lshl_b32 s30, s27, 9
	s_and_b32 s30, s30, 0x600
	s_add_u32 s30, s21, s30
	v_cndmask_b32_e32 v156, 1.0, v164, vcc
	s_addc_u32 s31, s4, 0
	v_lshl_add_u64 v[170:171], s[30:31], 0, v[136:137]
	v_lshlrev_b64 v[158:159], 11, v[154:155]
	v_pk_mul_f32 v[168:169], v[156:157], v[126:127] op_sel_hi:[0,1]
	v_pk_mul_f32 v[166:167], v[156:157], v[124:125] op_sel_hi:[0,1]
	v_pk_mul_f32 v[172:173], v[156:157], v[122:123] op_sel_hi:[0,1]
	v_pk_mul_f32 v[174:175], v[156:157], v[120:121] op_sel_hi:[0,1]
	v_lshl_add_u64 v[158:159], v[170:171], 0, v[158:159]
	v_cvt_pk_bf16_f32 v166, v166, v167
	v_cvt_pk_bf16_f32 v167, v168, v169
	v_cvt_pk_bf16_f32 v168, v174, v175
	v_cvt_pk_bf16_f32 v169, v172, v173
	global_store_dwordx4 v[158:159], v[166:169], off
	v_pk_mul_f32 v[172:173], v[156:157], v[106:107] op_sel_hi:[0,1]
	v_pk_mul_f32 v[174:175], v[156:157], v[104:105] op_sel_hi:[0,1]
	v_pk_mul_f32 v[168:169], v[156:157], v[118:119] op_sel_hi:[0,1]
	v_pk_mul_f32 v[166:167], v[156:157], v[116:117] op_sel_hi:[0,1]
	v_cvt_pk_bf16_f32 v166, v166, v167
	v_cvt_pk_bf16_f32 v167, v168, v169
	v_cvt_pk_bf16_f32 v168, v174, v175
	v_cvt_pk_bf16_f32 v169, v172, v173
	global_store_dwordx4 v[158:159], v[166:169], off offset:256
	v_pk_mul_f32 v[174:175], v[156:157], v[110:111] op_sel_hi:[0,1]
	v_pk_mul_f32 v[176:177], v[156:157], v[108:109] op_sel_hi:[0,1]
	v_lshlrev_b64 v[166:167], 11, v[152:153]
	v_lshl_add_u64 v[172:173], v[170:171], 0, v[166:167]
	v_pk_mul_f32 v[168:169], v[156:157], v[114:115] op_sel_hi:[0,1]
	v_pk_mul_f32 v[166:167], v[156:157], v[112:113] op_sel_hi:[0,1]
	v_cvt_pk_bf16_f32 v166, v166, v167
	v_cvt_pk_bf16_f32 v167, v168, v169
	v_cvt_pk_bf16_f32 v168, v176, v177
	v_cvt_pk_bf16_f32 v169, v174, v175
	global_store_dwordx4 v[172:173], v[166:169], off
	v_pk_mul_f32 v[174:175], v[156:157], v[90:91] op_sel_hi:[0,1]
	v_pk_mul_f32 v[176:177], v[156:157], v[88:89] op_sel_hi:[0,1]
	v_pk_mul_f32 v[168:169], v[156:157], v[98:99] op_sel_hi:[0,1]
	v_pk_mul_f32 v[166:167], v[156:157], v[96:97] op_sel_hi:[0,1]
	v_cvt_pk_bf16_f32 v166, v166, v167
	v_cvt_pk_bf16_f32 v167, v168, v169
	v_cvt_pk_bf16_f32 v168, v176, v177
	v_cvt_pk_bf16_f32 v169, v174, v175
	global_store_dwordx4 v[172:173], v[166:169], off offset:256
	v_pk_mul_f32 v[174:175], v[156:157], v[94:95] op_sel_hi:[0,1]
	v_pk_mul_f32 v[176:177], v[156:157], v[92:93] op_sel_hi:[0,1]
	v_lshlrev_b64 v[166:167], 11, v[150:151]
; __device__ __forceinline__ unsigned cvt_pk_bf16(float lo, float hi) { const bf16x2_t r = __builtin_convertvector((f32x2){lo, hi}, bf16x2_t); return __builtin_bit_cast(unsigned, r); }
;     __device__ __forceinline__ void operator()(const AccT& acc, const Unit& u, int wr, int wc, int fr, int fq) const {
;     ...
;         if (pn < 8) {
;             bf16_t* base = pn < 4 ? Q : Kn; const int colt = (pn & 3) * BM; const float sc = pn < 4 ? 0.08838834764831845f : 1.0f;
; #pragma unroll
;             for (int ai = 0; ai < 2; ++ai)
; #pragma unroll
;                 for (int m = 0; m < 4; ++m) { bf16_t* rowp = base + (size_t)(row0 + ai * HALF + m * 16) * 1024 + colt + cl;
; #pragma unroll
;                     for (int bj = 0; bj < 2; ++bj) { const f32x4 v0 = acc[ai][bj][m][0] * sc, v1 = acc[ai][bj][m][1] * sc;
;                         u32x4 w; w.x = cvt_pk_bf16(v0[0], v0[1]); w.y = cvt_pk_bf16(v0[2], v0[3]); w.z = cvt_pk_bf16(v1[0], v1[1]); w.w = cvt_pk_bf16(v1[2], v1[3]);
;                         *(u32x4*)(rowp + bj * HALF) = w; } }
;         }
;         if (pn >= 16) {
	v_lshl_add_u64 v[172:173], v[170:171], 0, v[166:167]
	v_pk_mul_f32 v[168:169], v[156:157], v[102:103] op_sel_hi:[0,1]
	v_pk_mul_f32 v[166:167], v[156:157], v[100:101] op_sel_hi:[0,1]
	v_cvt_pk_bf16_f32 v166, v166, v167
	v_cvt_pk_bf16_f32 v167, v168, v169
	v_cvt_pk_bf16_f32 v168, v176, v177
	v_cvt_pk_bf16_f32 v169, v174, v175
	global_store_dwordx4 v[172:173], v[166:169], off
	v_pk_mul_f32 v[174:175], v[156:157], v[74:75] op_sel_hi:[0,1]
	v_pk_mul_f32 v[176:177], v[156:157], v[72:73] op_sel_hi:[0,1]
	v_pk_mul_f32 v[168:169], v[156:157], v[82:83] op_sel_hi:[0,1]
	v_pk_mul_f32 v[166:167], v[156:157], v[80:81] op_sel_hi:[0,1]
	v_cvt_pk_bf16_f32 v166, v166, v167
	v_cvt_pk_bf16_f32 v167, v168, v169
	v_cvt_pk_bf16_f32 v168, v176, v177
	v_cvt_pk_bf16_f32 v169, v174, v175
	global_store_dwordx4 v[172:173], v[166:169], off offset:256
	v_pk_mul_f32 v[172:173], v[156:157], v[78:79] op_sel_hi:[0,1]
	v_pk_mul_f32 v[174:175], v[156:157], v[76:77] op_sel_hi:[0,1]
	v_lshlrev_b64 v[166:167], 11, v[148:149]
	v_lshl_add_u64 v[170:171], v[170:171], 0, v[166:167]
	v_pk_mul_f32 v[168:169], v[156:157], v[86:87] op_sel_hi:[0,1]
	v_pk_mul_f32 v[166:167], v[156:157], v[84:85] op_sel_hi:[0,1]
	v_cvt_pk_bf16_f32 v166, v166, v167
	v_cvt_pk_bf16_f32 v167, v168, v169
	v_cvt_pk_bf16_f32 v168, v174, v175
	v_cvt_pk_bf16_f32 v169, v172, v173
	global_store_dwordx4 v[170:171], v[166:169], off
	v_pk_mul_f32 v[172:173], v[156:157], v[66:67] op_sel_hi:[0,1]
	v_pk_mul_f32 v[174:175], v[156:157], v[64:65] op_sel_hi:[0,1]
	v_pk_mul_f32 v[168:169], v[156:157], v[70:71] op_sel_hi:[0,1]
	v_pk_mul_f32 v[166:167], v[156:157], v[68:69] op_sel_hi:[0,1]
	v_cvt_pk_bf16_f32 v166, v166, v167
	v_cvt_pk_bf16_f32 v167, v168, v169
	v_cvt_pk_bf16_f32 v168, v174, v175
	v_cvt_pk_bf16_f32 v169, v172, v173
	global_store_dwordx4 v[170:171], v[166:169], off offset:256
	v_pk_mul_f32 v[172:173], v[156:157], v[58:59] op_sel_hi:[0,1]
	s_mov_b32 s4, 0x40000
	v_pk_mul_f32 v[168:169], v[156:157], v[62:63] op_sel_hi:[0,1]
	v_pk_mul_f32 v[166:167], v[156:157], v[60:61] op_sel_hi:[0,1]
	v_pk_mul_f32 v[174:175], v[156:157], v[56:57] op_sel_hi:[0,1]
	v_cvt_pk_bf16_f32 v166, v166, v167
	v_cvt_pk_bf16_f32 v167, v168, v169
	v_cvt_pk_bf16_f32 v169, v172, v173
	v_add_co_u32_e32 v172, vcc, s4, v158
	v_cvt_pk_bf16_f32 v168, v174, v175
	s_nop 0
	v_addc_co_u32_e32 v173, vcc, 0, v159, vcc
	s_mov_b64 s[30:31], 0x40000
	global_store_dwordx4 v[172:173], v[166:169], off
	v_pk_mul_f32 v[172:173], v[156:157], v[42:43] op_sel_hi:[0,1]
	v_pk_mul_f32 v[174:175], v[156:157], v[40:41] op_sel_hi:[0,1]
	v_pk_mul_f32 v[168:169], v[156:157], v[50:51] op_sel_hi:[0,1]
	v_pk_mul_f32 v[166:167], v[156:157], v[48:49] op_sel_hi:[0,1]
	v_lshl_add_u64 v[170:171], v[158:159], 0, s[30:31]
	v_cvt_pk_bf16_f32 v166, v166, v167
	v_cvt_pk_bf16_f32 v167, v168, v169
	v_cvt_pk_bf16_f32 v168, v174, v175
	v_cvt_pk_bf16_f32 v169, v172, v173
	global_store_dwordx4 v[170:171], v[166:169], off offset:256
	v_pk_mul_f32 v[172:173], v[156:157], v[46:47] op_sel_hi:[0,1]
	s_mov_b32 s4, 0x48000
	v_pk_mul_f32 v[168:169], v[156:157], v[54:55] op_sel_hi:[0,1]
	v_pk_mul_f32 v[166:167], v[156:157], v[52:53] op_sel_hi:[0,1]
	v_pk_mul_f32 v[174:175], v[156:157], v[44:45] op_sel_hi:[0,1]
	v_cvt_pk_bf16_f32 v166, v166, v167
	v_cvt_pk_bf16_f32 v167, v168, v169
	v_cvt_pk_bf16_f32 v169, v172, v173
	v_add_co_u32_e32 v172, vcc, s4, v158
	v_cvt_pk_bf16_f32 v168, v174, v175
	s_nop 0
	v_addc_co_u32_e32 v173, vcc, 0, v159, vcc
	s_mov_b64 s[30:31], 0x48000
	global_store_dwordx4 v[172:173], v[166:169], off
	v_pk_mul_f32 v[172:173], v[156:157], v[26:27] op_sel_hi:[0,1]
	v_pk_mul_f32 v[174:175], v[156:157], v[24:25] op_sel_hi:[0,1]
	v_pk_mul_f32 v[168:169], v[156:157], v[34:35] op_sel_hi:[0,1]
	v_pk_mul_f32 v[166:167], v[156:157], v[32:33] op_sel_hi:[0,1]
	v_lshl_add_u64 v[170:171], v[158:159], 0, s[30:31]
	v_cvt_pk_bf16_f32 v166, v166, v167
	v_cvt_pk_bf16_f32 v167, v168, v169
	v_cvt_pk_bf16_f32 v168, v174, v175
	v_cvt_pk_bf16_f32 v169, v172, v173
	global_store_dwordx4 v[170:171], v[166:169], off offset:256
	v_pk_mul_f32 v[172:173], v[156:157], v[30:31] op_sel_hi:[0,1]
	v_pk_mul_f32 v[174:175], v[156:157], v[28:29] op_sel_hi:[0,1]
	v_pk_mul_f32 v[168:169], v[156:157], v[38:39] op_sel_hi:[0,1]
	v_pk_mul_f32 v[166:167], v[156:157], v[36:37] op_sel_hi:[0,1]
	v_cvt_pk_bf16_f32 v166, v166, v167
	v_cvt_pk_bf16_f32 v167, v168, v169
	v_cvt_pk_bf16_f32 v169, v172, v173
	v_add_co_u32_e32 v172, vcc, s48, v158
	v_cvt_pk_bf16_f32 v168, v174, v175
	s_nop 0
	v_addc_co_u32_e32 v173, vcc, 0, v159, vcc
	global_store_dwordx4 v[172:173], v[166:169], off
	v_pk_mul_f32 v[172:173], v[156:157], v[10:11] op_sel_hi:[0,1]
	v_pk_mul_f32 v[174:175], v[156:157], v[8:9] op_sel_hi:[0,1]
	v_pk_mul_f32 v[168:169], v[156:157], v[18:19] op_sel_hi:[0,1]
	v_pk_mul_f32 v[166:167], v[156:157], v[16:17] op_sel_hi:[0,1]
	v_lshl_add_u64 v[170:171], v[158:159], 0, s[8:9]
	v_cvt_pk_bf16_f32 v166, v166, v167
	v_cvt_pk_bf16_f32 v167, v168, v169
	v_cvt_pk_bf16_f32 v168, v174, v175
	v_cvt_pk_bf16_f32 v169, v172, v173
	global_store_dwordx4 v[170:171], v[166:169], off offset:256
	v_lshl_add_u64 v[170:171], v[158:159], 0, s[10:11]
	v_pk_mul_f32 v[172:173], v[156:157], v[14:15] op_sel_hi:[0,1]
	v_pk_mul_f32 v[168:169], v[156:157], v[22:23] op_sel_hi:[0,1]
	v_pk_mul_f32 v[166:167], v[156:157], v[20:21] op_sel_hi:[0,1]
	v_pk_mul_f32 v[174:175], v[156:157], v[12:13] op_sel_hi:[0,1]
	v_add_co_u32_e32 v158, vcc, s49, v158
	v_cvt_pk_bf16_f32 v166, v166, v167
	v_cvt_pk_bf16_f32 v167, v168, v169
	v_cvt_pk_bf16_f32 v168, v174, v175
	v_cvt_pk_bf16_f32 v169, v172, v173
	v_addc_co_u32_e32 v159, vcc, 0, v159, vcc
	global_store_dwordx4 v[158:159], v[166:169], off
	v_pk_mul_f32 v[158:159], v[156:157], v[6:7] op_sel_hi:[0,1]
	v_pk_mul_f32 v[172:173], v[156:157], v[0:1] op_sel_hi:[0,1]
	v_pk_mul_f32 v[166:167], v[156:157], v[4:5] op_sel_hi:[0,1]
	v_pk_mul_f32 v[168:169], v[156:157], v[2:3] op_sel_hi:[0,1]
	v_cvt_pk_bf16_f32 v156, v166, v167
	v_cvt_pk_bf16_f32 v157, v158, v159
	v_cvt_pk_bf16_f32 v158, v172, v173
	v_cvt_pk_bf16_f32 v159, v168, v169
	global_store_dwordx4 v[170:171], v[156:159], off offset:256
	s_cmp_lt_i32 s27, 16
	s_cbranch_scc0 .LBB0_204

; #define PG8_STAGE(bufoff, gbase, voff) do { _Pragma("unroll") for (int _i = 0; _i < 2; ++_i) \
;         __builtin_amdgcn_global_load_lds((const unsigned*)((const char*)(gbase) + (voff)[_i]), (LAS unsigned*)(lds + (bufoff) + ldsw + _i * 8192), 16, 0, 0); } while (0)
; #define PG8_LDA(dst, b, h) do { _Pragma("unroll") for (int m = 0; m < 4; ++m) _Pragma("unroll") for (int k = 0; k < 2; ++k) dst[m][k] = *(const LAS bf16x8*)(lds + PG8_SA(b, h) + aoff + m * 2048 + k * 1024); } while (0)
; #define PG8_LDB(dst, b, h) do { _Pragma("unroll") for (int n = 0; n < 2; ++n) _Pragma("unroll") for (int k = 0; k < 2; ++k) dst[n][k] = *(const LAS bf16x8*)(lds + PG8_SB(b, h) + boff + n * 2048 + k * 1024); } while (0)
; #define PG8_WAIT_V(n) asm volatile("s_waitcnt vmcnt(" #n ")" ::: "memory")
; #define PG8_WAIT_L(n) asm volatile("s_waitcnt lgkmcnt(" #n ")" ::: "memory")
; #define PG8_BAR __builtin_amdgcn_s_barrier()
; #define PG8_SCHED __builtin_amdgcn_sched_barrier(0)
; template <class Epi>
; __device__ __forceinline__ void gemm_phase(LAS unsigned char* lds, const bf16_t* A, int lda, const bf16_t* Bt, int ldb, int M, int N, int K, int asel, const Epi& E, const int fixed_round = -1) {
;     ...
;         for (int t = 0; t < nt; t += 2) {
;             const bool last = (t == nt - 2);
;             const char* a1 = cA + (size_t)(t + 1) * kstep;
;             const char* a2 = last ? nA : cA + (size_t)(t + 2) * kstep; const char* b2 = last ? nB : cB + (size_t)(t + 2) * kstep;
;             const char* a3 = a2 + kstep; const char* b3 = b2 + kstep;
;             PG8_LDB(B0, 0, 0); PG8_SCHED; PG8_LDA(At, 0, 0); PG8_STAGE(PG8_SA(1, 1), a1 + hstepA, voffA);
;             PG8_WAIT_L(8); PG8_BAR; PG8_WAIT_L(0); PG8_MMA(0, 0, At, B0); PG8_BAR; PG8_SCHED;
;             PG8_LDB(B1, 0, 1); PG8_STAGE(PG8_SB(0, 0), b2, voffB);
;             PG8_BAR; PG8_WAIT_L(0); PG8_MMA(0, 1, At, B1); PG8_BAR;
;             PG8_LDA(At, 0, 1); PG8_STAGE(PG8_SA(0, 0), a2, voffA);
;             PG8_BAR; PG8_WAIT_L(0); PG8_MMA(1, 0, At, B0); PG8_BAR; PG8_SCHED;
;             PG8_STAGE(PG8_SB(0, 1), b2 + hstepB, voffB);
;             PG8_WAIT_V(6); PG8_BAR; PG8_MMA(1, 1, At, B1); PG8_BAR;
.LBB0_224:
	ds_read_b128 v[146:149], v143
	ds_read_b128 v[150:153], v143 offset:1024
	ds_read_b128 v[154:157], v143 offset:2048
	ds_read_b128 v[158:161], v143 offset:3072
	s_add_i32 m0, s7, 0xc000
	ds_read_b128 v[162:165], v144
	ds_read_b128 v[166:169], v144 offset:1024
	ds_read_b128 v[170:173], v144 offset:2048
	ds_read_b128 v[174:177], v144 offset:3072
	ds_read_b128 v[178:181], v144 offset:4096
	ds_read_b128 v[182:185], v144 offset:5120
	ds_read_b128 v[186:189], v144 offset:6144
	ds_read_b128 v[190:193], v144 offset:7168
	global_load_lds_dwordx4 v132, s[16:17]
	s_add_i32 m0, s7, 0xe000
	s_nop 0
	global_load_lds_dwordx4 v134, s[16:17]
	s_waitcnt lgkmcnt(8)
	s_barrier
	s_waitcnt lgkmcnt(0)
	s_setprio 1
	s_waitcnt lgkmcnt(0)
	v_mfma_f32_16x16x32_bf16 v[124:127], v[162:165], v[146:149], v[124:127]
	v_mfma_f32_16x16x32_bf16 v[108:111], v[162:165], v[154:157], v[108:111]
	v_mfma_f32_16x16x32_bf16 v[120:123], v[170:173], v[146:149], v[120:123]
	v_mfma_f32_16x16x32_bf16 v[104:107], v[170:173], v[154:157], v[104:107]
	v_mfma_f32_16x16x32_bf16 v[116:119], v[178:181], v[146:149], v[116:119]
	v_mfma_f32_16x16x32_bf16 v[100:103], v[178:181], v[154:157], v[100:103]
	v_mfma_f32_16x16x32_bf16 v[112:115], v[186:189], v[146:149], v[112:115]
	v_mfma_f32_16x16x32_bf16 v[92:95], v[186:189], v[154:157], v[92:95]
	v_mfma_f32_16x16x32_bf16 v[124:127], v[166:169], v[150:153], v[124:127]
	v_mfma_f32_16x16x32_bf16 v[108:111], v[166:169], v[158:161], v[108:111]
	v_mfma_f32_16x16x32_bf16 v[120:123], v[174:177], v[150:153], v[120:123]
	v_mfma_f32_16x16x32_bf16 v[104:107], v[174:177], v[158:161], v[104:107]
	v_mfma_f32_16x16x32_bf16 v[116:119], v[182:185], v[150:153], v[116:119]
	v_mfma_f32_16x16x32_bf16 v[100:103], v[182:185], v[158:161], v[100:103]
	v_mfma_f32_16x16x32_bf16 v[112:115], v[190:193], v[150:153], v[112:115]
	v_mfma_f32_16x16x32_bf16 v[92:95], v[190:193], v[158:161], v[92:95]
	s_setprio 0
	s_barrier
	s_add_u32 s18, s16, 0xfff80080
	s_addc_u32 s19, s17, -1
	s_cmp_eq_u32 s41, 28
	s_cselect_b32 s21, s11, s19
	s_cselect_b32 s20, s37, s18
	s_cselect_b32 s19, s9, s40
	s_cselect_b32 s18, s38, s39
	s_add_i32 s42, s34, s25
	s_add_u32 s98, s18, s2
	s_addc_u32 s99, s19, s3
	s_mov_b32 m0, s42
	ds_read_b128 v[196:199], v145
	ds_read_b128 v[202:205], v145 offset:1024
	ds_read_b128 v[206:209], v145 offset:2048
	ds_read_b128 v[210:213], v145 offset:3072
	global_load_lds_dwordx4 v128, s[18:19]
	s_add_i32 m0, s42, 0x2000
	s_nop 0
	global_load_lds_dwordx4 v130, s[18:19]
	s_barrier
	s_waitcnt lgkmcnt(0)
	s_setprio 1
	s_waitcnt lgkmcnt(0)
	v_mfma_f32_16x16x32_bf16 v[80:83], v[162:165], v[196:199], v[80:83]
	v_mfma_f32_16x16x32_bf16 v[48:51], v[162:165], v[206:209], v[48:51]
	v_mfma_f32_16x16x32_bf16 v[68:71], v[170:173], v[196:199], v[68:71]
	v_mfma_f32_16x16x32_bf16 v[40:43], v[170:173], v[206:209], v[40:43]
	v_mfma_f32_16x16x32_bf16 v[60:63], v[178:181], v[196:199], v[60:63]
	v_mfma_f32_16x16x32_bf16 v[36:39], v[178:181], v[206:209], v[36:39]
	v_mfma_f32_16x16x32_bf16 v[52:55], v[186:189], v[196:199], v[52:55]
	v_mfma_f32_16x16x32_bf16 v[28:31], v[186:189], v[206:209], v[28:31]
	v_mfma_f32_16x16x32_bf16 v[80:83], v[166:169], v[202:205], v[80:83]
	v_mfma_f32_16x16x32_bf16 v[48:51], v[166:169], v[210:213], v[48:51]
	v_mfma_f32_16x16x32_bf16 v[68:71], v[174:177], v[202:205], v[68:71]
	v_mfma_f32_16x16x32_bf16 v[40:43], v[174:177], v[210:213], v[40:43]
	v_mfma_f32_16x16x32_bf16 v[60:63], v[182:185], v[202:205], v[60:63]
	v_mfma_f32_16x16x32_bf16 v[36:39], v[182:185], v[210:213], v[36:39]
	v_mfma_f32_16x16x32_bf16 v[52:55], v[190:193], v[202:205], v[52:55]
	v_mfma_f32_16x16x32_bf16 v[28:31], v[190:193], v[210:213], v[28:31]
	s_setprio 0
	s_mov_b32 m0, s7
	s_add_u32 s100, s20, s2
	s_addc_u32 s101, s21, s3
	s_barrier
	ds_read_b128 v[162:165], v144 offset:16384
	ds_read_b128 v[166:169], v144 offset:17408
	ds_read_b128 v[170:173], v144 offset:18432
	ds_read_b128 v[174:177], v144 offset:19456
	ds_read_b128 v[178:181], v144 offset:20480
	ds_read_b128 v[182:185], v144 offset:21504
	ds_read_b128 v[186:189], v144 offset:22528
	ds_read_b128 v[190:193], v144 offset:23552
	global_load_lds_dwordx4 v128, s[20:21]
	s_mov_b32 m0, s26
	s_nop 0
	global_load_lds_dwordx4 v130, s[20:21]
	s_barrier
	s_waitcnt lgkmcnt(0)
	s_setprio 1
	s_waitcnt lgkmcnt(0)
	v_mfma_f32_16x16x32_bf16 v[96:99], v[162:165], v[146:149], v[96:99]
	v_mfma_f32_16x16x32_bf16 v[72:75], v[162:165], v[154:157], v[72:75]
	v_mfma_f32_16x16x32_bf16 v[88:91], v[170:173], v[146:149], v[88:91]
	v_mfma_f32_16x16x32_bf16 v[64:67], v[170:173], v[154:157], v[64:67]
	v_mfma_f32_16x16x32_bf16 v[84:87], v[178:181], v[146:149], v[84:87]
	v_mfma_f32_16x16x32_bf16 v[56:59], v[178:181], v[154:157], v[56:59]
	v_mfma_f32_16x16x32_bf16 v[76:79], v[186:189], v[146:149], v[76:79]
	v_mfma_f32_16x16x32_bf16 v[44:47], v[186:189], v[154:157], v[44:47]
	v_mfma_f32_16x16x32_bf16 v[96:99], v[166:169], v[150:153], v[96:99]
	v_mfma_f32_16x16x32_bf16 v[72:75], v[166:169], v[158:161], v[72:75]
	v_mfma_f32_16x16x32_bf16 v[88:91], v[174:177], v[150:153], v[88:91]
	v_mfma_f32_16x16x32_bf16 v[64:67], v[174:177], v[158:161], v[64:67]
	v_mfma_f32_16x16x32_bf16 v[84:87], v[182:185], v[150:153], v[84:87]
	v_mfma_f32_16x16x32_bf16 v[56:59], v[182:185], v[158:161], v[56:59]
	v_mfma_f32_16x16x32_bf16 v[76:79], v[190:193], v[150:153], v[76:79]
	v_mfma_f32_16x16x32_bf16 v[44:47], v[190:193], v[158:161], v[44:47]
	s_setprio 0
	s_barrier
	s_add_u32 s42, s18, 0x80000
	s_addc_u32 s43, s19, 0
	s_add_i32 s44, s35, s25
	s_mov_b32 m0, s44
	s_nop 0
	global_load_lds_dwordx4 v128, s[42:43]
	s_add_i32 m0, s44, 0x2000
	s_nop 0
	global_load_lds_dwordx4 v130, s[42:43]
	s_waitcnt vmcnt(6)
	s_barrier
; #define PG8_STAGE(bufoff, gbase, voff) do { _Pragma("unroll") for (int _i = 0; _i < 2; ++_i) \
;         __builtin_amdgcn_global_load_lds((const unsigned*)((const char*)(gbase) + (voff)[_i]), (LAS unsigned*)(lds + (bufoff) + ldsw + _i * 8192), 16, 0, 0); } while (0)
; #define PG8_LDA(dst, b, h) do { _Pragma("unroll") for (int m = 0; m < 4; ++m) _Pragma("unroll") for (int k = 0; k < 2; ++k) dst[m][k] = *(const LAS bf16x8*)(lds + PG8_SA(b, h) + aoff + m * 2048 + k * 1024); } while (0)
; #define PG8_LDB(dst, b, h) do { _Pragma("unroll") for (int n = 0; n < 2; ++n) _Pragma("unroll") for (int k = 0; k < 2; ++k) dst[n][k] = *(const LAS bf16x8*)(lds + PG8_SB(b, h) + boff + n * 2048 + k * 1024); } while (0)
; #define PG8_WAIT_V(n) asm volatile("s_waitcnt vmcnt(" #n ")" ::: "memory")
; #define PG8_WAIT_L(n) asm volatile("s_waitcnt lgkmcnt(" #n ")" ::: "memory")
; #define PG8_BAR __builtin_amdgcn_s_barrier()
; #define PG8_SCHED __builtin_amdgcn_sched_barrier(0)
; template <class Epi>
; __device__ __forceinline__ void gemm_phase(LAS unsigned char* lds, const bf16_t* A, int lda, const bf16_t* Bt, int ldb, int M, int N, int K, int asel, const Epi& E, const int fixed_round = -1) {
;     ...
;             PG8_WAIT_V(6); PG8_BAR; PG8_MMA(1, 1, At, B1); PG8_BAR;
;             PG8_LDB(B0, 1, 0); PG8_SCHED; PG8_LDA(At, 1, 0); PG8_STAGE(PG8_SA(0, 1), a2 + hstepA, voffA);
;             PG8_WAIT_L(8); PG8_BAR; PG8_WAIT_L(0); PG8_MMA(0, 0, At, B0); PG8_BAR; PG8_SCHED;
;             PG8_LDB(B1, 1, 1); PG8_STAGE(PG8_SB(1, 0), b3, voffB);
;             PG8_BAR; PG8_WAIT_L(0); PG8_MMA(0, 1, At, B1); PG8_BAR;
;             PG8_LDA(At, 1, 1); PG8_STAGE(PG8_SA(1, 0), a3, voffA);
;             PG8_BAR; PG8_WAIT_L(0); PG8_MMA(1, 0, At, B0); PG8_BAR; PG8_SCHED;
	s_setprio 1
	v_mfma_f32_16x16x32_bf16 v[32:35], v[162:165], v[196:199], v[32:35]
	v_mfma_f32_16x16x32_bf16 v[12:15], v[162:165], v[206:209], v[12:15]
	v_mfma_f32_16x16x32_bf16 v[24:27], v[170:173], v[196:199], v[24:27]
	v_mfma_f32_16x16x32_bf16 v[8:11], v[170:173], v[206:209], v[8:11]
	v_mfma_f32_16x16x32_bf16 v[20:23], v[178:181], v[196:199], v[20:23]
	v_mfma_f32_16x16x32_bf16 v[4:7], v[178:181], v[206:209], v[4:7]
	v_mfma_f32_16x16x32_bf16 v[16:19], v[186:189], v[196:199], v[16:19]
	v_mfma_f32_16x16x32_bf16 v[0:3], v[186:189], v[206:209], v[0:3]
	v_mfma_f32_16x16x32_bf16 v[32:35], v[166:169], v[202:205], v[32:35]
	v_mfma_f32_16x16x32_bf16 v[12:15], v[166:169], v[210:213], v[12:15]
	v_mfma_f32_16x16x32_bf16 v[24:27], v[174:177], v[202:205], v[24:27]
	v_mfma_f32_16x16x32_bf16 v[8:11], v[174:177], v[210:213], v[8:11]
	v_mfma_f32_16x16x32_bf16 v[20:23], v[182:185], v[202:205], v[20:23]
	v_mfma_f32_16x16x32_bf16 v[4:7], v[182:185], v[210:213], v[4:7]
	v_mfma_f32_16x16x32_bf16 v[16:19], v[190:193], v[202:205], v[16:19]
	v_mfma_f32_16x16x32_bf16 v[0:3], v[190:193], v[210:213], v[0:3]
	s_setprio 0
	s_add_i32 s42, 0, 0x18000
	v_add_u32_e32 v158, s42, v140
	s_barrier
	ds_read_b128 v[146:149], v158
	ds_read_b128 v[150:153], v158 offset:1024
	ds_read_b128 v[154:157], v158 offset:2048
	ds_read_b128 v[158:161], v158 offset:3072
	s_add_u32 s20, s20, 0x80000
	s_addc_u32 s21, s21, 0
	s_mov_b32 m0, s27
	ds_read_b128 v[162:165], v144 offset:32768
	ds_read_b128 v[166:169], v144 offset:33792
	ds_read_b128 v[170:173], v144 offset:34816
	ds_read_b128 v[174:177], v144 offset:35840
	ds_read_b128 v[178:181], v144 offset:36864
	ds_read_b128 v[182:185], v144 offset:37888
	ds_read_b128 v[186:189], v144 offset:38912
	ds_read_b128 v[190:193], v144 offset:39936
	global_load_lds_dwordx4 v128, s[20:21]
	s_mov_b32 m0, s28
	s_nop 0
	global_load_lds_dwordx4 v130, s[20:21]
	s_waitcnt lgkmcnt(8)
	s_barrier
	s_waitcnt lgkmcnt(0)
	s_setprio 1
	s_waitcnt lgkmcnt(0)
	v_mfma_f32_16x16x32_bf16 v[124:127], v[162:165], v[146:149], v[124:127]
	v_mfma_f32_16x16x32_bf16 v[108:111], v[162:165], v[154:157], v[108:111]
	v_mfma_f32_16x16x32_bf16 v[120:123], v[170:173], v[146:149], v[120:123]
	v_mfma_f32_16x16x32_bf16 v[104:107], v[170:173], v[154:157], v[104:107]
	v_mfma_f32_16x16x32_bf16 v[116:119], v[178:181], v[146:149], v[116:119]
	v_mfma_f32_16x16x32_bf16 v[100:103], v[178:181], v[154:157], v[100:103]
	v_mfma_f32_16x16x32_bf16 v[112:115], v[186:189], v[146:149], v[112:115]
	v_mfma_f32_16x16x32_bf16 v[92:95], v[186:189], v[154:157], v[92:95]
	v_mfma_f32_16x16x32_bf16 v[124:127], v[166:169], v[150:153], v[124:127]
	v_mfma_f32_16x16x32_bf16 v[108:111], v[166:169], v[158:161], v[108:111]
	v_mfma_f32_16x16x32_bf16 v[120:123], v[174:177], v[150:153], v[120:123]
	v_mfma_f32_16x16x32_bf16 v[104:107], v[174:177], v[158:161], v[104:107]
	v_mfma_f32_16x16x32_bf16 v[116:119], v[182:185], v[150:153], v[116:119]
	v_mfma_f32_16x16x32_bf16 v[100:103], v[182:185], v[158:161], v[100:103]
	v_mfma_f32_16x16x32_bf16 v[112:115], v[190:193], v[150:153], v[112:115]
	v_mfma_f32_16x16x32_bf16 v[92:95], v[190:193], v[158:161], v[92:95]
	s_setprio 0
	s_barrier
	s_add_i32 s20, 0, 0x1c000
	s_add_i32 s21, s42, s25
	v_add_u32_e32 v195, s20, v140
	s_mov_b32 m0, s21
	ds_read_b128 v[196:199], v195
	ds_read_b128 v[202:205], v195 offset:1024
	ds_read_b128 v[206:209], v195 offset:2048
	ds_read_b128 v[210:213], v195 offset:3072
	global_load_lds_dwordx4 v128, s[98:99]
	s_add_i32 m0, s21, 0x2000
	s_nop 0
	global_load_lds_dwordx4 v130, s[98:99]
	s_barrier
	s_waitcnt lgkmcnt(0)
	s_setprio 1
	s_waitcnt lgkmcnt(0)
	v_mfma_f32_16x16x32_bf16 v[80:83], v[162:165], v[196:199], v[80:83]
	v_mfma_f32_16x16x32_bf16 v[48:51], v[162:165], v[206:209], v[48:51]
	v_mfma_f32_16x16x32_bf16 v[68:71], v[170:173], v[196:199], v[68:71]
	v_mfma_f32_16x16x32_bf16 v[40:43], v[170:173], v[206:209], v[40:43]
	v_mfma_f32_16x16x32_bf16 v[60:63], v[178:181], v[196:199], v[60:63]
	v_mfma_f32_16x16x32_bf16 v[36:39], v[178:181], v[206:209], v[36:39]
	v_mfma_f32_16x16x32_bf16 v[52:55], v[186:189], v[196:199], v[52:55]
	v_mfma_f32_16x16x32_bf16 v[28:31], v[186:189], v[206:209], v[28:31]
	v_mfma_f32_16x16x32_bf16 v[80:83], v[166:169], v[202:205], v[80:83]
	v_mfma_f32_16x16x32_bf16 v[48:51], v[166:169], v[210:213], v[48:51]
	v_mfma_f32_16x16x32_bf16 v[68:71], v[174:177], v[202:205], v[68:71]
	v_mfma_f32_16x16x32_bf16 v[40:43], v[174:177], v[210:213], v[40:43]
	v_mfma_f32_16x16x32_bf16 v[60:63], v[182:185], v[202:205], v[60:63]
	v_mfma_f32_16x16x32_bf16 v[36:39], v[182:185], v[210:213], v[36:39]
	v_mfma_f32_16x16x32_bf16 v[52:55], v[190:193], v[202:205], v[52:55]
	v_mfma_f32_16x16x32_bf16 v[28:31], v[190:193], v[210:213], v[28:31]
	s_setprio 0
	s_mov_b32 m0, s30
	s_barrier
	ds_read_b128 v[162:165], v144 offset:49152
	ds_read_b128 v[166:169], v144 offset:50176
	ds_read_b128 v[170:173], v144 offset:51200
	ds_read_b128 v[174:177], v144 offset:52224
	ds_read_b128 v[178:181], v144 offset:53248
	ds_read_b128 v[182:185], v144 offset:54272
	ds_read_b128 v[186:189], v144 offset:55296
	ds_read_b128 v[190:193], v144 offset:56320
	global_load_lds_dwordx4 v128, s[100:101]
	s_mov_b32 m0, s31
	s_nop 0
	global_load_lds_dwordx4 v130, s[100:101]
	s_barrier
; #define PG8_STAGE(bufoff, gbase, voff) do { _Pragma("unroll") for (int _i = 0; _i < 2; ++_i) \
;         __builtin_amdgcn_global_load_lds((const unsigned*)((const char*)(gbase) + (voff)[_i]), (LAS unsigned*)(lds + (bufoff) + ldsw + _i * 8192), 16, 0, 0); } while (0)
; #define PG8_WAIT_V(n) asm volatile("s_waitcnt vmcnt(" #n ")" ::: "memory")
; #define PG8_WAIT_L(n) asm volatile("s_waitcnt lgkmcnt(" #n ")" ::: "memory")
; #define PG8_BAR __builtin_amdgcn_s_barrier()
; #define PG8_SCHED __builtin_amdgcn_sched_barrier(0)
; template <class Epi>
; __device__ __forceinline__ void gemm_phase(LAS unsigned char* lds, const bf16_t* A, int lda, const bf16_t* Bt, int ldb, int M, int N, int K, int asel, const Epi& E, const int fixed_round = -1) {
;     ...
;             PG8_BAR; PG8_WAIT_L(0); PG8_MMA(1, 0, At, B0); PG8_BAR; PG8_SCHED;
;             PG8_STAGE(PG8_SB(1, 1), b3 + hstepB, voffB);
;             PG8_WAIT_V(6); PG8_BAR; PG8_MMA(1, 1, At, B1); PG8_BAR;
	s_waitcnt lgkmcnt(0)
	s_setprio 1
	s_waitcnt lgkmcnt(0)
	v_mfma_f32_16x16x32_bf16 v[96:99], v[162:165], v[146:149], v[96:99]
	v_mfma_f32_16x16x32_bf16 v[72:75], v[162:165], v[154:157], v[72:75]
	v_mfma_f32_16x16x32_bf16 v[88:91], v[170:173], v[146:149], v[88:91]
	v_mfma_f32_16x16x32_bf16 v[64:67], v[170:173], v[154:157], v[64:67]
	v_mfma_f32_16x16x32_bf16 v[84:87], v[178:181], v[146:149], v[84:87]
	v_mfma_f32_16x16x32_bf16 v[56:59], v[178:181], v[154:157], v[56:59]
	v_mfma_f32_16x16x32_bf16 v[76:79], v[186:189], v[146:149], v[76:79]
	v_mfma_f32_16x16x32_bf16 v[44:47], v[186:189], v[154:157], v[44:47]
	v_mfma_f32_16x16x32_bf16 v[96:99], v[166:169], v[150:153], v[96:99]
	v_mfma_f32_16x16x32_bf16 v[72:75], v[166:169], v[158:161], v[72:75]
	v_mfma_f32_16x16x32_bf16 v[88:91], v[174:177], v[150:153], v[88:91]
	v_mfma_f32_16x16x32_bf16 v[64:67], v[174:177], v[158:161], v[64:67]
	v_mfma_f32_16x16x32_bf16 v[84:87], v[182:185], v[150:153], v[84:87]
	v_mfma_f32_16x16x32_bf16 v[56:59], v[182:185], v[158:161], v[56:59]
	v_mfma_f32_16x16x32_bf16 v[76:79], v[190:193], v[150:153], v[76:79]
	v_mfma_f32_16x16x32_bf16 v[44:47], v[190:193], v[158:161], v[44:47]
	s_setprio 0
	s_barrier
	s_add_u32 s18, s18, 0x80080
	s_addc_u32 s19, s19, 0
	s_add_i32 s20, s20, s25
	s_mov_b32 m0, s20
	s_nop 0
	global_load_lds_dwordx4 v128, s[18:19]
	s_add_i32 m0, s20, 0x2000
	s_nop 0
	global_load_lds_dwordx4 v130, s[18:19]
	s_waitcnt vmcnt(6)
	s_barrier
	s_setprio 1
	v_mfma_f32_16x16x32_bf16 v[32:35], v[162:165], v[196:199], v[32:35]
	v_mfma_f32_16x16x32_bf16 v[12:15], v[162:165], v[206:209], v[12:15]
	v_mfma_f32_16x16x32_bf16 v[24:27], v[170:173], v[196:199], v[24:27]
	v_mfma_f32_16x16x32_bf16 v[8:11], v[170:173], v[206:209], v[8:11]
	v_mfma_f32_16x16x32_bf16 v[20:23], v[178:181], v[196:199], v[20:23]
	v_mfma_f32_16x16x32_bf16 v[4:7], v[178:181], v[206:209], v[4:7]
	v_mfma_f32_16x16x32_bf16 v[16:19], v[186:189], v[196:199], v[16:19]
	v_mfma_f32_16x16x32_bf16 v[0:3], v[186:189], v[206:209], v[0:3]
	v_mfma_f32_16x16x32_bf16 v[32:35], v[166:169], v[202:205], v[32:35]
	v_mfma_f32_16x16x32_bf16 v[12:15], v[166:169], v[210:213], v[12:15]
	v_mfma_f32_16x16x32_bf16 v[24:27], v[174:177], v[202:205], v[24:27]
	v_mfma_f32_16x16x32_bf16 v[8:11], v[174:177], v[210:213], v[8:11]
	v_mfma_f32_16x16x32_bf16 v[20:23], v[182:185], v[202:205], v[20:23]
	v_mfma_f32_16x16x32_bf16 v[4:7], v[182:185], v[210:213], v[4:7]
	v_mfma_f32_16x16x32_bf16 v[16:19], v[190:193], v[202:205], v[16:19]
	v_mfma_f32_16x16x32_bf16 v[0:3], v[190:193], v[210:213], v[0:3]
	s_setprio 0
	s_add_i32 s41, s41, 2
	s_add_u32 s16, s16, 0x100
	s_addc_u32 s17, s17, 0
	s_add_u32 s39, s39, 0x100
	s_addc_u32 s40, s40, 0
	s_cmp_gt_u32 s41, 29
	s_cbranch_scc0 .Lrot_2
	s_barrier
; __device__ __forceinline__ unsigned cvt_pk_bf16(float lo, float hi) { const bf16x2_t r = __builtin_convertvector((f32x2){lo, hi}, bf16x2_t); return __builtin_bit_cast(unsigned, r); }
; #define PG8_WAIT_V(n) asm volatile("s_waitcnt vmcnt(" #n ")" ::: "memory")
; #define PG8_BAR __builtin_amdgcn_s_barrier()
; template <class Epi>
; __device__ __forceinline__ void gemm_phase(LAS unsigned char* lds, const bf16_t* A, int lda, const bf16_t* Bt, int ldb, int M, int N, int K, int asel, const Epi& E, const int fixed_round = -1) {
;     ...
;         if (!has_next) break;
; #pragma unroll
;         for (int a = 0; a < 2; ++a)
; #pragma unroll
;             for (int b = 0; b < 2; ++b)
; #pragma unroll
;                 for (int m = 0; m < 4; ++m)
; #pragma unroll
;                     for (int n = 0; n < 2; ++n) acc[a][b][m][n] = (f32x4){0.f, 0.f, 0.f, 0.f};
;         cur = nxt; cA = nA; cB = nB; ++ui;
;     }
;     PG8_WAIT_V(0);
;     if (wr == 0) PG8_BAR;
;     __device__ __forceinline__ void operator()(const AccT& acc, const Unit& u, int wr, int wc, int fr, int fq) const {
;         const int bb = u.pm >> 4, s0 = (u.pm & 15) * BM + wr * 64 + 4 * fq, feat0 = u.pn * BM + wc * 32 + fr;
; #pragma unroll
;         for (int bj = 0; bj < 2; ++bj)
; #pragma unroll
;             for (int n = 0; n < 2; ++n) { bf16_t* fp = VT + ((size_t)bb * 2048 + feat0 + bj * HALF + n * 16) * SEQ + s0;
; #pragma unroll
;                 for (int ai = 0; ai < 2; ++ai)
; #pragma unroll
;                     for (int m = 0; m < 4; ++m) { const f32x4 v = acc[ai][bj][m][n]; u32x2 w; w.x = cvt_pk_bf16(v[0], v[1]); w.y = cvt_pk_bf16(v[2], v[3]);
;                         *(u32x2*)(fp + ai * HALF + m * 16) = w; } }
;     }
	s_ashr_i32 s16, s6, 4
	v_lshl_or_b32 v148, s36, 8, v142
	s_lshl_b32 s6, s6, 8
	s_ashr_i32 s17, s16, 31
	v_ashrrev_i32_e32 v149, 31, v148
	s_and_b32 s6, s6, 0xf00
	s_lshl_b64 s[16:17], s[16:17], 24
	v_lshlrev_b64 v[148:149], 13, v[148:149]
	v_add_u32_e32 v146, s6, v141
	v_lshl_add_u64 v[148:149], v[148:149], 0, s[16:17]
	v_readlane_b32 s16, v254, 47
	v_ashrrev_i32_e32 v147, 31, v146
	v_readlane_b32 s17, v254, 48
	v_lshlrev_b64 v[146:147], 1, v[146:147]
	v_cvt_pk_bf16_f32 v76, v76, v77
	v_lshl_add_u64 v[150:151], s[16:17], 0, v[148:149]
	v_lshl_add_u64 v[150:151], v[150:151], 0, v[146:147]
	v_cvt_pk_bf16_f32 v77, v78, v79
	global_store_dwordx2 v[150:151], v[76:77], off offset:352
	v_or_b32_e32 v76, 0x20000, v148
	v_mov_b32_e32 v77, v149
	v_lshl_add_u64 v[76:77], s[16:17], 0, v[76:77]
	v_cvt_pk_bf16_f32 v124, v124, v125
	v_cvt_pk_bf16_f32 v125, v126, v127
	v_cvt_pk_bf16_f32 v120, v120, v121
	v_cvt_pk_bf16_f32 v121, v122, v123
	v_cvt_pk_bf16_f32 v116, v116, v117
	v_cvt_pk_bf16_f32 v117, v118, v119
	v_cvt_pk_bf16_f32 v112, v112, v113
	v_cvt_pk_bf16_f32 v113, v114, v115
	v_cvt_pk_bf16_f32 v96, v96, v97
	v_cvt_pk_bf16_f32 v97, v98, v99
	v_cvt_pk_bf16_f32 v88, v88, v89
	v_cvt_pk_bf16_f32 v89, v90, v91
	v_cvt_pk_bf16_f32 v84, v84, v85
	v_cvt_pk_bf16_f32 v85, v86, v87
	v_lshl_add_u64 v[76:77], v[76:77], 0, v[146:147]
	v_cvt_pk_bf16_f32 v78, v108, v109
	v_cvt_pk_bf16_f32 v79, v110, v111
	v_cvt_pk_bf16_f32 v44, v44, v45
	v_cvt_pk_bf16_f32 v45, v46, v47
	global_store_dwordx2 v[150:151], v[124:125], off
	global_store_dwordx2 v[150:151], v[120:121], off offset:32
	global_store_dwordx2 v[150:151], v[116:117], off offset:64
	global_store_dwordx2 v[150:151], v[112:113], off offset:96
	global_store_dwordx2 v[150:151], v[96:97], off offset:256
	global_store_dwordx2 v[150:151], v[88:89], off offset:288
	global_store_dwordx2 v[150:151], v[84:85], off offset:320
	global_store_dwordx2 v[76:77], v[78:79], off
	v_cvt_pk_bf16_f32 v78, v104, v105
	v_cvt_pk_bf16_f32 v79, v106, v107
	global_store_dwordx2 v[76:77], v[44:45], off offset:352
	v_or_b32_e32 v44, 0x100000, v148
	v_mov_b32_e32 v45, v149
	global_store_dwordx2 v[76:77], v[78:79], off offset:32
	v_cvt_pk_bf16_f32 v78, v100, v101
	v_cvt_pk_bf16_f32 v79, v102, v103
	v_lshl_add_u64 v[44:45], s[16:17], 0, v[44:45]
	global_store_dwordx2 v[76:77], v[78:79], off offset:64
	v_cvt_pk_bf16_f32 v78, v92, v93
	v_cvt_pk_bf16_f32 v79, v94, v95
	v_cvt_pk_bf16_f32 v72, v72, v73
	v_cvt_pk_bf16_f32 v73, v74, v75
	v_cvt_pk_bf16_f32 v64, v64, v65
	v_cvt_pk_bf16_f32 v65, v66, v67
	v_cvt_pk_bf16_f32 v56, v56, v57
	v_cvt_pk_bf16_f32 v57, v58, v59
	v_lshl_add_u64 v[44:45], v[44:45], 0, v[146:147]
	v_cvt_pk_bf16_f32 v46, v80, v81
	v_cvt_pk_bf16_f32 v47, v82, v83
	global_store_dwordx2 v[76:77], v[78:79], off offset:96
	global_store_dwordx2 v[76:77], v[72:73], off offset:256
	global_store_dwordx2 v[76:77], v[64:65], off offset:288
	global_store_dwordx2 v[76:77], v[56:57], off offset:320
	global_store_dwordx2 v[44:45], v[46:47], off
	v_cvt_pk_bf16_f32 v46, v68, v69
	v_cvt_pk_bf16_f32 v47, v70, v71
	v_cvt_pk_bf16_f32 v16, v16, v17
	v_cvt_pk_bf16_f32 v17, v18, v19
	v_or_b32_e32 v148, 0x120000, v148
	global_store_dwordx2 v[44:45], v[46:47], off offset:32
	v_cvt_pk_bf16_f32 v46, v60, v61
	v_cvt_pk_bf16_f32 v47, v62, v63
	global_store_dwordx2 v[44:45], v[16:17], off offset:352
	v_lshl_add_u64 v[16:17], s[16:17], 0, v[148:149]
	global_store_dwordx2 v[44:45], v[46:47], off offset:64
	v_cvt_pk_bf16_f32 v46, v52, v53
	v_cvt_pk_bf16_f32 v47, v54, v55
	v_cvt_pk_bf16_f32 v32, v32, v33
	v_cvt_pk_bf16_f32 v33, v34, v35
	v_cvt_pk_bf16_f32 v24, v24, v25
	v_cvt_pk_bf16_f32 v25, v26, v27
	v_cvt_pk_bf16_f32 v20, v20, v21
	v_cvt_pk_bf16_f32 v21, v22, v23
	v_lshl_add_u64 v[16:17], v[16:17], 0, v[146:147]
	v_cvt_pk_bf16_f32 v18, v48, v49
	v_cvt_pk_bf16_f32 v19, v50, v51
	global_store_dwordx2 v[44:45], v[46:47], off offset:96
	global_store_dwordx2 v[44:45], v[32:33], off offset:256
	global_store_dwordx2 v[44:45], v[24:25], off offset:288
	global_store_dwordx2 v[44:45], v[20:21], off offset:320
	global_store_dwordx2 v[16:17], v[18:19], off
	v_cvt_pk_bf16_f32 v18, v40, v41
	v_cvt_pk_bf16_f32 v19, v42, v43
	global_store_dwordx2 v[16:17], v[18:19], off offset:32
	v_cvt_pk_bf16_f32 v18, v36, v37
	v_cvt_pk_bf16_f32 v19, v38, v39
	global_store_dwordx2 v[16:17], v[18:19], off offset:64
	v_cvt_pk_bf16_f32 v18, v28, v29
	v_cvt_pk_bf16_f32 v19, v30, v31
	v_cvt_pk_bf16_f32 v12, v12, v13
	v_cvt_pk_bf16_f32 v13, v14, v15
	v_cvt_pk_bf16_f32 v8, v8, v9
	v_cvt_pk_bf16_f32 v9, v10, v11
	v_cvt_pk_bf16_f32 v4, v4, v5
	v_cvt_pk_bf16_f32 v5, v6, v7
	v_cvt_pk_bf16_f32 v0, v0, v1
	v_cvt_pk_bf16_f32 v1, v2, v3
	s_and_b64 vcc, exec, s[4:5]
	s_mov_b32 s36, s8
	s_mov_b32 s6, s10
	s_mov_b64 s[18:19], s[14:15]
	s_mov_b64 s[16:17], s[12:13]
	global_store_dwordx2 v[16:17], v[18:19], off offset:96
	global_store_dwordx2 v[16:17], v[12:13], off offset:256
	global_store_dwordx2 v[16:17], v[8:9], off offset:288
	global_store_dwordx2 v[16:17], v[4:5], off offset:320
	global_store_dwordx2 v[16:17], v[0:1], off offset:352
	s_cbranch_vccz .LBB0_217
	s_waitcnt vmcnt(0)
	s_cmpk_gt_u32 s22, 0xff
	s_cbranch_scc1 .LBB0_228
	s_barrier

; #define PG8_STAGE(bufoff, gbase, voff) do { _Pragma("unroll") for (int _i = 0; _i < 2; ++_i) \
;         __builtin_amdgcn_global_load_lds((const unsigned*)((const char*)(gbase) + (voff)[_i]), (LAS unsigned*)(lds + (bufoff) + ldsw + _i * 8192), 16, 0, 0); } while (0)
; #define PG8_LDA(dst, b, h) do { _Pragma("unroll") for (int m = 0; m < 4; ++m) _Pragma("unroll") for (int k = 0; k < 2; ++k) dst[m][k] = *(const LAS bf16x8*)(lds + PG8_SA(b, h) + aoff + m * 2048 + k * 1024); } while (0)
; #define PG8_LDB(dst, b, h) do { _Pragma("unroll") for (int n = 0; n < 2; ++n) _Pragma("unroll") for (int k = 0; k < 2; ++k) dst[n][k] = *(const LAS bf16x8*)(lds + PG8_SB(b, h) + boff + n * 2048 + k * 1024); } while (0)
; #define PG8_WAIT_V(n) asm volatile("s_waitcnt vmcnt(" #n ")" ::: "memory")
; #define PG8_WAIT_L(n) asm volatile("s_waitcnt lgkmcnt(" #n ")" ::: "memory")
; #define PG8_BAR __builtin_amdgcn_s_barrier()
; #define PG8_SCHED __builtin_amdgcn_sched_barrier(0)
; template <class Epi>
; __device__ __forceinline__ void gemm_phase(LAS unsigned char* lds, const bf16_t* A, int lda, const bf16_t* Bt, int ldb, int M, int N, int K, int asel, const Epi& E, const int fixed_round = -1) {
;     ...
;         for (int t = 0; t < nt; t += 2) {
;             const bool last = (t == nt - 2);
;             const char* a1 = cA + (size_t)(t + 1) * kstep;
;             const char* a2 = last ? nA : cA + (size_t)(t + 2) * kstep; const char* b2 = last ? nB : cB + (size_t)(t + 2) * kstep;
;             const char* a3 = a2 + kstep; const char* b3 = b2 + kstep;
;             PG8_LDB(B0, 0, 0); PG8_SCHED; PG8_LDA(At, 0, 0); PG8_STAGE(PG8_SA(1, 1), a1 + hstepA, voffA);
;             PG8_WAIT_L(8); PG8_BAR; PG8_WAIT_L(0); PG8_MMA(0, 0, At, B0); PG8_BAR; PG8_SCHED;
;             PG8_LDB(B1, 0, 1); PG8_STAGE(PG8_SB(0, 0), b2, voffB);
;             PG8_BAR; PG8_WAIT_L(0); PG8_MMA(0, 1, At, B1); PG8_BAR;
;             PG8_LDA(At, 0, 1); PG8_STAGE(PG8_SA(0, 0), a2, voffA);
;             PG8_BAR; PG8_WAIT_L(0); PG8_MMA(1, 0, At, B0); PG8_BAR; PG8_SCHED;
;             PG8_STAGE(PG8_SB(0, 1), b2 + hstepB, voffB);
;             PG8_WAIT_V(6); PG8_BAR; PG8_MMA(1, 1, At, B1); PG8_BAR;
.LBB0_245:
	ds_read_b128 v[148:151], v161
	ds_read_b128 v[152:155], v161 offset:1024
	ds_read_b128 v[156:159], v161 offset:2048
	ds_read_b128 v[166:169], v161 offset:3072
	s_add_i32 m0, s37, 0xc000
	ds_read_b128 v[170:173], v162
	ds_read_b128 v[174:177], v162 offset:1024
	ds_read_b128 v[178:181], v162 offset:2048
	ds_read_b128 v[182:185], v162 offset:3072
	ds_read_b128 v[186:189], v162 offset:4096
	ds_read_b128 v[190:193], v162 offset:5120
	ds_read_b128 v[196:199], v162 offset:6144
	ds_read_b128 v[202:205], v162 offset:7168
	global_load_lds_dwordx4 v140, s[26:27]
	s_add_i32 m0, s37, 0xe000
	s_nop 0
	global_load_lds_dwordx4 v142, s[26:27]
	s_waitcnt lgkmcnt(8)
	s_barrier
	s_waitcnt lgkmcnt(0)
	s_setprio 1
	s_waitcnt lgkmcnt(0)
	v_mfma_f32_16x16x32_bf16 v[124:127], v[148:151], v[170:173], v[124:127]
	v_mfma_f32_16x16x32_bf16 v[120:123], v[156:159], v[170:173], v[120:123]
	v_mfma_f32_16x16x32_bf16 v[112:115], v[148:151], v[178:181], v[112:115]
	v_mfma_f32_16x16x32_bf16 v[108:111], v[156:159], v[178:181], v[108:111]
	v_mfma_f32_16x16x32_bf16 v[100:103], v[148:151], v[186:189], v[100:103]
	v_mfma_f32_16x16x32_bf16 v[92:95], v[156:159], v[186:189], v[92:95]
	v_mfma_f32_16x16x32_bf16 v[84:87], v[148:151], v[196:199], v[84:87]
	v_mfma_f32_16x16x32_bf16 v[76:79], v[156:159], v[196:199], v[76:79]
	v_mfma_f32_16x16x32_bf16 v[124:127], v[152:155], v[174:177], v[124:127]
	v_mfma_f32_16x16x32_bf16 v[120:123], v[166:169], v[174:177], v[120:123]
	v_mfma_f32_16x16x32_bf16 v[112:115], v[152:155], v[182:185], v[112:115]
	v_mfma_f32_16x16x32_bf16 v[108:111], v[166:169], v[182:185], v[108:111]
	v_mfma_f32_16x16x32_bf16 v[100:103], v[152:155], v[190:193], v[100:103]
	v_mfma_f32_16x16x32_bf16 v[92:95], v[166:169], v[190:193], v[92:95]
	v_mfma_f32_16x16x32_bf16 v[84:87], v[152:155], v[202:205], v[84:87]
	v_mfma_f32_16x16x32_bf16 v[76:79], v[166:169], v[202:205], v[76:79]
	s_setprio 0
	s_barrier
	s_add_u32 s28, s26, 0xfff80080
	s_addc_u32 s29, s27, -1
	s_cmp_eq_u32 s57, 28
	s_cselect_b32 s31, s2, s29
	s_cselect_b32 s30, s19, s28
	s_cselect_b32 s29, s17, s56
	s_cselect_b32 s28, s54, s55
	s_add_i32 s58, s44, s36
	s_add_u32 s98, s28, s4
	s_addc_u32 s99, s29, s5
	s_mov_b32 m0, s58
	ds_read_b128 v[206:209], v163
	ds_read_b128 v[210:213], v163 offset:1024
	ds_read_b128 v[214:217], v163 offset:2048
	ds_read_b128 v[218:221], v163 offset:3072
	global_load_lds_dwordx4 v130, s[28:29]
	s_add_i32 m0, s58, 0x2000
	s_nop 0
	global_load_lds_dwordx4 v134, s[28:29]
	s_barrier
	s_waitcnt lgkmcnt(0)
	s_setprio 1
	s_waitcnt lgkmcnt(0)
	v_mfma_f32_16x16x32_bf16 v[116:119], v[206:209], v[170:173], v[116:119]
	v_mfma_f32_16x16x32_bf16 v[104:107], v[214:217], v[170:173], v[104:107]
	v_mfma_f32_16x16x32_bf16 v[96:99], v[206:209], v[178:181], v[96:99]
	v_mfma_f32_16x16x32_bf16 v[88:91], v[214:217], v[178:181], v[88:91]
	v_mfma_f32_16x16x32_bf16 v[80:83], v[206:209], v[186:189], v[80:83]
	v_mfma_f32_16x16x32_bf16 v[72:75], v[214:217], v[186:189], v[72:75]
	v_mfma_f32_16x16x32_bf16 v[68:71], v[206:209], v[196:199], v[68:71]
	v_mfma_f32_16x16x32_bf16 v[64:67], v[214:217], v[196:199], v[64:67]
	v_mfma_f32_16x16x32_bf16 v[116:119], v[210:213], v[174:177], v[116:119]
	v_mfma_f32_16x16x32_bf16 v[104:107], v[218:221], v[174:177], v[104:107]
	v_mfma_f32_16x16x32_bf16 v[96:99], v[210:213], v[182:185], v[96:99]
	v_mfma_f32_16x16x32_bf16 v[88:91], v[218:221], v[182:185], v[88:91]
	v_mfma_f32_16x16x32_bf16 v[80:83], v[210:213], v[190:193], v[80:83]
	v_mfma_f32_16x16x32_bf16 v[72:75], v[218:221], v[190:193], v[72:75]
	v_mfma_f32_16x16x32_bf16 v[68:71], v[210:213], v[202:205], v[68:71]
	v_mfma_f32_16x16x32_bf16 v[64:67], v[218:221], v[202:205], v[64:67]
	s_setprio 0
	s_mov_b32 m0, s37
	s_add_u32 s100, s30, s4
	s_addc_u32 s101, s31, s5
	s_barrier
	ds_read_b128 v[170:173], v162 offset:16384
	ds_read_b128 v[174:177], v162 offset:17408
	ds_read_b128 v[178:181], v162 offset:18432
	ds_read_b128 v[182:185], v162 offset:19456
	ds_read_b128 v[186:189], v162 offset:20480
	ds_read_b128 v[190:193], v162 offset:21504
	ds_read_b128 v[196:199], v162 offset:22528
	ds_read_b128 v[202:205], v162 offset:23552
	global_load_lds_dwordx4 v128, s[30:31]
	s_mov_b32 m0, s38
	s_nop 0
	global_load_lds_dwordx4 v132, s[30:31]
	s_barrier
	s_waitcnt lgkmcnt(0)
	s_setprio 1
	s_waitcnt lgkmcnt(0)
	v_mfma_f32_16x16x32_bf16 v[60:63], v[148:151], v[170:173], v[60:63]
	v_mfma_f32_16x16x32_bf16 v[56:59], v[156:159], v[170:173], v[56:59]
	v_mfma_f32_16x16x32_bf16 v[52:55], v[148:151], v[178:181], v[52:55]
	v_mfma_f32_16x16x32_bf16 v[44:47], v[156:159], v[178:181], v[44:47]
	v_mfma_f32_16x16x32_bf16 v[36:39], v[148:151], v[186:189], v[36:39]
	v_mfma_f32_16x16x32_bf16 v[28:31], v[156:159], v[186:189], v[28:31]
	v_mfma_f32_16x16x32_bf16 v[20:23], v[148:151], v[196:199], v[20:23]
	v_mfma_f32_16x16x32_bf16 v[12:15], v[156:159], v[196:199], v[12:15]
	v_mfma_f32_16x16x32_bf16 v[60:63], v[152:155], v[174:177], v[60:63]
	v_mfma_f32_16x16x32_bf16 v[56:59], v[166:169], v[174:177], v[56:59]
	v_mfma_f32_16x16x32_bf16 v[52:55], v[152:155], v[182:185], v[52:55]
	v_mfma_f32_16x16x32_bf16 v[44:47], v[166:169], v[182:185], v[44:47]
	v_mfma_f32_16x16x32_bf16 v[36:39], v[152:155], v[190:193], v[36:39]
	v_mfma_f32_16x16x32_bf16 v[28:31], v[166:169], v[190:193], v[28:31]
	v_mfma_f32_16x16x32_bf16 v[20:23], v[152:155], v[202:205], v[20:23]
	v_mfma_f32_16x16x32_bf16 v[12:15], v[166:169], v[202:205], v[12:15]
	s_setprio 0
	s_barrier
	s_add_u32 s58, s28, 0x80000
	s_addc_u32 s59, s29, 0
	s_add_i32 s60, s45, s36
	s_mov_b32 m0, s60
	s_nop 0
	global_load_lds_dwordx4 v130, s[58:59]
	s_add_i32 m0, s60, 0x2000
	s_nop 0
	global_load_lds_dwordx4 v134, s[58:59]
	s_waitcnt vmcnt(6)
	s_barrier
; #define PG8_STAGE(bufoff, gbase, voff) do { _Pragma("unroll") for (int _i = 0; _i < 2; ++_i) \
;         __builtin_amdgcn_global_load_lds((const unsigned*)((const char*)(gbase) + (voff)[_i]), (LAS unsigned*)(lds + (bufoff) + ldsw + _i * 8192), 16, 0, 0); } while (0)
; #define PG8_LDA(dst, b, h) do { _Pragma("unroll") for (int m = 0; m < 4; ++m) _Pragma("unroll") for (int k = 0; k < 2; ++k) dst[m][k] = *(const LAS bf16x8*)(lds + PG8_SA(b, h) + aoff + m * 2048 + k * 1024); } while (0)
; #define PG8_LDB(dst, b, h) do { _Pragma("unroll") for (int n = 0; n < 2; ++n) _Pragma("unroll") for (int k = 0; k < 2; ++k) dst[n][k] = *(const LAS bf16x8*)(lds + PG8_SB(b, h) + boff + n * 2048 + k * 1024); } while (0)
; #define PG8_WAIT_V(n) asm volatile("s_waitcnt vmcnt(" #n ")" ::: "memory")
; #define PG8_WAIT_L(n) asm volatile("s_waitcnt lgkmcnt(" #n ")" ::: "memory")
; #define PG8_BAR __builtin_amdgcn_s_barrier()
; #define PG8_SCHED __builtin_amdgcn_sched_barrier(0)
; template <class Epi>
; __device__ __forceinline__ void gemm_phase(LAS unsigned char* lds, const bf16_t* A, int lda, const bf16_t* Bt, int ldb, int M, int N, int K, int asel, const Epi& E, const int fixed_round = -1) {
;     ...
;             PG8_WAIT_V(6); PG8_BAR; PG8_MMA(1, 1, At, B1); PG8_BAR;
;             PG8_LDB(B0, 1, 0); PG8_SCHED; PG8_LDA(At, 1, 0); PG8_STAGE(PG8_SA(0, 1), a2 + hstepA, voffA);
;             PG8_WAIT_L(8); PG8_BAR; PG8_WAIT_L(0); PG8_MMA(0, 0, At, B0); PG8_BAR; PG8_SCHED;
;             PG8_LDB(B1, 1, 1); PG8_STAGE(PG8_SB(1, 0), b3, voffB);
;             PG8_BAR; PG8_WAIT_L(0); PG8_MMA(0, 1, At, B1); PG8_BAR;
;             PG8_LDA(At, 1, 1); PG8_STAGE(PG8_SA(1, 0), a3, voffA);
;             PG8_BAR; PG8_WAIT_L(0); PG8_MMA(1, 0, At, B0); PG8_BAR; PG8_SCHED;
	s_setprio 1
	v_mfma_f32_16x16x32_bf16 v[48:51], v[206:209], v[170:173], v[48:51]
	v_mfma_f32_16x16x32_bf16 v[40:43], v[214:217], v[170:173], v[40:43]
	v_mfma_f32_16x16x32_bf16 v[32:35], v[206:209], v[178:181], v[32:35]
	v_mfma_f32_16x16x32_bf16 v[24:27], v[214:217], v[178:181], v[24:27]
	v_mfma_f32_16x16x32_bf16 v[16:19], v[206:209], v[186:189], v[16:19]
	v_mfma_f32_16x16x32_bf16 v[8:11], v[214:217], v[186:189], v[8:11]
	v_mfma_f32_16x16x32_bf16 v[4:7], v[206:209], v[196:199], v[4:7]
	v_mfma_f32_16x16x32_bf16 v[0:3], v[214:217], v[196:199], v[0:3]
	v_mfma_f32_16x16x32_bf16 v[48:51], v[210:213], v[174:177], v[48:51]
	v_mfma_f32_16x16x32_bf16 v[40:43], v[218:221], v[174:177], v[40:43]
	v_mfma_f32_16x16x32_bf16 v[32:35], v[210:213], v[182:185], v[32:35]
	v_mfma_f32_16x16x32_bf16 v[24:27], v[218:221], v[182:185], v[24:27]
	v_mfma_f32_16x16x32_bf16 v[16:19], v[210:213], v[190:193], v[16:19]
	v_mfma_f32_16x16x32_bf16 v[8:11], v[218:221], v[190:193], v[8:11]
	v_mfma_f32_16x16x32_bf16 v[4:7], v[210:213], v[202:205], v[4:7]
	v_mfma_f32_16x16x32_bf16 v[0:3], v[218:221], v[202:205], v[0:3]
	s_setprio 0
	s_add_i32 s58, 0, 0x18000
	v_add_u32_e32 v136, s58, v160
	s_barrier
	ds_read_b128 v[148:151], v136
	ds_read_b128 v[152:155], v136 offset:1024
	ds_read_b128 v[156:159], v136 offset:2048
	ds_read_b128 v[166:169], v136 offset:3072
	s_add_u32 s30, s30, 0x80000
	s_addc_u32 s31, s31, 0
	s_mov_b32 m0, s39
	ds_read_b128 v[170:173], v162 offset:32768
	ds_read_b128 v[174:177], v162 offset:33792
	ds_read_b128 v[178:181], v162 offset:34816
	ds_read_b128 v[182:185], v162 offset:35840
	ds_read_b128 v[186:189], v162 offset:36864
	ds_read_b128 v[190:193], v162 offset:37888
	ds_read_b128 v[196:199], v162 offset:38912
	ds_read_b128 v[202:205], v162 offset:39936
	global_load_lds_dwordx4 v128, s[30:31]
	s_mov_b32 m0, s40
	s_nop 0
	global_load_lds_dwordx4 v132, s[30:31]
	s_waitcnt lgkmcnt(8)
	s_barrier
	s_waitcnt lgkmcnt(0)
	s_setprio 1
	s_waitcnt lgkmcnt(0)
	v_mfma_f32_16x16x32_bf16 v[124:127], v[148:151], v[170:173], v[124:127]
	v_mfma_f32_16x16x32_bf16 v[120:123], v[156:159], v[170:173], v[120:123]
	v_mfma_f32_16x16x32_bf16 v[112:115], v[148:151], v[178:181], v[112:115]
	v_mfma_f32_16x16x32_bf16 v[108:111], v[156:159], v[178:181], v[108:111]
	v_mfma_f32_16x16x32_bf16 v[100:103], v[148:151], v[186:189], v[100:103]
	v_mfma_f32_16x16x32_bf16 v[92:95], v[156:159], v[186:189], v[92:95]
	v_mfma_f32_16x16x32_bf16 v[84:87], v[148:151], v[196:199], v[84:87]
	v_mfma_f32_16x16x32_bf16 v[76:79], v[156:159], v[196:199], v[76:79]
	v_mfma_f32_16x16x32_bf16 v[124:127], v[152:155], v[174:177], v[124:127]
	v_mfma_f32_16x16x32_bf16 v[120:123], v[166:169], v[174:177], v[120:123]
	v_mfma_f32_16x16x32_bf16 v[112:115], v[152:155], v[182:185], v[112:115]
	v_mfma_f32_16x16x32_bf16 v[108:111], v[166:169], v[182:185], v[108:111]
	v_mfma_f32_16x16x32_bf16 v[100:103], v[152:155], v[190:193], v[100:103]
	v_mfma_f32_16x16x32_bf16 v[92:95], v[166:169], v[190:193], v[92:95]
	v_mfma_f32_16x16x32_bf16 v[84:87], v[152:155], v[202:205], v[84:87]
	v_mfma_f32_16x16x32_bf16 v[76:79], v[166:169], v[202:205], v[76:79]
	s_setprio 0
	s_barrier
	s_add_i32 s30, 0, 0x1c000
	s_add_i32 s31, s58, s36
	v_add_u32_e32 v136, s30, v160
	s_mov_b32 m0, s31
	ds_read_b128 v[206:209], v136
	ds_read_b128 v[210:213], v136 offset:1024
	ds_read_b128 v[214:217], v136 offset:2048
	ds_read_b128 v[218:221], v136 offset:3072
	global_load_lds_dwordx4 v130, s[98:99]
	s_add_i32 m0, s31, 0x2000
	s_nop 0
	global_load_lds_dwordx4 v134, s[98:99]
	s_barrier
	s_waitcnt lgkmcnt(0)
	s_setprio 1
	s_waitcnt lgkmcnt(0)
	v_mfma_f32_16x16x32_bf16 v[116:119], v[206:209], v[170:173], v[116:119]
	v_mfma_f32_16x16x32_bf16 v[104:107], v[214:217], v[170:173], v[104:107]
	v_mfma_f32_16x16x32_bf16 v[96:99], v[206:209], v[178:181], v[96:99]
	v_mfma_f32_16x16x32_bf16 v[88:91], v[214:217], v[178:181], v[88:91]
	v_mfma_f32_16x16x32_bf16 v[80:83], v[206:209], v[186:189], v[80:83]
	v_mfma_f32_16x16x32_bf16 v[72:75], v[214:217], v[186:189], v[72:75]
	v_mfma_f32_16x16x32_bf16 v[68:71], v[206:209], v[196:199], v[68:71]
	v_mfma_f32_16x16x32_bf16 v[64:67], v[214:217], v[196:199], v[64:67]
	v_mfma_f32_16x16x32_bf16 v[116:119], v[210:213], v[174:177], v[116:119]
	v_mfma_f32_16x16x32_bf16 v[104:107], v[218:221], v[174:177], v[104:107]
	v_mfma_f32_16x16x32_bf16 v[96:99], v[210:213], v[182:185], v[96:99]
	v_mfma_f32_16x16x32_bf16 v[88:91], v[218:221], v[182:185], v[88:91]
	v_mfma_f32_16x16x32_bf16 v[80:83], v[210:213], v[190:193], v[80:83]
	v_mfma_f32_16x16x32_bf16 v[72:75], v[218:221], v[190:193], v[72:75]
	v_mfma_f32_16x16x32_bf16 v[68:71], v[210:213], v[202:205], v[68:71]
	v_mfma_f32_16x16x32_bf16 v[64:67], v[218:221], v[202:205], v[64:67]
	s_setprio 0
	s_mov_b32 m0, s41
	s_barrier
	ds_read_b128 v[170:173], v162 offset:49152
	ds_read_b128 v[174:177], v162 offset:50176
	ds_read_b128 v[178:181], v162 offset:51200
	ds_read_b128 v[182:185], v162 offset:52224
	ds_read_b128 v[186:189], v162 offset:53248
	ds_read_b128 v[190:193], v162 offset:54272
	ds_read_b128 v[196:199], v162 offset:55296
	ds_read_b128 v[202:205], v162 offset:56320
	global_load_lds_dwordx4 v128, s[100:101]
	s_mov_b32 m0, s42
	s_nop 0
	global_load_lds_dwordx4 v132, s[100:101]
	s_barrier
; __device__ __forceinline__ unsigned cvt_pk_bf16(float lo, float hi) { const bf16x2_t r = __builtin_convertvector((f32x2){lo, hi}, bf16x2_t); return __builtin_bit_cast(unsigned, r); }
; #define PG8_STAGE(bufoff, gbase, voff) do { _Pragma("unroll") for (int _i = 0; _i < 2; ++_i) \
;         __builtin_amdgcn_global_load_lds((const unsigned*)((const char*)(gbase) + (voff)[_i]), (LAS unsigned*)(lds + (bufoff) + ldsw + _i * 8192), 16, 0, 0); } while (0)
; #define PG8_WAIT_V(n) asm volatile("s_waitcnt vmcnt(" #n ")" ::: "memory")
; #define PG8_WAIT_L(n) asm volatile("s_waitcnt lgkmcnt(" #n ")" ::: "memory")
; #define PG8_BAR __builtin_amdgcn_s_barrier()
; #define PG8_SCHED __builtin_amdgcn_sched_barrier(0)
; template <class Epi>
; __device__ __forceinline__ void gemm_phase(LAS unsigned char* lds, const bf16_t* A, int lda, const bf16_t* Bt, int ldb, int M, int N, int K, int asel, const Epi& E, const int fixed_round = -1) {
;     ...
;             PG8_BAR; PG8_WAIT_L(0); PG8_MMA(1, 0, At, B0); PG8_BAR; PG8_SCHED;
;             PG8_STAGE(PG8_SB(1, 1), b3 + hstepB, voffB);
;             PG8_WAIT_V(6); PG8_BAR; PG8_MMA(1, 1, At, B1); PG8_BAR;
;     __device__ __forceinline__ void operator()(const AccT& acc, const Unit& u, int wr, int wc, int fr, int fq) const {
;     ...
;         if (pn < 8) {
;             bf16_t* base = pn < 4 ? Q : Kn; const int colt = (pn & 3) * BM; const float sc = pn < 4 ? 0.08838834764831845f : 1.0f;
; #pragma unroll
;             for (int ai = 0; ai < 2; ++ai)
; #pragma unroll
;                 for (int m = 0; m < 4; ++m) { bf16_t* rowp = base + (size_t)(row0 + ai * HALF + m * 16) * 1024 + colt + cl;
; #pragma unroll
;                     for (int bj = 0; bj < 2; ++bj) { const f32x4 v0 = acc[ai][bj][m][0] * sc, v1 = acc[ai][bj][m][1] * sc;
;                         u32x4 w; w.x = cvt_pk_bf16(v0[0], v0[1]); w.y = cvt_pk_bf16(v0[2], v0[3]); w.z = cvt_pk_bf16(v1[0], v1[1]); w.w = cvt_pk_bf16(v1[2], v1[3]);
;                         *(u32x4*)(rowp + bj * HALF) = w; } }
	s_waitcnt lgkmcnt(0)
	s_setprio 1
	s_waitcnt lgkmcnt(0)
	v_mfma_f32_16x16x32_bf16 v[60:63], v[148:151], v[170:173], v[60:63]
	v_mfma_f32_16x16x32_bf16 v[56:59], v[156:159], v[170:173], v[56:59]
	v_mfma_f32_16x16x32_bf16 v[52:55], v[148:151], v[178:181], v[52:55]
	v_mfma_f32_16x16x32_bf16 v[44:47], v[156:159], v[178:181], v[44:47]
	v_mfma_f32_16x16x32_bf16 v[36:39], v[148:151], v[186:189], v[36:39]
	v_mfma_f32_16x16x32_bf16 v[28:31], v[156:159], v[186:189], v[28:31]
	v_mfma_f32_16x16x32_bf16 v[20:23], v[148:151], v[196:199], v[20:23]
	v_mfma_f32_16x16x32_bf16 v[12:15], v[156:159], v[196:199], v[12:15]
	v_mfma_f32_16x16x32_bf16 v[60:63], v[152:155], v[174:177], v[60:63]
	v_mfma_f32_16x16x32_bf16 v[56:59], v[166:169], v[174:177], v[56:59]
	v_mfma_f32_16x16x32_bf16 v[52:55], v[152:155], v[182:185], v[52:55]
	v_mfma_f32_16x16x32_bf16 v[44:47], v[166:169], v[182:185], v[44:47]
	v_mfma_f32_16x16x32_bf16 v[36:39], v[152:155], v[190:193], v[36:39]
	v_mfma_f32_16x16x32_bf16 v[28:31], v[166:169], v[190:193], v[28:31]
	v_mfma_f32_16x16x32_bf16 v[20:23], v[152:155], v[202:205], v[20:23]
	v_mfma_f32_16x16x32_bf16 v[12:15], v[166:169], v[202:205], v[12:15]
	s_setprio 0
	s_barrier
	s_add_u32 s28, s28, 0x80080
	s_addc_u32 s29, s29, 0
	s_add_i32 s30, s30, s36
	s_mov_b32 m0, s30
	s_nop 0
	global_load_lds_dwordx4 v130, s[28:29]
	s_add_i32 m0, s30, 0x2000
	s_nop 0
	global_load_lds_dwordx4 v134, s[28:29]
	s_waitcnt vmcnt(6)
	s_barrier
	s_setprio 1
	v_mfma_f32_16x16x32_bf16 v[48:51], v[206:209], v[170:173], v[48:51]
	v_mfma_f32_16x16x32_bf16 v[40:43], v[214:217], v[170:173], v[40:43]
	v_mfma_f32_16x16x32_bf16 v[32:35], v[206:209], v[178:181], v[32:35]
	v_mfma_f32_16x16x32_bf16 v[24:27], v[214:217], v[178:181], v[24:27]
	v_mfma_f32_16x16x32_bf16 v[16:19], v[206:209], v[186:189], v[16:19]
	v_mfma_f32_16x16x32_bf16 v[8:11], v[214:217], v[186:189], v[8:11]
	v_mfma_f32_16x16x32_bf16 v[4:7], v[206:209], v[196:199], v[4:7]
	v_mfma_f32_16x16x32_bf16 v[0:3], v[214:217], v[196:199], v[0:3]
	v_mfma_f32_16x16x32_bf16 v[48:51], v[210:213], v[174:177], v[48:51]
	v_mfma_f32_16x16x32_bf16 v[40:43], v[218:221], v[174:177], v[40:43]
	v_mfma_f32_16x16x32_bf16 v[32:35], v[210:213], v[182:185], v[32:35]
	v_mfma_f32_16x16x32_bf16 v[24:27], v[218:221], v[182:185], v[24:27]
	v_mfma_f32_16x16x32_bf16 v[16:19], v[210:213], v[190:193], v[16:19]
	v_mfma_f32_16x16x32_bf16 v[8:11], v[218:221], v[190:193], v[8:11]
	v_mfma_f32_16x16x32_bf16 v[4:7], v[210:213], v[202:205], v[4:7]
	v_mfma_f32_16x16x32_bf16 v[0:3], v[218:221], v[202:205], v[0:3]
	s_setprio 0
	s_add_i32 s57, s57, 2
	s_add_u32 s26, s26, 0x100
	s_addc_u32 s27, s27, 0
	s_add_u32 s55, s55, 0x100
	s_addc_u32 s56, s56, 0
	s_cmp_gt_u32 s57, 29
	s_cbranch_scc0 .Lrot_3
	s_barrier
	s_lshl_b32 s17, s24, 8
	v_add_u32_e32 v154, s17, v139
	s_cmp_lt_i32 s25, -8
	v_or_b32_e32 v152, 16, v154
	v_or_b32_e32 v150, 32, v154
	v_or_b32_e32 v148, 48, v154
	s_cselect_b64 s[26:27], -1, 0
	s_cmp_gt_i32 s25, -9
	v_ashrrev_i32_e32 v155, 31, v154
	v_lshlrev_b32_e32 v136, 1, v138
	v_ashrrev_i32_e32 v153, 31, v152
	v_ashrrev_i32_e32 v151, 31, v150
	v_ashrrev_i32_e32 v149, 31, v148
	s_cbranch_scc1 .LBB0_248
	s_cmp_lt_u32 s25, -12
	s_cselect_b64 vcc, -1, 0
	s_and_b64 s[28:29], vcc, exec
	s_cselect_b32 s2, s89, s81
	s_cselect_b32 s19, s88, s91
	s_lshl_b32 s28, s25, 9
	s_and_b32 s28, s28, 0x600
	s_add_u32 s28, s19, s28
	v_cndmask_b32_e32 v156, 1.0, v164, vcc
	s_addc_u32 s29, s2, 0
	v_lshl_add_u64 v[170:171], s[28:29], 0, v[136:137]
	v_lshlrev_b64 v[158:159], 11, v[154:155]
	v_pk_mul_f32 v[168:169], v[156:157], v[126:127] op_sel_hi:[0,1]
	v_pk_mul_f32 v[166:167], v[156:157], v[124:125] op_sel_hi:[0,1]
	v_pk_mul_f32 v[172:173], v[156:157], v[122:123] op_sel_hi:[0,1]
	v_pk_mul_f32 v[174:175], v[156:157], v[120:121] op_sel_hi:[0,1]
	v_lshl_add_u64 v[158:159], v[170:171], 0, v[158:159]
	v_cvt_pk_bf16_f32 v166, v166, v167
	v_cvt_pk_bf16_f32 v167, v168, v169
	v_cvt_pk_bf16_f32 v168, v174, v175
	v_cvt_pk_bf16_f32 v169, v172, v173
	global_store_dwordx4 v[158:159], v[166:169], off
	v_pk_mul_f32 v[172:173], v[156:157], v[106:107] op_sel_hi:[0,1]
	v_pk_mul_f32 v[174:175], v[156:157], v[104:105] op_sel_hi:[0,1]
	v_pk_mul_f32 v[168:169], v[156:157], v[118:119] op_sel_hi:[0,1]
	v_pk_mul_f32 v[166:167], v[156:157], v[116:117] op_sel_hi:[0,1]
	v_cvt_pk_bf16_f32 v166, v166, v167
	v_cvt_pk_bf16_f32 v167, v168, v169
	v_cvt_pk_bf16_f32 v168, v174, v175
	v_cvt_pk_bf16_f32 v169, v172, v173
	global_store_dwordx4 v[158:159], v[166:169], off offset:256
	v_pk_mul_f32 v[174:175], v[156:157], v[110:111] op_sel_hi:[0,1]
	v_pk_mul_f32 v[176:177], v[156:157], v[108:109] op_sel_hi:[0,1]
	v_lshlrev_b64 v[166:167], 11, v[152:153]
	v_lshl_add_u64 v[172:173], v[170:171], 0, v[166:167]
	v_pk_mul_f32 v[168:169], v[156:157], v[114:115] op_sel_hi:[0,1]
	v_pk_mul_f32 v[166:167], v[156:157], v[112:113] op_sel_hi:[0,1]
	v_cvt_pk_bf16_f32 v166, v166, v167
	v_cvt_pk_bf16_f32 v167, v168, v169
	v_cvt_pk_bf16_f32 v168, v176, v177
	v_cvt_pk_bf16_f32 v169, v174, v175
	global_store_dwordx4 v[172:173], v[166:169], off
	v_pk_mul_f32 v[174:175], v[156:157], v[90:91] op_sel_hi:[0,1]
	v_pk_mul_f32 v[176:177], v[156:157], v[88:89] op_sel_hi:[0,1]
	v_pk_mul_f32 v[168:169], v[156:157], v[98:99] op_sel_hi:[0,1]
	v_pk_mul_f32 v[166:167], v[156:157], v[96:97] op_sel_hi:[0,1]
	v_cvt_pk_bf16_f32 v166, v166, v167
	v_cvt_pk_bf16_f32 v167, v168, v169
	v_cvt_pk_bf16_f32 v168, v176, v177
	v_cvt_pk_bf16_f32 v169, v174, v175
	global_store_dwordx4 v[172:173], v[166:169], off offset:256
	v_pk_mul_f32 v[174:175], v[156:157], v[94:95] op_sel_hi:[0,1]
	v_pk_mul_f32 v[176:177], v[156:157], v[92:93] op_sel_hi:[0,1]
	v_lshlrev_b64 v[166:167], 11, v[150:151]
; __device__ __forceinline__ unsigned cvt_pk_bf16(float lo, float hi) { const bf16x2_t r = __builtin_convertvector((f32x2){lo, hi}, bf16x2_t); return __builtin_bit_cast(unsigned, r); }
;     __device__ __forceinline__ void operator()(const AccT& acc, const Unit& u, int wr, int wc, int fr, int fq) const {
;     ...
;         if (pn < 8) {
;             bf16_t* base = pn < 4 ? Q : Kn; const int colt = (pn & 3) * BM; const float sc = pn < 4 ? 0.08838834764831845f : 1.0f;
; #pragma unroll
;             for (int ai = 0; ai < 2; ++ai)
; #pragma unroll
;                 for (int m = 0; m < 4; ++m) { bf16_t* rowp = base + (size_t)(row0 + ai * HALF + m * 16) * 1024 + colt + cl;
; #pragma unroll
;                     for (int bj = 0; bj < 2; ++bj) { const f32x4 v0 = acc[ai][bj][m][0] * sc, v1 = acc[ai][bj][m][1] * sc;
;                         u32x4 w; w.x = cvt_pk_bf16(v0[0], v0[1]); w.y = cvt_pk_bf16(v0[2], v0[3]); w.z = cvt_pk_bf16(v1[0], v1[1]); w.w = cvt_pk_bf16(v1[2], v1[3]);
;                         *(u32x4*)(rowp + bj * HALF) = w; } }
	v_lshl_add_u64 v[172:173], v[170:171], 0, v[166:167]
	v_pk_mul_f32 v[168:169], v[156:157], v[102:103] op_sel_hi:[0,1]
	v_pk_mul_f32 v[166:167], v[156:157], v[100:101] op_sel_hi:[0,1]
	v_cvt_pk_bf16_f32 v166, v166, v167
	v_cvt_pk_bf16_f32 v167, v168, v169
	v_cvt_pk_bf16_f32 v168, v176, v177
	v_cvt_pk_bf16_f32 v169, v174, v175
	global_store_dwordx4 v[172:173], v[166:169], off
	v_pk_mul_f32 v[174:175], v[156:157], v[74:75] op_sel_hi:[0,1]
	v_pk_mul_f32 v[176:177], v[156:157], v[72:73] op_sel_hi:[0,1]
	v_pk_mul_f32 v[168:169], v[156:157], v[82:83] op_sel_hi:[0,1]
	v_pk_mul_f32 v[166:167], v[156:157], v[80:81] op_sel_hi:[0,1]
	v_cvt_pk_bf16_f32 v166, v166, v167
	v_cvt_pk_bf16_f32 v167, v168, v169
	v_cvt_pk_bf16_f32 v168, v176, v177
	v_cvt_pk_bf16_f32 v169, v174, v175
	global_store_dwordx4 v[172:173], v[166:169], off offset:256
	v_pk_mul_f32 v[172:173], v[156:157], v[78:79] op_sel_hi:[0,1]
	v_pk_mul_f32 v[174:175], v[156:157], v[76:77] op_sel_hi:[0,1]
	v_lshlrev_b64 v[166:167], 11, v[148:149]
	v_lshl_add_u64 v[170:171], v[170:171], 0, v[166:167]
	v_pk_mul_f32 v[168:169], v[156:157], v[86:87] op_sel_hi:[0,1]
	v_pk_mul_f32 v[166:167], v[156:157], v[84:85] op_sel_hi:[0,1]
	v_cvt_pk_bf16_f32 v166, v166, v167
	v_cvt_pk_bf16_f32 v167, v168, v169
	v_cvt_pk_bf16_f32 v168, v174, v175
	v_cvt_pk_bf16_f32 v169, v172, v173
	global_store_dwordx4 v[170:171], v[166:169], off
	v_pk_mul_f32 v[172:173], v[156:157], v[66:67] op_sel_hi:[0,1]
	v_pk_mul_f32 v[174:175], v[156:157], v[64:65] op_sel_hi:[0,1]
	v_pk_mul_f32 v[168:169], v[156:157], v[70:71] op_sel_hi:[0,1]
	v_pk_mul_f32 v[166:167], v[156:157], v[68:69] op_sel_hi:[0,1]
	v_cvt_pk_bf16_f32 v166, v166, v167
	v_cvt_pk_bf16_f32 v167, v168, v169
	v_cvt_pk_bf16_f32 v168, v174, v175
	v_cvt_pk_bf16_f32 v169, v172, v173
	global_store_dwordx4 v[170:171], v[166:169], off offset:256
	v_pk_mul_f32 v[172:173], v[156:157], v[58:59] op_sel_hi:[0,1]
	s_mov_b32 s2, 0x40000
	v_pk_mul_f32 v[168:169], v[156:157], v[62:63] op_sel_hi:[0,1]
	v_pk_mul_f32 v[166:167], v[156:157], v[60:61] op_sel_hi:[0,1]
	v_pk_mul_f32 v[174:175], v[156:157], v[56:57] op_sel_hi:[0,1]
	v_cvt_pk_bf16_f32 v166, v166, v167
	v_cvt_pk_bf16_f32 v167, v168, v169
	v_cvt_pk_bf16_f32 v169, v172, v173
	v_add_co_u32_e32 v172, vcc, s2, v158
	v_cvt_pk_bf16_f32 v168, v174, v175
	s_nop 0
	v_addc_co_u32_e32 v173, vcc, 0, v159, vcc
	s_mov_b64 s[28:29], 0x40000
	global_store_dwordx4 v[172:173], v[166:169], off
	v_pk_mul_f32 v[172:173], v[156:157], v[42:43] op_sel_hi:[0,1]
	v_pk_mul_f32 v[174:175], v[156:157], v[40:41] op_sel_hi:[0,1]
	v_pk_mul_f32 v[168:169], v[156:157], v[50:51] op_sel_hi:[0,1]
	v_pk_mul_f32 v[166:167], v[156:157], v[48:49] op_sel_hi:[0,1]
	v_lshl_add_u64 v[170:171], v[158:159], 0, s[28:29]
	v_cvt_pk_bf16_f32 v166, v166, v167
	v_cvt_pk_bf16_f32 v167, v168, v169
	v_cvt_pk_bf16_f32 v168, v174, v175
	v_cvt_pk_bf16_f32 v169, v172, v173
	global_store_dwordx4 v[170:171], v[166:169], off offset:256
	v_pk_mul_f32 v[172:173], v[156:157], v[46:47] op_sel_hi:[0,1]
	v_pk_mul_f32 v[174:175], v[156:157], v[44:45] op_sel_hi:[0,1]
	v_pk_mul_f32 v[168:169], v[156:157], v[54:55] op_sel_hi:[0,1]
	v_pk_mul_f32 v[166:167], v[156:157], v[52:53] op_sel_hi:[0,1]
	v_cvt_pk_bf16_f32 v166, v166, v167
	v_cvt_pk_bf16_f32 v167, v168, v169
	v_cvt_pk_bf16_f32 v169, v172, v173
	v_add_co_u32_e32 v172, vcc, s46, v158
	v_cvt_pk_bf16_f32 v168, v174, v175
	s_nop 0
	v_addc_co_u32_e32 v173, vcc, 0, v159, vcc
	s_mov_b64 s[28:29], 0x48000
	global_store_dwordx4 v[172:173], v[166:169], off
	v_pk_mul_f32 v[172:173], v[156:157], v[26:27] op_sel_hi:[0,1]
	v_pk_mul_f32 v[174:175], v[156:157], v[24:25] op_sel_hi:[0,1]
	v_pk_mul_f32 v[168:169], v[156:157], v[34:35] op_sel_hi:[0,1]
	v_pk_mul_f32 v[166:167], v[156:157], v[32:33] op_sel_hi:[0,1]
	v_lshl_add_u64 v[170:171], v[158:159], 0, s[28:29]
	v_cvt_pk_bf16_f32 v166, v166, v167
	v_cvt_pk_bf16_f32 v167, v168, v169
	v_cvt_pk_bf16_f32 v168, v174, v175
	v_cvt_pk_bf16_f32 v169, v172, v173
	global_store_dwordx4 v[170:171], v[166:169], off offset:256
	v_pk_mul_f32 v[172:173], v[156:157], v[30:31] op_sel_hi:[0,1]
	v_pk_mul_f32 v[174:175], v[156:157], v[28:29] op_sel_hi:[0,1]
	v_pk_mul_f32 v[168:169], v[156:157], v[38:39] op_sel_hi:[0,1]
	v_pk_mul_f32 v[166:167], v[156:157], v[36:37] op_sel_hi:[0,1]
	v_cvt_pk_bf16_f32 v166, v166, v167
	v_cvt_pk_bf16_f32 v167, v168, v169
	v_cvt_pk_bf16_f32 v169, v172, v173
	v_add_co_u32_e32 v172, vcc, s47, v158
	v_cvt_pk_bf16_f32 v168, v174, v175
	s_nop 0
	v_addc_co_u32_e32 v173, vcc, 0, v159, vcc
	global_store_dwordx4 v[172:173], v[166:169], off
	v_pk_mul_f32 v[172:173], v[156:157], v[10:11] op_sel_hi:[0,1]
	v_pk_mul_f32 v[174:175], v[156:157], v[8:9] op_sel_hi:[0,1]
	v_pk_mul_f32 v[168:169], v[156:157], v[18:19] op_sel_hi:[0,1]
	v_pk_mul_f32 v[166:167], v[156:157], v[16:17] op_sel_hi:[0,1]
	v_lshl_add_u64 v[170:171], v[158:159], 0, s[6:7]
	v_cvt_pk_bf16_f32 v166, v166, v167
	v_cvt_pk_bf16_f32 v167, v168, v169
	v_cvt_pk_bf16_f32 v168, v174, v175
	v_cvt_pk_bf16_f32 v169, v172, v173
	global_store_dwordx4 v[170:171], v[166:169], off offset:256
	v_lshl_add_u64 v[170:171], v[158:159], 0, s[8:9]
	v_pk_mul_f32 v[172:173], v[156:157], v[14:15] op_sel_hi:[0,1]
	v_pk_mul_f32 v[168:169], v[156:157], v[22:23] op_sel_hi:[0,1]
	v_pk_mul_f32 v[166:167], v[156:157], v[20:21] op_sel_hi:[0,1]
	v_pk_mul_f32 v[174:175], v[156:157], v[12:13] op_sel_hi:[0,1]
	v_add_co_u32_e32 v158, vcc, s48, v158
	v_cvt_pk_bf16_f32 v166, v166, v167
	v_cvt_pk_bf16_f32 v167, v168, v169
	v_cvt_pk_bf16_f32 v168, v174, v175
	v_cvt_pk_bf16_f32 v169, v172, v173
	v_addc_co_u32_e32 v159, vcc, 0, v159, vcc
	global_store_dwordx4 v[158:159], v[166:169], off
	v_pk_mul_f32 v[158:159], v[156:157], v[6:7] op_sel_hi:[0,1]
	v_pk_mul_f32 v[172:173], v[156:157], v[0:1] op_sel_hi:[0,1]
	v_pk_mul_f32 v[166:167], v[156:157], v[4:5] op_sel_hi:[0,1]
	v_pk_mul_f32 v[168:169], v[156:157], v[2:3] op_sel_hi:[0,1]
	v_cvt_pk_bf16_f32 v156, v166, v167
	v_cvt_pk_bf16_f32 v157, v158, v159
	v_cvt_pk_bf16_f32 v158, v172, v173
	v_cvt_pk_bf16_f32 v159, v168, v169
	global_store_dwordx4 v[170:171], v[156:159], off offset:256

; #define PG8_STAGE(bufoff, gbase, voff) do { _Pragma("unroll") for (int _i = 0; _i < 2; ++_i) \
;         __builtin_amdgcn_global_load_lds((const unsigned*)((const char*)(gbase) + (voff)[_i]), (LAS unsigned*)(lds + (bufoff) + ldsw + _i * 8192), 16, 0, 0); } while (0)
; #define PG8_LDA(dst, b, h) do { _Pragma("unroll") for (int m = 0; m < 4; ++m) _Pragma("unroll") for (int k = 0; k < 2; ++k) dst[m][k] = *(const LAS bf16x8*)(lds + PG8_SA(b, h) + aoff + m * 2048 + k * 1024); } while (0)
; #define PG8_LDB(dst, b, h) do { _Pragma("unroll") for (int n = 0; n < 2; ++n) _Pragma("unroll") for (int k = 0; k < 2; ++k) dst[n][k] = *(const LAS bf16x8*)(lds + PG8_SB(b, h) + boff + n * 2048 + k * 1024); } while (0)
; #define PG8_WAIT_V(n) asm volatile("s_waitcnt vmcnt(" #n ")" ::: "memory")
; #define PG8_WAIT_L(n) asm volatile("s_waitcnt lgkmcnt(" #n ")" ::: "memory")
; #define PG8_BAR __builtin_amdgcn_s_barrier()
; #define PG8_SCHED __builtin_amdgcn_sched_barrier(0)
; template <class Epi>
; __device__ __forceinline__ void gemm_phase(LAS unsigned char* lds, const bf16_t* A, int lda, const bf16_t* Bt, int ldb, int M, int N, int K, int asel, const Epi& E, const int fixed_round = -1) {
;     ...
;         const char* nA = has_next ? PG8_ABASE(nxt) : cA; const char* nB = has_next ? (const char*)Bt + (size_t)nxt.pn * tstepB : cB;
;         for (int t = 0; t < nt; t += 2) {
;             const bool last = (t == nt - 2);
;             const char* a1 = cA + (size_t)(t + 1) * kstep;
;             const char* a2 = last ? nA : cA + (size_t)(t + 2) * kstep; const char* b2 = last ? nB : cB + (size_t)(t + 2) * kstep;
;             const char* a3 = a2 + kstep; const char* b3 = b2 + kstep;
;             PG8_LDB(B0, 0, 0); PG8_SCHED; PG8_LDA(At, 0, 0); PG8_STAGE(PG8_SA(1, 1), a1 + hstepA, voffA);
;             PG8_WAIT_L(8); PG8_BAR; PG8_WAIT_L(0); PG8_MMA(0, 0, At, B0); PG8_BAR; PG8_SCHED;
;             PG8_LDB(B1, 0, 1); PG8_STAGE(PG8_SB(0, 0), b2, voffB);
;             PG8_BAR; PG8_WAIT_L(0); PG8_MMA(0, 1, At, B1); PG8_BAR;
;             PG8_LDA(At, 0, 1); PG8_STAGE(PG8_SA(0, 0), a2, voffA);
;             PG8_BAR; PG8_WAIT_L(0); PG8_MMA(1, 0, At, B0); PG8_BAR; PG8_SCHED;
;             PG8_STAGE(PG8_SB(0, 1), b2 + hstepB, voffB);
;             PG8_WAIT_V(6); PG8_BAR; PG8_MMA(1, 1, At, B1); PG8_BAR;
.LBB0_591:
	ds_read_b128 v[152:155], v149
	ds_read_b128 v[156:159], v149 offset:1024
	ds_read_b128 v[160:163], v149 offset:2048
	ds_read_b128 v[164:167], v149 offset:3072
	s_add_i32 m0, s27, 0xc000
	ds_read_b128 v[168:171], v150
	ds_read_b128 v[172:175], v150 offset:1024
	ds_read_b128 v[176:179], v150 offset:2048
	ds_read_b128 v[180:183], v150 offset:3072
	ds_read_b128 v[184:187], v150 offset:4096
	ds_read_b128 v[188:191], v150 offset:5120
	ds_read_b128 v[192:195], v150 offset:6144
	ds_read_b128 v[196:199], v150 offset:7168
	global_load_lds_dwordx4 v136, s[30:31]
	s_add_i32 m0, s27, 0xe000
	s_nop 0
	global_load_lds_dwordx4 v138, s[30:31]
	s_waitcnt lgkmcnt(8)
	s_barrier
	s_waitcnt lgkmcnt(0)
	s_setprio 1
	s_waitcnt lgkmcnt(0)
	v_mfma_f32_16x16x32_bf16 v[124:127], v[152:155], v[168:171], v[124:127]
	v_mfma_f32_16x16x32_bf16 v[120:123], v[160:163], v[168:171], v[120:123]
	v_mfma_f32_16x16x32_bf16 v[108:111], v[152:155], v[176:179], v[108:111]
	v_mfma_f32_16x16x32_bf16 v[104:107], v[160:163], v[176:179], v[104:107]
	v_mfma_f32_16x16x32_bf16 v[92:95], v[152:155], v[184:187], v[92:95]
	v_mfma_f32_16x16x32_bf16 v[88:91], v[160:163], v[184:187], v[88:91]
	v_mfma_f32_16x16x32_bf16 v[76:79], v[152:155], v[192:195], v[76:79]
	v_mfma_f32_16x16x32_bf16 v[72:75], v[160:163], v[192:195], v[72:75]
	v_mfma_f32_16x16x32_bf16 v[124:127], v[156:159], v[172:175], v[124:127]
	v_mfma_f32_16x16x32_bf16 v[120:123], v[164:167], v[172:175], v[120:123]
	v_mfma_f32_16x16x32_bf16 v[108:111], v[156:159], v[180:183], v[108:111]
	v_mfma_f32_16x16x32_bf16 v[104:107], v[164:167], v[180:183], v[104:107]
	v_mfma_f32_16x16x32_bf16 v[92:95], v[156:159], v[188:191], v[92:95]
	v_mfma_f32_16x16x32_bf16 v[88:91], v[164:167], v[188:191], v[88:91]
	v_mfma_f32_16x16x32_bf16 v[76:79], v[156:159], v[196:199], v[76:79]
	v_mfma_f32_16x16x32_bf16 v[72:75], v[164:167], v[196:199], v[72:75]
	s_setprio 0
	s_barrier
	s_add_u32 s28, s30, 0xfff80080
	s_addc_u32 s29, s31, -1
	s_cmp_eq_u32 s56, 28
	s_cselect_b32 s37, s7, s29
	s_cselect_b32 s36, s52, s28
	s_cselect_b32 s35, s5, s55
	s_cselect_b32 s34, s53, s54
	s_add_i32 s28, s81, s42
	s_add_u32 s98, s34, s2
	s_addc_u32 s99, s35, s3
	s_mov_b32 m0, s28
	ds_read_b128 v[202:205], v151
	ds_read_b128 v[206:209], v151 offset:1024
	ds_read_b128 v[210:213], v151 offset:2048
	ds_read_b128 v[214:217], v151 offset:3072
	global_load_lds_dwordx4 v130, s[34:35]
	s_add_i32 m0, s28, 0x2000
	s_nop 0
	global_load_lds_dwordx4 v134, s[34:35]
	s_barrier
	s_waitcnt lgkmcnt(0)
	s_setprio 1
	s_waitcnt lgkmcnt(0)
	v_mfma_f32_16x16x32_bf16 v[116:119], v[202:205], v[168:171], v[116:119]
	v_mfma_f32_16x16x32_bf16 v[112:115], v[210:213], v[168:171], v[112:115]
	v_mfma_f32_16x16x32_bf16 v[100:103], v[202:205], v[176:179], v[100:103]
	v_mfma_f32_16x16x32_bf16 v[96:99], v[210:213], v[176:179], v[96:99]
	v_mfma_f32_16x16x32_bf16 v[84:87], v[202:205], v[184:187], v[84:87]
	v_mfma_f32_16x16x32_bf16 v[80:83], v[210:213], v[184:187], v[80:83]
	v_mfma_f32_16x16x32_bf16 v[68:71], v[202:205], v[192:195], v[68:71]
	v_mfma_f32_16x16x32_bf16 v[64:67], v[210:213], v[192:195], v[64:67]
	v_mfma_f32_16x16x32_bf16 v[116:119], v[206:209], v[172:175], v[116:119]
	v_mfma_f32_16x16x32_bf16 v[112:115], v[214:217], v[172:175], v[112:115]
	v_mfma_f32_16x16x32_bf16 v[100:103], v[206:209], v[180:183], v[100:103]
	v_mfma_f32_16x16x32_bf16 v[96:99], v[214:217], v[180:183], v[96:99]
	v_mfma_f32_16x16x32_bf16 v[84:87], v[206:209], v[188:191], v[84:87]
	v_mfma_f32_16x16x32_bf16 v[80:83], v[214:217], v[188:191], v[80:83]
	v_mfma_f32_16x16x32_bf16 v[68:71], v[206:209], v[196:199], v[68:71]
	v_mfma_f32_16x16x32_bf16 v[64:67], v[214:217], v[196:199], v[64:67]
	s_setprio 0
	s_mov_b32 m0, s27
	s_add_u32 s100, s36, s2
	s_addc_u32 s101, s37, s3
	s_barrier
	ds_read_b128 v[168:171], v150 offset:16384
	ds_read_b128 v[172:175], v150 offset:17408
	ds_read_b128 v[176:179], v150 offset:18432
	ds_read_b128 v[180:183], v150 offset:19456
	ds_read_b128 v[184:187], v150 offset:20480
	ds_read_b128 v[188:191], v150 offset:21504
	ds_read_b128 v[192:195], v150 offset:22528
	ds_read_b128 v[196:199], v150 offset:23552
	global_load_lds_dwordx4 v128, s[36:37]
	s_mov_b32 m0, s43
	s_nop 0
	global_load_lds_dwordx4 v132, s[36:37]
	s_barrier
	s_waitcnt lgkmcnt(0)
	s_setprio 1
	s_waitcnt lgkmcnt(0)
	v_mfma_f32_16x16x32_bf16 v[60:63], v[152:155], v[168:171], v[60:63]
	v_mfma_f32_16x16x32_bf16 v[56:59], v[160:163], v[168:171], v[56:59]
	v_mfma_f32_16x16x32_bf16 v[44:47], v[152:155], v[176:179], v[44:47]
	v_mfma_f32_16x16x32_bf16 v[40:43], v[160:163], v[176:179], v[40:43]
	v_mfma_f32_16x16x32_bf16 v[28:31], v[152:155], v[184:187], v[28:31]
	v_mfma_f32_16x16x32_bf16 v[24:27], v[160:163], v[184:187], v[24:27]
	v_mfma_f32_16x16x32_bf16 v[12:15], v[152:155], v[192:195], v[12:15]
	v_mfma_f32_16x16x32_bf16 v[8:11], v[160:163], v[192:195], v[8:11]
	v_mfma_f32_16x16x32_bf16 v[60:63], v[156:159], v[172:175], v[60:63]
	v_mfma_f32_16x16x32_bf16 v[56:59], v[164:167], v[172:175], v[56:59]
	v_mfma_f32_16x16x32_bf16 v[44:47], v[156:159], v[180:183], v[44:47]
	v_mfma_f32_16x16x32_bf16 v[40:43], v[164:167], v[180:183], v[40:43]
	v_mfma_f32_16x16x32_bf16 v[28:31], v[156:159], v[188:191], v[28:31]
	v_mfma_f32_16x16x32_bf16 v[24:27], v[164:167], v[188:191], v[24:27]
	v_mfma_f32_16x16x32_bf16 v[12:15], v[156:159], v[196:199], v[12:15]
	v_mfma_f32_16x16x32_bf16 v[8:11], v[164:167], v[196:199], v[8:11]
	s_setprio 0
	s_barrier
	s_add_u32 s28, s34, 0x80000
	s_addc_u32 s29, s35, 0
	s_add_i32 s57, s82, s42
	s_mov_b32 m0, s57
	s_nop 0
	global_load_lds_dwordx4 v130, s[28:29]
	s_add_i32 m0, s57, 0x2000
	s_nop 0
	global_load_lds_dwordx4 v134, s[28:29]
	s_waitcnt vmcnt(6)
	s_barrier
; #define PG8_STAGE(bufoff, gbase, voff) do { _Pragma("unroll") for (int _i = 0; _i < 2; ++_i) \
;         __builtin_amdgcn_global_load_lds((const unsigned*)((const char*)(gbase) + (voff)[_i]), (LAS unsigned*)(lds + (bufoff) + ldsw + _i * 8192), 16, 0, 0); } while (0)
; #define PG8_LDA(dst, b, h) do { _Pragma("unroll") for (int m = 0; m < 4; ++m) _Pragma("unroll") for (int k = 0; k < 2; ++k) dst[m][k] = *(const LAS bf16x8*)(lds + PG8_SA(b, h) + aoff + m * 2048 + k * 1024); } while (0)
; #define PG8_LDB(dst, b, h) do { _Pragma("unroll") for (int n = 0; n < 2; ++n) _Pragma("unroll") for (int k = 0; k < 2; ++k) dst[n][k] = *(const LAS bf16x8*)(lds + PG8_SB(b, h) + boff + n * 2048 + k * 1024); } while (0)
; #define PG8_WAIT_V(n) asm volatile("s_waitcnt vmcnt(" #n ")" ::: "memory")
; #define PG8_WAIT_L(n) asm volatile("s_waitcnt lgkmcnt(" #n ")" ::: "memory")
; #define PG8_BAR __builtin_amdgcn_s_barrier()
; #define PG8_SCHED __builtin_amdgcn_sched_barrier(0)
; template <class Epi>
; __device__ __forceinline__ void gemm_phase(LAS unsigned char* lds, const bf16_t* A, int lda, const bf16_t* Bt, int ldb, int M, int N, int K, int asel, const Epi& E, const int fixed_round = -1) {
;     ...
;             PG8_WAIT_V(6); PG8_BAR; PG8_MMA(1, 1, At, B1); PG8_BAR;
;             PG8_LDB(B0, 1, 0); PG8_SCHED; PG8_LDA(At, 1, 0); PG8_STAGE(PG8_SA(0, 1), a2 + hstepA, voffA);
;             PG8_WAIT_L(8); PG8_BAR; PG8_WAIT_L(0); PG8_MMA(0, 0, At, B0); PG8_BAR; PG8_SCHED;
;             PG8_LDB(B1, 1, 1); PG8_STAGE(PG8_SB(1, 0), b3, voffB);
;             PG8_BAR; PG8_WAIT_L(0); PG8_MMA(0, 1, At, B1); PG8_BAR;
;             PG8_LDA(At, 1, 1); PG8_STAGE(PG8_SA(1, 0), a3, voffA);
;             PG8_BAR; PG8_WAIT_L(0); PG8_MMA(1, 0, At, B0); PG8_BAR; PG8_SCHED;
	s_setprio 1
	v_mfma_f32_16x16x32_bf16 v[52:55], v[202:205], v[168:171], v[52:55]
	v_mfma_f32_16x16x32_bf16 v[48:51], v[210:213], v[168:171], v[48:51]
	v_mfma_f32_16x16x32_bf16 v[36:39], v[202:205], v[176:179], v[36:39]
	v_mfma_f32_16x16x32_bf16 v[32:35], v[210:213], v[176:179], v[32:35]
	v_mfma_f32_16x16x32_bf16 v[20:23], v[202:205], v[184:187], v[20:23]
	v_mfma_f32_16x16x32_bf16 v[16:19], v[210:213], v[184:187], v[16:19]
	v_mfma_f32_16x16x32_bf16 v[4:7], v[202:205], v[192:195], v[4:7]
	v_mfma_f32_16x16x32_bf16 v[0:3], v[210:213], v[192:195], v[0:3]
	v_mfma_f32_16x16x32_bf16 v[52:55], v[206:209], v[172:175], v[52:55]
	v_mfma_f32_16x16x32_bf16 v[48:51], v[214:217], v[172:175], v[48:51]
	v_mfma_f32_16x16x32_bf16 v[36:39], v[206:209], v[180:183], v[36:39]
	v_mfma_f32_16x16x32_bf16 v[32:35], v[214:217], v[180:183], v[32:35]
	v_mfma_f32_16x16x32_bf16 v[20:23], v[206:209], v[188:191], v[20:23]
	v_mfma_f32_16x16x32_bf16 v[16:19], v[214:217], v[188:191], v[16:19]
	v_mfma_f32_16x16x32_bf16 v[4:7], v[206:209], v[196:199], v[4:7]
	v_mfma_f32_16x16x32_bf16 v[0:3], v[214:217], v[196:199], v[0:3]
	s_setprio 0
	v_add_u32_e32 v164, s83, v147
	s_barrier
	ds_read_b128 v[152:155], v164
	ds_read_b128 v[156:159], v164 offset:1024
	ds_read_b128 v[160:163], v164 offset:2048
	ds_read_b128 v[164:167], v164 offset:3072
	s_add_u32 s28, s36, 0x80000
	s_addc_u32 s29, s37, 0
	s_mov_b32 m0, s44
	ds_read_b128 v[168:171], v150 offset:32768
	ds_read_b128 v[172:175], v150 offset:33792
	ds_read_b128 v[176:179], v150 offset:34816
	ds_read_b128 v[180:183], v150 offset:35840
	ds_read_b128 v[184:187], v150 offset:36864
	ds_read_b128 v[188:191], v150 offset:37888
	ds_read_b128 v[192:195], v150 offset:38912
	ds_read_b128 v[196:199], v150 offset:39936
	global_load_lds_dwordx4 v128, s[28:29]
	s_mov_b32 m0, s45
	s_nop 0
	global_load_lds_dwordx4 v132, s[28:29]
	s_waitcnt lgkmcnt(8)
	s_barrier
	s_waitcnt lgkmcnt(0)
	s_setprio 1
	s_waitcnt lgkmcnt(0)
	v_mfma_f32_16x16x32_bf16 v[124:127], v[152:155], v[168:171], v[124:127]
	v_mfma_f32_16x16x32_bf16 v[120:123], v[160:163], v[168:171], v[120:123]
	v_mfma_f32_16x16x32_bf16 v[108:111], v[152:155], v[176:179], v[108:111]
	v_mfma_f32_16x16x32_bf16 v[104:107], v[160:163], v[176:179], v[104:107]
	v_mfma_f32_16x16x32_bf16 v[92:95], v[152:155], v[184:187], v[92:95]
	v_mfma_f32_16x16x32_bf16 v[88:91], v[160:163], v[184:187], v[88:91]
	v_mfma_f32_16x16x32_bf16 v[76:79], v[152:155], v[192:195], v[76:79]
	v_mfma_f32_16x16x32_bf16 v[72:75], v[160:163], v[192:195], v[72:75]
	v_mfma_f32_16x16x32_bf16 v[124:127], v[156:159], v[172:175], v[124:127]
	v_mfma_f32_16x16x32_bf16 v[120:123], v[164:167], v[172:175], v[120:123]
	v_mfma_f32_16x16x32_bf16 v[108:111], v[156:159], v[180:183], v[108:111]
	v_mfma_f32_16x16x32_bf16 v[104:107], v[164:167], v[180:183], v[104:107]
	v_mfma_f32_16x16x32_bf16 v[92:95], v[156:159], v[188:191], v[92:95]
	v_mfma_f32_16x16x32_bf16 v[88:91], v[164:167], v[188:191], v[88:91]
	v_mfma_f32_16x16x32_bf16 v[76:79], v[156:159], v[196:199], v[76:79]
	v_mfma_f32_16x16x32_bf16 v[72:75], v[164:167], v[196:199], v[72:75]
	s_setprio 0
	s_barrier
	s_add_i32 s28, s83, s42
	v_add_u32_e32 v214, s84, v147
	s_mov_b32 m0, s28
	ds_read_b128 v[202:205], v214
	ds_read_b128 v[206:209], v214 offset:1024
	ds_read_b128 v[210:213], v214 offset:2048
	ds_read_b128 v[214:217], v214 offset:3072
	global_load_lds_dwordx4 v130, s[98:99]
	s_add_i32 m0, s28, 0x2000
	s_nop 0
	global_load_lds_dwordx4 v134, s[98:99]
	s_barrier
	s_waitcnt lgkmcnt(0)
	s_setprio 1
	s_waitcnt lgkmcnt(0)
	v_mfma_f32_16x16x32_bf16 v[116:119], v[202:205], v[168:171], v[116:119]
	v_mfma_f32_16x16x32_bf16 v[112:115], v[210:213], v[168:171], v[112:115]
	v_mfma_f32_16x16x32_bf16 v[100:103], v[202:205], v[176:179], v[100:103]
	v_mfma_f32_16x16x32_bf16 v[96:99], v[210:213], v[176:179], v[96:99]
	v_mfma_f32_16x16x32_bf16 v[84:87], v[202:205], v[184:187], v[84:87]
	v_mfma_f32_16x16x32_bf16 v[80:83], v[210:213], v[184:187], v[80:83]
	v_mfma_f32_16x16x32_bf16 v[68:71], v[202:205], v[192:195], v[68:71]
	v_mfma_f32_16x16x32_bf16 v[64:67], v[210:213], v[192:195], v[64:67]
	v_mfma_f32_16x16x32_bf16 v[116:119], v[206:209], v[172:175], v[116:119]
	v_mfma_f32_16x16x32_bf16 v[112:115], v[214:217], v[172:175], v[112:115]
	v_mfma_f32_16x16x32_bf16 v[100:103], v[206:209], v[180:183], v[100:103]
	v_mfma_f32_16x16x32_bf16 v[96:99], v[214:217], v[180:183], v[96:99]
	v_mfma_f32_16x16x32_bf16 v[84:87], v[206:209], v[188:191], v[84:87]
	v_mfma_f32_16x16x32_bf16 v[80:83], v[214:217], v[188:191], v[80:83]
	v_mfma_f32_16x16x32_bf16 v[68:71], v[206:209], v[196:199], v[68:71]
	v_mfma_f32_16x16x32_bf16 v[64:67], v[214:217], v[196:199], v[64:67]
	s_setprio 0
	s_mov_b32 m0, s47
	s_barrier
	ds_read_b128 v[168:171], v150 offset:49152
	ds_read_b128 v[172:175], v150 offset:50176
	ds_read_b128 v[176:179], v150 offset:51200
	ds_read_b128 v[180:183], v150 offset:52224
	ds_read_b128 v[184:187], v150 offset:53248
	ds_read_b128 v[188:191], v150 offset:54272
	ds_read_b128 v[192:195], v150 offset:55296
	ds_read_b128 v[196:199], v150 offset:56320
	global_load_lds_dwordx4 v128, s[100:101]
	s_mov_b32 m0, s48
	s_nop 0
	global_load_lds_dwordx4 v132, s[100:101]
	s_barrier
; __device__ __forceinline__ unsigned cvt_pk_bf16(float lo, float hi) { const bf16x2_t r = __builtin_convertvector((f32x2){lo, hi}, bf16x2_t); return __builtin_bit_cast(unsigned, r); }
; #define PG8_STAGE(bufoff, gbase, voff) do { _Pragma("unroll") for (int _i = 0; _i < 2; ++_i) \
;         __builtin_amdgcn_global_load_lds((const unsigned*)((const char*)(gbase) + (voff)[_i]), (LAS unsigned*)(lds + (bufoff) + ldsw + _i * 8192), 16, 0, 0); } while (0)
; #define PG8_WAIT_V(n) asm volatile("s_waitcnt vmcnt(" #n ")" ::: "memory")
; #define PG8_BAR __builtin_amdgcn_s_barrier()
; template <class Epi>
; __device__ __forceinline__ void gemm_phase(LAS unsigned char* lds, const bf16_t* A, int lda, const bf16_t* Bt, int ldb, int M, int N, int K, int asel, const Epi& E, const int fixed_round = -1) {
;     ...
;             PG8_WAIT_V(6); PG8_BAR; PG8_MMA(1, 1, At, B1); PG8_BAR;
;             PG8_LDB(B0, 1, 0); PG8_SCHED; PG8_LDA(At, 1, 0); PG8_STAGE(PG8_SA(0, 1), a2 + hstepA, voffA);
;             PG8_WAIT_L(8); PG8_BAR; PG8_WAIT_L(0); PG8_MMA(0, 0, At, B0); PG8_BAR; PG8_SCHED;
;             PG8_LDB(B1, 1, 1); PG8_STAGE(PG8_SB(1, 0), b3, voffB);
;             PG8_BAR; PG8_WAIT_L(0); PG8_MMA(0, 1, At, B1); PG8_BAR;
;             PG8_LDA(At, 1, 1); PG8_STAGE(PG8_SA(1, 0), a3, voffA);
;             PG8_BAR; PG8_WAIT_L(0); PG8_MMA(1, 0, At, B0); PG8_BAR; PG8_SCHED;
;             PG8_STAGE(PG8_SB(1, 1), b3 + hstepB, voffB);
;             PG8_WAIT_V(6); PG8_BAR; PG8_MMA(1, 1, At, B1); PG8_BAR;
;     __device__ __forceinline__ void operator()(const AccT& acc, const Unit& u, int wr, int wc, int fr, int fq) const {
;         const int row0 = u.pm * BM + wr * 64 + fr, col0 = u.pn * BM + wc * 32 + 8 * fq;
; #pragma unroll
;         for (int ai = 0; ai < 2; ++ai)
; #pragma unroll
;             for (int m = 0; m < 4; ++m) { bf16_t* rowp = O + (size_t)(row0 + ai * HALF + m * 16) * DFF + col0;
; #pragma unroll
;                 for (int bj = 0; bj < 2; ++bj) { f32x4 v0 = acc[ai][bj][m][0], v1 = acc[ai][bj][m][1];
; #pragma unroll
;                     for (int j = 0; j < 4; ++j) { float a = fmaxf(v0[j], 0.f), b = fmaxf(v1[j], 0.f); v0[j] = a * a; v1[j] = b * b; }
;                     u32x4 w; w.x = cvt_pk_bf16(v0[0], v0[1]); w.y = cvt_pk_bf16(v0[2], v0[3]); w.z = cvt_pk_bf16(v1[0], v1[1]); w.w = cvt_pk_bf16(v1[2], v1[3]);
;                     *(u32x4*)(rowp + bj * HALF) = w; } }
	s_waitcnt lgkmcnt(0)
	s_setprio 1
	s_waitcnt lgkmcnt(0)
	v_mfma_f32_16x16x32_bf16 v[60:63], v[152:155], v[168:171], v[60:63]
	v_mfma_f32_16x16x32_bf16 v[56:59], v[160:163], v[168:171], v[56:59]
	v_mfma_f32_16x16x32_bf16 v[44:47], v[152:155], v[176:179], v[44:47]
	v_mfma_f32_16x16x32_bf16 v[40:43], v[160:163], v[176:179], v[40:43]
	v_mfma_f32_16x16x32_bf16 v[28:31], v[152:155], v[184:187], v[28:31]
	v_mfma_f32_16x16x32_bf16 v[24:27], v[160:163], v[184:187], v[24:27]
	v_mfma_f32_16x16x32_bf16 v[12:15], v[152:155], v[192:195], v[12:15]
	v_mfma_f32_16x16x32_bf16 v[8:11], v[160:163], v[192:195], v[8:11]
	v_mfma_f32_16x16x32_bf16 v[60:63], v[156:159], v[172:175], v[60:63]
	v_mfma_f32_16x16x32_bf16 v[56:59], v[164:167], v[172:175], v[56:59]
	v_mfma_f32_16x16x32_bf16 v[44:47], v[156:159], v[180:183], v[44:47]
	v_mfma_f32_16x16x32_bf16 v[40:43], v[164:167], v[180:183], v[40:43]
	v_mfma_f32_16x16x32_bf16 v[28:31], v[156:159], v[188:191], v[28:31]
	v_mfma_f32_16x16x32_bf16 v[24:27], v[164:167], v[188:191], v[24:27]
	v_mfma_f32_16x16x32_bf16 v[12:15], v[156:159], v[196:199], v[12:15]
	v_mfma_f32_16x16x32_bf16 v[8:11], v[164:167], v[196:199], v[8:11]
	s_setprio 0
	s_barrier
	s_add_u32 s28, s34, 0x80080
	s_addc_u32 s29, s35, 0
	s_add_i32 s34, s84, s42
	s_mov_b32 m0, s34
	s_nop 0
	global_load_lds_dwordx4 v130, s[28:29]
	s_add_i32 m0, s34, 0x2000
	s_nop 0
	global_load_lds_dwordx4 v134, s[28:29]
	s_waitcnt vmcnt(6)
	s_barrier
	s_setprio 1
	v_mfma_f32_16x16x32_bf16 v[52:55], v[202:205], v[168:171], v[52:55]
	v_mfma_f32_16x16x32_bf16 v[48:51], v[210:213], v[168:171], v[48:51]
	v_mfma_f32_16x16x32_bf16 v[36:39], v[202:205], v[176:179], v[36:39]
	v_mfma_f32_16x16x32_bf16 v[32:35], v[210:213], v[176:179], v[32:35]
	v_mfma_f32_16x16x32_bf16 v[20:23], v[202:205], v[184:187], v[20:23]
	v_mfma_f32_16x16x32_bf16 v[16:19], v[210:213], v[184:187], v[16:19]
	v_mfma_f32_16x16x32_bf16 v[4:7], v[202:205], v[192:195], v[4:7]
	v_mfma_f32_16x16x32_bf16 v[0:3], v[210:213], v[192:195], v[0:3]
	v_mfma_f32_16x16x32_bf16 v[52:55], v[206:209], v[172:175], v[52:55]
	v_mfma_f32_16x16x32_bf16 v[48:51], v[214:217], v[172:175], v[48:51]
	v_mfma_f32_16x16x32_bf16 v[36:39], v[206:209], v[180:183], v[36:39]
	v_mfma_f32_16x16x32_bf16 v[32:35], v[214:217], v[180:183], v[32:35]
	v_mfma_f32_16x16x32_bf16 v[20:23], v[206:209], v[188:191], v[20:23]
	v_mfma_f32_16x16x32_bf16 v[16:19], v[214:217], v[188:191], v[16:19]
	v_mfma_f32_16x16x32_bf16 v[4:7], v[206:209], v[196:199], v[4:7]
	v_mfma_f32_16x16x32_bf16 v[0:3], v[214:217], v[196:199], v[0:3]
	s_setprio 0
	s_add_i32 s56, s56, 2
	s_add_u32 s30, s30, 0x100
	s_addc_u32 s31, s31, 0
	s_add_u32 s54, s54, 0x100
	s_addc_u32 s55, s55, 0
	s_cmp_gt_u32 s56, 29
	s_cbranch_scc0 .Lrot_4
	s_barrier
	v_lshl_add_u32 v152, s26, 8, v146
	v_lshl_or_b32 v144, s51, 8, v148
	v_ashrrev_i32_e32 v153, 31, v152
	v_ashrrev_i32_e32 v145, 31, v144
	v_lshlrev_b64 v[154:155], 14, v[152:153]
	v_lshl_add_u64 v[154:155], s[88:89], 0, v[154:155]
	v_lshlrev_b64 v[156:157], 1, v[144:145]
	v_max_f32_e32 v120, 0, v120
	v_max_f32_e32 v121, 0, v121
	v_lshl_add_u64 v[144:145], v[154:155], 0, v[156:157]
	v_pk_mul_f32 v[154:155], v[120:121], v[120:121]
	v_max_f32_e32 v121, v122, v122
	v_max_f32_e32 v120, v126, v126
	v_max_f32_e32 v122, 0, v121
	v_max_f32_e32 v121, v127, v127
	v_max_f32_e32 v124, 0, v124
	v_max_f32_e32 v125, 0, v125
	v_max_f32_e32 v120, 0, v120
	v_max_f32_e32 v121, 0, v121
	v_max_f32_e32 v123, 0, v123
	v_pk_mul_f32 v[124:125], v[124:125], v[124:125]
	v_pk_mul_f32 v[126:127], v[120:121], v[120:121]
	v_pk_mul_f32 v[158:159], v[122:123], v[122:123]
	v_cvt_pk_bf16_f32 v120, v124, v125
	v_cvt_pk_bf16_f32 v121, v126, v127
	v_cvt_pk_bf16_f32 v122, v154, v155
	v_cvt_pk_bf16_f32 v123, v158, v159
	v_max_f32_e32 v112, 0, v112
	v_max_f32_e32 v113, 0, v113
	global_store_dwordx4 v[144:145], v[120:123], off
	s_nop 1
	v_pk_mul_f32 v[120:121], v[112:113], v[112:113]
	v_max_f32_e32 v113, v114, v114
	v_max_f32_e32 v112, v118, v118
	v_max_f32_e32 v114, 0, v113
	v_max_f32_e32 v113, v119, v119
	v_max_f32_e32 v116, 0, v116
	v_max_f32_e32 v117, 0, v117
	v_max_f32_e32 v112, 0, v112
	v_max_f32_e32 v113, 0, v113
	v_max_f32_e32 v115, 0, v115
	v_pk_mul_f32 v[116:117], v[116:117], v[116:117]
	v_pk_mul_f32 v[118:119], v[112:113], v[112:113]
	v_pk_mul_f32 v[122:123], v[114:115], v[114:115]
	v_cvt_pk_bf16_f32 v112, v116, v117
	v_cvt_pk_bf16_f32 v113, v118, v119
	v_cvt_pk_bf16_f32 v114, v120, v121
	v_cvt_pk_bf16_f32 v115, v122, v123
	v_max_f32_e32 v104, 0, v104
	v_max_f32_e32 v105, 0, v105
	global_store_dwordx4 v[144:145], v[112:115], off offset:256
	s_nop 1
	v_or_b32_e32 v112, 16, v152
	v_pk_mul_f32 v[114:115], v[104:105], v[104:105]
	v_max_f32_e32 v105, v106, v106
	v_ashrrev_i32_e32 v113, 31, v112
	v_max_f32_e32 v104, v110, v110
	v_max_f32_e32 v106, 0, v105
	v_max_f32_e32 v105, v111, v111
	v_lshlrev_b64 v[112:113], 14, v[112:113]
	v_max_f32_e32 v108, 0, v108
	v_max_f32_e32 v109, 0, v109
	v_max_f32_e32 v104, 0, v104
	v_max_f32_e32 v105, 0, v105
	v_max_f32_e32 v107, 0, v107
	v_lshl_add_u64 v[112:113], s[88:89], 0, v[112:113]
	v_pk_mul_f32 v[108:109], v[108:109], v[108:109]
	v_pk_mul_f32 v[110:111], v[104:105], v[104:105]
	v_pk_mul_f32 v[116:117], v[106:107], v[106:107]
	v_lshl_add_u64 v[112:113], v[112:113], 0, v[156:157]
	v_cvt_pk_bf16_f32 v104, v108, v109
	v_cvt_pk_bf16_f32 v105, v110, v111
	v_cvt_pk_bf16_f32 v106, v114, v115
	v_cvt_pk_bf16_f32 v107, v116, v117
	v_max_f32_e32 v96, 0, v96
	v_max_f32_e32 v97, 0, v97
	global_store_dwordx4 v[112:113], v[104:107], off
	s_nop 1
	v_pk_mul_f32 v[104:105], v[96:97], v[96:97]
	v_max_f32_e32 v97, v98, v98
	v_max_f32_e32 v96, v102, v102
	v_max_f32_e32 v98, 0, v97
; __device__ __forceinline__ unsigned cvt_pk_bf16(float lo, float hi) { const bf16x2_t r = __builtin_convertvector((f32x2){lo, hi}, bf16x2_t); return __builtin_bit_cast(unsigned, r); }
;     __device__ __forceinline__ void operator()(const AccT& acc, const Unit& u, int wr, int wc, int fr, int fq) const {
;         const int row0 = u.pm * BM + wr * 64 + fr, col0 = u.pn * BM + wc * 32 + 8 * fq;
; #pragma unroll
;         for (int ai = 0; ai < 2; ++ai)
; #pragma unroll
;             for (int m = 0; m < 4; ++m) { bf16_t* rowp = O + (size_t)(row0 + ai * HALF + m * 16) * DFF + col0;
; #pragma unroll
;                 for (int bj = 0; bj < 2; ++bj) { f32x4 v0 = acc[ai][bj][m][0], v1 = acc[ai][bj][m][1];
; #pragma unroll
;                     for (int j = 0; j < 4; ++j) { float a = fmaxf(v0[j], 0.f), b = fmaxf(v1[j], 0.f); v0[j] = a * a; v1[j] = b * b; }
;                     u32x4 w; w.x = cvt_pk_bf16(v0[0], v0[1]); w.y = cvt_pk_bf16(v0[2], v0[3]); w.z = cvt_pk_bf16(v1[0], v1[1]); w.w = cvt_pk_bf16(v1[2], v1[3]);
;                     *(u32x4*)(rowp + bj * HALF) = w; } }
	v_max_f32_e32 v97, v103, v103
	v_max_f32_e32 v100, 0, v100
	v_max_f32_e32 v101, 0, v101
	v_max_f32_e32 v96, 0, v96
	v_max_f32_e32 v97, 0, v97
	v_max_f32_e32 v99, 0, v99
	v_pk_mul_f32 v[100:101], v[100:101], v[100:101]
	v_pk_mul_f32 v[102:103], v[96:97], v[96:97]
	v_pk_mul_f32 v[106:107], v[98:99], v[98:99]
	v_cvt_pk_bf16_f32 v96, v100, v101
	v_cvt_pk_bf16_f32 v97, v102, v103
	v_cvt_pk_bf16_f32 v98, v104, v105
	v_cvt_pk_bf16_f32 v99, v106, v107
	v_max_f32_e32 v88, 0, v88
	v_max_f32_e32 v89, 0, v89
	global_store_dwordx4 v[112:113], v[96:99], off offset:256
	s_nop 1
	v_or_b32_e32 v96, 32, v152
	v_pk_mul_f32 v[98:99], v[88:89], v[88:89]
	v_max_f32_e32 v89, v90, v90
	v_ashrrev_i32_e32 v97, 31, v96
	v_max_f32_e32 v88, v94, v94
	v_max_f32_e32 v90, 0, v89
	v_max_f32_e32 v89, v95, v95
	v_lshlrev_b64 v[96:97], 14, v[96:97]
	v_max_f32_e32 v92, 0, v92
	v_max_f32_e32 v93, 0, v93
	v_max_f32_e32 v88, 0, v88
	v_max_f32_e32 v89, 0, v89
	v_max_f32_e32 v91, 0, v91
	v_lshl_add_u64 v[96:97], s[88:89], 0, v[96:97]
	v_pk_mul_f32 v[92:93], v[92:93], v[92:93]
	v_pk_mul_f32 v[94:95], v[88:89], v[88:89]
	v_pk_mul_f32 v[100:101], v[90:91], v[90:91]
	v_lshl_add_u64 v[96:97], v[96:97], 0, v[156:157]
	v_cvt_pk_bf16_f32 v88, v92, v93
	v_cvt_pk_bf16_f32 v89, v94, v95
	v_cvt_pk_bf16_f32 v90, v98, v99
	v_cvt_pk_bf16_f32 v91, v100, v101
	v_max_f32_e32 v80, 0, v80
	v_max_f32_e32 v81, 0, v81
	global_store_dwordx4 v[96:97], v[88:91], off
	s_nop 1
	v_pk_mul_f32 v[88:89], v[80:81], v[80:81]
	v_max_f32_e32 v81, v82, v82
	v_max_f32_e32 v80, v86, v86
	v_max_f32_e32 v82, 0, v81
	v_max_f32_e32 v81, v87, v87
	v_max_f32_e32 v84, 0, v84
	v_max_f32_e32 v85, 0, v85
	v_max_f32_e32 v80, 0, v80
	v_max_f32_e32 v81, 0, v81
	v_max_f32_e32 v83, 0, v83
	v_pk_mul_f32 v[84:85], v[84:85], v[84:85]
	v_pk_mul_f32 v[86:87], v[80:81], v[80:81]
	v_pk_mul_f32 v[90:91], v[82:83], v[82:83]
	v_cvt_pk_bf16_f32 v80, v84, v85
	v_cvt_pk_bf16_f32 v81, v86, v87
	v_cvt_pk_bf16_f32 v82, v88, v89
	v_cvt_pk_bf16_f32 v83, v90, v91
	v_max_f32_e32 v72, 0, v72
	v_max_f32_e32 v73, 0, v73
	global_store_dwordx4 v[96:97], v[80:83], off offset:256
	s_nop 1
	v_or_b32_e32 v80, 48, v152
	v_pk_mul_f32 v[82:83], v[72:73], v[72:73]
	v_max_f32_e32 v73, v74, v74
	v_ashrrev_i32_e32 v81, 31, v80
	v_max_f32_e32 v72, v78, v78
	v_max_f32_e32 v74, 0, v73
	v_max_f32_e32 v73, v79, v79
	v_lshlrev_b64 v[80:81], 14, v[80:81]
	v_max_f32_e32 v76, 0, v76
	v_max_f32_e32 v77, 0, v77
	v_max_f32_e32 v72, 0, v72
	v_max_f32_e32 v73, 0, v73
	v_max_f32_e32 v75, 0, v75
	v_lshl_add_u64 v[80:81], s[88:89], 0, v[80:81]
	v_pk_mul_f32 v[76:77], v[76:77], v[76:77]
	v_pk_mul_f32 v[78:79], v[72:73], v[72:73]
	v_pk_mul_f32 v[84:85], v[74:75], v[74:75]
	v_lshl_add_u64 v[80:81], v[80:81], 0, v[156:157]
	v_cvt_pk_bf16_f32 v72, v76, v77
	v_cvt_pk_bf16_f32 v73, v78, v79
	v_cvt_pk_bf16_f32 v74, v82, v83
	v_cvt_pk_bf16_f32 v75, v84, v85
	v_max_f32_e32 v64, 0, v64
	v_max_f32_e32 v65, 0, v65
	global_store_dwordx4 v[80:81], v[72:75], off
	s_nop 1
	v_pk_mul_f32 v[72:73], v[64:65], v[64:65]
	v_max_f32_e32 v65, v66, v66
	v_max_f32_e32 v64, v70, v70
	v_max_f32_e32 v66, 0, v65
	v_max_f32_e32 v65, v71, v71
	v_max_f32_e32 v68, 0, v68
	v_max_f32_e32 v69, 0, v69
	v_max_f32_e32 v64, 0, v64
	v_max_f32_e32 v65, 0, v65
	v_max_f32_e32 v67, 0, v67
	v_pk_mul_f32 v[68:69], v[68:69], v[68:69]
	v_pk_mul_f32 v[70:71], v[64:65], v[64:65]
	v_pk_mul_f32 v[74:75], v[66:67], v[66:67]
	v_cvt_pk_bf16_f32 v64, v68, v69
	v_cvt_pk_bf16_f32 v65, v70, v71
	v_cvt_pk_bf16_f32 v66, v72, v73
	v_cvt_pk_bf16_f32 v67, v74, v75
	v_max_f32_e32 v56, 0, v56
	v_max_f32_e32 v57, 0, v57
	global_store_dwordx4 v[80:81], v[64:67], off offset:256
	s_nop 1
	v_pk_mul_f32 v[66:67], v[56:57], v[56:57]
	v_max_f32_e32 v57, v58, v58
	v_max_f32_e32 v60, 0, v60
	v_max_f32_e32 v61, 0, v61
	v_max_f32_e32 v56, v62, v62
	v_max_f32_e32 v58, 0, v57
	v_max_f32_e32 v57, v63, v63
	v_pk_mul_f32 v[60:61], v[60:61], v[60:61]
	v_max_f32_e32 v56, 0, v56
	v_max_f32_e32 v57, 0, v57
	v_max_f32_e32 v59, 0, v59
	s_mov_b32 s5, 0x200000
	v_pk_mul_f32 v[62:63], v[56:57], v[56:57]
	v_pk_mul_f32 v[68:69], v[58:59], v[58:59]
	v_cvt_pk_bf16_f32 v56, v60, v61
	v_add_co_u32_e32 v60, vcc, s5, v144
	v_cvt_pk_bf16_f32 v57, v62, v63
	v_cvt_pk_bf16_f32 v58, v66, v67
	v_cvt_pk_bf16_f32 v59, v68, v69
	v_addc_co_u32_e32 v61, vcc, 0, v145, vcc
	v_max_f32_e32 v48, 0, v48
	v_max_f32_e32 v49, 0, v49
	global_store_dwordx4 v[60:61], v[56:59], off
	s_nop 1
	v_pk_mul_f32 v[56:57], v[48:49], v[48:49]
	v_max_f32_e32 v49, v50, v50
	v_max_f32_e32 v48, v54, v54
	v_max_f32_e32 v50, 0, v49
	v_max_f32_e32 v49, v55, v55
	v_max_f32_e32 v52, 0, v52
	v_max_f32_e32 v53, 0, v53
	v_max_f32_e32 v48, 0, v48
	v_max_f32_e32 v49, 0, v49
	v_max_f32_e32 v51, 0, v51
	s_mov_b64 s[28:29], 0x200000
	v_pk_mul_f32 v[52:53], v[52:53], v[52:53]
	v_pk_mul_f32 v[54:55], v[48:49], v[48:49]
	v_pk_mul_f32 v[58:59], v[50:51], v[50:51]
	v_lshl_add_u64 v[64:65], v[144:145], 0, s[28:29]
; __device__ __forceinline__ unsigned cvt_pk_bf16(float lo, float hi) { const bf16x2_t r = __builtin_convertvector((f32x2){lo, hi}, bf16x2_t); return __builtin_bit_cast(unsigned, r); }
; #define PG8_WAIT_V(n) asm volatile("s_waitcnt vmcnt(" #n ")" ::: "memory")
; #define PG8_BAR __builtin_amdgcn_s_barrier()
; template <class Epi>
; __device__ __forceinline__ void gemm_phase(LAS unsigned char* lds, const bf16_t* A, int lda, const bf16_t* Bt, int ldb, int M, int N, int K, int asel, const Epi& E, const int fixed_round = -1) {
;     ...
;         if (!has_next) break;
; #pragma unroll
;         for (int a = 0; a < 2; ++a)
; #pragma unroll
;             for (int b = 0; b < 2; ++b)
; #pragma unroll
;                 for (int m = 0; m < 4; ++m)
; #pragma unroll
;                     for (int n = 0; n < 2; ++n) acc[a][b][m][n] = (f32x4){0.f, 0.f, 0.f, 0.f};
;         cur = nxt; cA = nA; cB = nB; ++ui;
;     }
;     PG8_WAIT_V(0);
;     if (wr == 0) PG8_BAR;
;     PG8_BAR;
;     __device__ __forceinline__ void operator()(const AccT& acc, const Unit& u, int wr, int wc, int fr, int fq) const {
;     ...
;             for (int m = 0; m < 4; ++m) { bf16_t* rowp = O + (size_t)(row0 + ai * HALF + m * 16) * DFF + col0;
; #pragma unroll
;                 for (int bj = 0; bj < 2; ++bj) { f32x4 v0 = acc[ai][bj][m][0], v1 = acc[ai][bj][m][1];
; #pragma unroll
;                     for (int j = 0; j < 4; ++j) { float a = fmaxf(v0[j], 0.f), b = fmaxf(v1[j], 0.f); v0[j] = a * a; v1[j] = b * b; }
;                     u32x4 w; w.x = cvt_pk_bf16(v0[0], v0[1]); w.y = cvt_pk_bf16(v0[2], v0[3]); w.z = cvt_pk_bf16(v1[0], v1[1]); w.w = cvt_pk_bf16(v1[2], v1[3]);
;                     *(u32x4*)(rowp + bj * HALF) = w; } }
	v_cvt_pk_bf16_f32 v48, v52, v53
	v_cvt_pk_bf16_f32 v49, v54, v55
	v_cvt_pk_bf16_f32 v50, v56, v57
	v_cvt_pk_bf16_f32 v51, v58, v59
	v_max_f32_e32 v40, 0, v40
	v_max_f32_e32 v41, 0, v41
	global_store_dwordx4 v[64:65], v[48:51], off offset:256
	s_nop 1
	v_pk_mul_f32 v[50:51], v[40:41], v[40:41]
	v_max_f32_e32 v41, v42, v42
	v_max_f32_e32 v44, 0, v44
	v_max_f32_e32 v45, 0, v45
	v_max_f32_e32 v40, v46, v46
	v_max_f32_e32 v42, 0, v41
	v_max_f32_e32 v41, v47, v47
	v_pk_mul_f32 v[44:45], v[44:45], v[44:45]
	v_max_f32_e32 v40, 0, v40
	v_max_f32_e32 v41, 0, v41
	v_max_f32_e32 v43, 0, v43
	s_mov_b32 s5, 0x240000
	v_pk_mul_f32 v[46:47], v[40:41], v[40:41]
	v_pk_mul_f32 v[52:53], v[42:43], v[42:43]
	v_cvt_pk_bf16_f32 v40, v44, v45
	v_add_co_u32_e32 v44, vcc, s5, v144
	v_cvt_pk_bf16_f32 v41, v46, v47
	v_cvt_pk_bf16_f32 v42, v50, v51
	v_cvt_pk_bf16_f32 v43, v52, v53
	v_addc_co_u32_e32 v45, vcc, 0, v145, vcc
	v_max_f32_e32 v32, 0, v32
	v_max_f32_e32 v33, 0, v33
	global_store_dwordx4 v[44:45], v[40:43], off
	s_nop 1
	v_pk_mul_f32 v[40:41], v[32:33], v[32:33]
	v_max_f32_e32 v33, v34, v34
	v_max_f32_e32 v32, v38, v38
	v_max_f32_e32 v34, 0, v33
	v_max_f32_e32 v33, v39, v39
	v_max_f32_e32 v36, 0, v36
	v_max_f32_e32 v37, 0, v37
	v_max_f32_e32 v32, 0, v32
	v_max_f32_e32 v33, 0, v33
	v_max_f32_e32 v35, 0, v35
	s_mov_b64 s[28:29], 0x240000
	v_pk_mul_f32 v[36:37], v[36:37], v[36:37]
	v_pk_mul_f32 v[38:39], v[32:33], v[32:33]
	v_pk_mul_f32 v[42:43], v[34:35], v[34:35]
	v_lshl_add_u64 v[48:49], v[144:145], 0, s[28:29]
	v_cvt_pk_bf16_f32 v32, v36, v37
	v_cvt_pk_bf16_f32 v33, v38, v39
	v_cvt_pk_bf16_f32 v34, v40, v41
	v_cvt_pk_bf16_f32 v35, v42, v43
	v_max_f32_e32 v24, 0, v24
	v_max_f32_e32 v25, 0, v25
	global_store_dwordx4 v[48:49], v[32:35], off offset:256
	s_nop 1
	v_pk_mul_f32 v[34:35], v[24:25], v[24:25]
	v_max_f32_e32 v25, v26, v26
	v_max_f32_e32 v28, 0, v28
	v_max_f32_e32 v29, 0, v29
	v_max_f32_e32 v24, v30, v30
	v_max_f32_e32 v26, 0, v25
	v_max_f32_e32 v25, v31, v31
	v_pk_mul_f32 v[28:29], v[28:29], v[28:29]
	v_max_f32_e32 v24, 0, v24
	v_max_f32_e32 v25, 0, v25
	v_max_f32_e32 v27, 0, v27
	s_mov_b32 s5, 0x280000
	v_pk_mul_f32 v[30:31], v[24:25], v[24:25]
	v_pk_mul_f32 v[36:37], v[26:27], v[26:27]
	v_cvt_pk_bf16_f32 v24, v28, v29
	v_add_co_u32_e32 v28, vcc, s5, v144
	v_cvt_pk_bf16_f32 v25, v30, v31
	v_cvt_pk_bf16_f32 v26, v34, v35
	v_cvt_pk_bf16_f32 v27, v36, v37
	v_addc_co_u32_e32 v29, vcc, 0, v145, vcc
	v_max_f32_e32 v16, 0, v16
	v_max_f32_e32 v17, 0, v17
	global_store_dwordx4 v[28:29], v[24:27], off
	s_nop 1
	v_pk_mul_f32 v[24:25], v[16:17], v[16:17]
	v_max_f32_e32 v17, v18, v18
	v_max_f32_e32 v16, v22, v22
	v_max_f32_e32 v18, 0, v17
	v_max_f32_e32 v17, v23, v23
	v_max_f32_e32 v20, 0, v20
	v_max_f32_e32 v21, 0, v21
	v_max_f32_e32 v16, 0, v16
	v_max_f32_e32 v17, 0, v17
	v_max_f32_e32 v19, 0, v19
	s_mov_b64 s[28:29], 0x280000
	v_pk_mul_f32 v[20:21], v[20:21], v[20:21]
	v_pk_mul_f32 v[22:23], v[16:17], v[16:17]
	v_pk_mul_f32 v[26:27], v[18:19], v[18:19]
	v_lshl_add_u64 v[32:33], v[144:145], 0, s[28:29]
	v_cvt_pk_bf16_f32 v16, v20, v21
	v_cvt_pk_bf16_f32 v17, v22, v23
	v_cvt_pk_bf16_f32 v18, v24, v25
	v_cvt_pk_bf16_f32 v19, v26, v27
	v_max_f32_e32 v8, 0, v8
	v_max_f32_e32 v9, 0, v9
	global_store_dwordx4 v[32:33], v[16:19], off offset:256
	s_nop 1
	v_pk_mul_f32 v[18:19], v[8:9], v[8:9]
	v_max_f32_e32 v9, v10, v10
	v_max_f32_e32 v12, 0, v12
	v_max_f32_e32 v13, 0, v13
	v_max_f32_e32 v8, v14, v14
	v_max_f32_e32 v10, 0, v9
	v_max_f32_e32 v9, v15, v15
	v_pk_mul_f32 v[12:13], v[12:13], v[12:13]
	v_max_f32_e32 v8, 0, v8
	v_max_f32_e32 v9, 0, v9
	v_max_f32_e32 v11, 0, v11
	v_pk_mul_f32 v[14:15], v[8:9], v[8:9]
	v_pk_mul_f32 v[20:21], v[10:11], v[10:11]
	v_cvt_pk_bf16_f32 v8, v12, v13
	v_add_co_u32_e32 v12, vcc, s50, v144
	v_cvt_pk_bf16_f32 v9, v14, v15
	v_cvt_pk_bf16_f32 v10, v18, v19
	v_cvt_pk_bf16_f32 v11, v20, v21
	v_addc_co_u32_e32 v13, vcc, 0, v145, vcc
	v_max_f32_e32 v0, 0, v0
	v_max_f32_e32 v1, 0, v1
	global_store_dwordx4 v[12:13], v[8:11], off
	s_nop 1
	v_pk_mul_f32 v[8:9], v[0:1], v[0:1]
	v_max_f32_e32 v1, v2, v2
	v_max_f32_e32 v0, v6, v6
	v_max_f32_e32 v2, 0, v1
	v_max_f32_e32 v1, v7, v7
	v_max_f32_e32 v4, 0, v4
	v_max_f32_e32 v5, 0, v5
	v_max_f32_e32 v0, 0, v0
	v_max_f32_e32 v1, 0, v1
	v_max_f32_e32 v3, 0, v3
	s_mov_b64 s[28:29], 0x2c0000
	v_pk_mul_f32 v[4:5], v[4:5], v[4:5]
	v_pk_mul_f32 v[6:7], v[0:1], v[0:1]
	v_pk_mul_f32 v[10:11], v[2:3], v[2:3]
	v_lshl_add_u64 v[16:17], v[144:145], 0, s[28:29]
	v_cvt_pk_bf16_f32 v0, v4, v5
	v_cvt_pk_bf16_f32 v1, v6, v7
	v_cvt_pk_bf16_f32 v2, v8, v9
	v_cvt_pk_bf16_f32 v3, v10, v11
	s_and_b64 vcc, exec, s[0:1]
	s_mov_b32 s51, s4
	s_mov_b32 s26, s6
	s_mov_b64 s[34:35], s[20:21]
	s_mov_b64 s[30:31], s[18:19]
	global_store_dwordx4 v[16:17], v[0:3], off offset:256
	s_cbranch_vccz .LBB0_584
	s_waitcnt vmcnt(0)
	s_cmpk_gt_u32 s33, 0xff
	s_cbranch_scc1 .LBB0_595
	s_barrier

; #define PG8_STAGE(bufoff, gbase, voff) do { _Pragma("unroll") for (int _i = 0; _i < 2; ++_i) \
;         __builtin_amdgcn_global_load_lds((const unsigned*)((const char*)(gbase) + (voff)[_i]), (LAS unsigned*)(lds + (bufoff) + ldsw + _i * 8192), 16, 0, 0); } while (0)
; #define PG8_LDA(dst, b, h) do { _Pragma("unroll") for (int m = 0; m < 4; ++m) _Pragma("unroll") for (int k = 0; k < 2; ++k) dst[m][k] = *(const LAS bf16x8*)(lds + PG8_SA(b, h) + aoff + m * 2048 + k * 1024); } while (0)
; #define PG8_LDB(dst, b, h) do { _Pragma("unroll") for (int n = 0; n < 2; ++n) _Pragma("unroll") for (int k = 0; k < 2; ++k) dst[n][k] = *(const LAS bf16x8*)(lds + PG8_SB(b, h) + boff + n * 2048 + k * 1024); } while (0)
; #define PG8_WAIT_V(n) asm volatile("s_waitcnt vmcnt(" #n ")" ::: "memory")
; #define PG8_WAIT_L(n) asm volatile("s_waitcnt lgkmcnt(" #n ")" ::: "memory")
; #define PG8_BAR __builtin_amdgcn_s_barrier()
; #define PG8_SCHED __builtin_amdgcn_sched_barrier(0)
; template <class Epi>
; __device__ __forceinline__ void gemm_phase(LAS unsigned char* lds, const bf16_t* A, int lda, const bf16_t* Bt, int ldb, int M, int N, int K, int asel, const Epi& E, const int fixed_round = -1) {
;     ...
;         const char* nA = has_next ? PG8_ABASE(nxt) : cA; const char* nB = has_next ? (const char*)Bt + (size_t)nxt.pn * tstepB : cB;
;         for (int t = 0; t < nt; t += 2) {
;             const bool last = (t == nt - 2);
;             const char* a1 = cA + (size_t)(t + 1) * kstep;
;             const char* a2 = last ? nA : cA + (size_t)(t + 2) * kstep; const char* b2 = last ? nB : cB + (size_t)(t + 2) * kstep;
;             const char* a3 = a2 + kstep; const char* b3 = b2 + kstep;
;             PG8_LDB(B0, 0, 0); PG8_SCHED; PG8_LDA(At, 0, 0); PG8_STAGE(PG8_SA(1, 1), a1 + hstepA, voffA);
;             PG8_WAIT_L(8); PG8_BAR; PG8_WAIT_L(0); PG8_MMA(0, 0, At, B0); PG8_BAR; PG8_SCHED;
;             PG8_LDB(B1, 0, 1); PG8_STAGE(PG8_SB(0, 0), b2, voffB);
;             PG8_BAR; PG8_WAIT_L(0); PG8_MMA(0, 1, At, B1); PG8_BAR;
;             PG8_LDA(At, 0, 1); PG8_STAGE(PG8_SA(0, 0), a2, voffA);
;             PG8_BAR; PG8_WAIT_L(0); PG8_MMA(1, 0, At, B0); PG8_BAR; PG8_SCHED;
;             PG8_STAGE(PG8_SB(0, 1), b2 + hstepB, voffB);
;             PG8_WAIT_V(6); PG8_BAR; PG8_MMA(1, 1, At, B1); PG8_BAR;
.LBB0_799:
	ds_read_b128 v[146:149], v155
	ds_read_b128 v[158:161], v155 offset:1024
	ds_read_b128 v[162:165], v155 offset:2048
	ds_read_b128 v[166:169], v155 offset:3072
	s_add_i32 m0, s49, 0xc000
	ds_read_b128 v[170:173], v156
	ds_read_b128 v[174:177], v156 offset:1024
	ds_read_b128 v[178:181], v156 offset:2048
	ds_read_b128 v[182:185], v156 offset:3072
	ds_read_b128 v[186:189], v156 offset:4096
	ds_read_b128 v[190:193], v156 offset:5120
	ds_read_b128 v[194:197], v156 offset:6144
	ds_read_b128 v[202:205], v156 offset:7168
	global_load_lds_dwordx4 v138, s[50:51]
	s_add_i32 m0, s49, 0xe000
	s_nop 0
	global_load_lds_dwordx4 v140, s[50:51]
	s_waitcnt lgkmcnt(8)
	s_barrier
	s_waitcnt lgkmcnt(0)
	s_setprio 1
	s_waitcnt lgkmcnt(0)
	v_mfma_f32_16x16x32_bf16 v[124:127], v[146:149], v[170:173], v[124:127]
	v_mfma_f32_16x16x32_bf16 v[120:123], v[162:165], v[170:173], v[120:123]
	v_mfma_f32_16x16x32_bf16 v[108:111], v[146:149], v[178:181], v[108:111]
	v_mfma_f32_16x16x32_bf16 v[104:107], v[162:165], v[178:181], v[104:107]
	v_mfma_f32_16x16x32_bf16 v[92:95], v[146:149], v[186:189], v[92:95]
	v_mfma_f32_16x16x32_bf16 v[88:91], v[162:165], v[186:189], v[88:91]
	v_mfma_f32_16x16x32_bf16 v[76:79], v[146:149], v[194:197], v[76:79]
	v_mfma_f32_16x16x32_bf16 v[72:75], v[162:165], v[194:197], v[72:75]
	v_mfma_f32_16x16x32_bf16 v[124:127], v[158:161], v[174:177], v[124:127]
	v_mfma_f32_16x16x32_bf16 v[120:123], v[166:169], v[174:177], v[120:123]
	v_mfma_f32_16x16x32_bf16 v[108:111], v[158:161], v[182:185], v[108:111]
	v_mfma_f32_16x16x32_bf16 v[104:107], v[166:169], v[182:185], v[104:107]
	v_mfma_f32_16x16x32_bf16 v[92:95], v[158:161], v[190:193], v[92:95]
	v_mfma_f32_16x16x32_bf16 v[88:91], v[166:169], v[190:193], v[88:91]
	v_mfma_f32_16x16x32_bf16 v[76:79], v[158:161], v[202:205], v[76:79]
	v_mfma_f32_16x16x32_bf16 v[72:75], v[166:169], v[202:205], v[72:75]
	s_setprio 0
	s_barrier
	s_add_u32 s28, s50, 0xfff80080
	s_addc_u32 s29, s51, -1
	s_cmp_eq_u32 s68, 28
	s_cselect_b32 s55, s5, s29
	s_cselect_b32 s54, s41, s28
	s_cselect_b32 s53, s7, s67
	s_cselect_b32 s52, s65, s66
	s_add_i32 s28, s81, s58
	s_add_u32 s98, s52, s2
	s_addc_u32 s99, s53, s3
	s_mov_b32 m0, s28
	ds_read_b128 v[206:209], v157
	ds_read_b128 v[210:213], v157 offset:1024
	ds_read_b128 v[214:217], v157 offset:2048
	ds_read_b128 v[218:221], v157 offset:3072
	global_load_lds_dwordx4 v130, s[52:53]
	s_add_i32 m0, s28, 0x2000
	s_nop 0
	global_load_lds_dwordx4 v134, s[52:53]
	s_barrier
	s_waitcnt lgkmcnt(0)
	s_setprio 1
	s_waitcnt lgkmcnt(0)
	v_mfma_f32_16x16x32_bf16 v[116:119], v[206:209], v[170:173], v[116:119]
	v_mfma_f32_16x16x32_bf16 v[112:115], v[214:217], v[170:173], v[112:115]
	v_mfma_f32_16x16x32_bf16 v[100:103], v[206:209], v[178:181], v[100:103]
	v_mfma_f32_16x16x32_bf16 v[96:99], v[214:217], v[178:181], v[96:99]
	v_mfma_f32_16x16x32_bf16 v[84:87], v[206:209], v[186:189], v[84:87]
	v_mfma_f32_16x16x32_bf16 v[80:83], v[214:217], v[186:189], v[80:83]
	v_mfma_f32_16x16x32_bf16 v[68:71], v[206:209], v[194:197], v[68:71]
	v_mfma_f32_16x16x32_bf16 v[64:67], v[214:217], v[194:197], v[64:67]
	v_mfma_f32_16x16x32_bf16 v[116:119], v[210:213], v[174:177], v[116:119]
	v_mfma_f32_16x16x32_bf16 v[112:115], v[218:221], v[174:177], v[112:115]
	v_mfma_f32_16x16x32_bf16 v[100:103], v[210:213], v[182:185], v[100:103]
	v_mfma_f32_16x16x32_bf16 v[96:99], v[218:221], v[182:185], v[96:99]
	v_mfma_f32_16x16x32_bf16 v[84:87], v[210:213], v[190:193], v[84:87]
	v_mfma_f32_16x16x32_bf16 v[80:83], v[218:221], v[190:193], v[80:83]
	v_mfma_f32_16x16x32_bf16 v[68:71], v[210:213], v[202:205], v[68:71]
	v_mfma_f32_16x16x32_bf16 v[64:67], v[218:221], v[202:205], v[64:67]
	s_setprio 0
	s_mov_b32 m0, s49
	s_add_u32 s100, s54, s2
	s_addc_u32 s101, s55, s3
	s_barrier
	ds_read_b128 v[170:173], v156 offset:16384
	ds_read_b128 v[174:177], v156 offset:17408
	ds_read_b128 v[178:181], v156 offset:18432
	ds_read_b128 v[182:185], v156 offset:19456
	ds_read_b128 v[186:189], v156 offset:20480
	ds_read_b128 v[190:193], v156 offset:21504
	ds_read_b128 v[194:197], v156 offset:22528
	ds_read_b128 v[202:205], v156 offset:23552
	global_load_lds_dwordx4 v128, s[54:55]
	s_mov_b32 m0, s59
	s_nop 0
	global_load_lds_dwordx4 v132, s[54:55]
	s_barrier
	s_waitcnt lgkmcnt(0)
	s_setprio 1
	s_waitcnt lgkmcnt(0)
	v_mfma_f32_16x16x32_bf16 v[60:63], v[146:149], v[170:173], v[60:63]
	v_mfma_f32_16x16x32_bf16 v[56:59], v[162:165], v[170:173], v[56:59]
	v_mfma_f32_16x16x32_bf16 v[44:47], v[146:149], v[178:181], v[44:47]
	v_mfma_f32_16x16x32_bf16 v[40:43], v[162:165], v[178:181], v[40:43]
	v_mfma_f32_16x16x32_bf16 v[28:31], v[146:149], v[186:189], v[28:31]
	v_mfma_f32_16x16x32_bf16 v[24:27], v[162:165], v[186:189], v[24:27]
	v_mfma_f32_16x16x32_bf16 v[12:15], v[146:149], v[194:197], v[12:15]
	v_mfma_f32_16x16x32_bf16 v[8:11], v[162:165], v[194:197], v[8:11]
	v_mfma_f32_16x16x32_bf16 v[60:63], v[158:161], v[174:177], v[60:63]
	v_mfma_f32_16x16x32_bf16 v[56:59], v[166:169], v[174:177], v[56:59]
	v_mfma_f32_16x16x32_bf16 v[44:47], v[158:161], v[182:185], v[44:47]
	v_mfma_f32_16x16x32_bf16 v[40:43], v[166:169], v[182:185], v[40:43]
	v_mfma_f32_16x16x32_bf16 v[28:31], v[158:161], v[190:193], v[28:31]
	v_mfma_f32_16x16x32_bf16 v[24:27], v[166:169], v[190:193], v[24:27]
	v_mfma_f32_16x16x32_bf16 v[12:15], v[158:161], v[202:205], v[12:15]
	v_mfma_f32_16x16x32_bf16 v[8:11], v[166:169], v[202:205], v[8:11]
	s_setprio 0
	s_barrier
	s_add_u32 s28, s52, 0x80000
	s_addc_u32 s29, s53, 0
	s_add_i32 s69, s82, s58
	s_mov_b32 m0, s69
	s_nop 0
	global_load_lds_dwordx4 v130, s[28:29]
	s_add_i32 m0, s69, 0x2000
	s_nop 0
	global_load_lds_dwordx4 v134, s[28:29]
	s_waitcnt vmcnt(6)
	s_barrier
; #define PG8_STAGE(bufoff, gbase, voff) do { _Pragma("unroll") for (int _i = 0; _i < 2; ++_i) \
;         __builtin_amdgcn_global_load_lds((const unsigned*)((const char*)(gbase) + (voff)[_i]), (LAS unsigned*)(lds + (bufoff) + ldsw + _i * 8192), 16, 0, 0); } while (0)
; #define PG8_LDA(dst, b, h) do { _Pragma("unroll") for (int m = 0; m < 4; ++m) _Pragma("unroll") for (int k = 0; k < 2; ++k) dst[m][k] = *(const LAS bf16x8*)(lds + PG8_SA(b, h) + aoff + m * 2048 + k * 1024); } while (0)
; #define PG8_LDB(dst, b, h) do { _Pragma("unroll") for (int n = 0; n < 2; ++n) _Pragma("unroll") for (int k = 0; k < 2; ++k) dst[n][k] = *(const LAS bf16x8*)(lds + PG8_SB(b, h) + boff + n * 2048 + k * 1024); } while (0)
; #define PG8_WAIT_V(n) asm volatile("s_waitcnt vmcnt(" #n ")" ::: "memory")
; #define PG8_WAIT_L(n) asm volatile("s_waitcnt lgkmcnt(" #n ")" ::: "memory")
; #define PG8_BAR __builtin_amdgcn_s_barrier()
; #define PG8_SCHED __builtin_amdgcn_sched_barrier(0)
; template <class Epi>
; __device__ __forceinline__ void gemm_phase(LAS unsigned char* lds, const bf16_t* A, int lda, const bf16_t* Bt, int ldb, int M, int N, int K, int asel, const Epi& E, const int fixed_round = -1) {
;     ...
;             PG8_WAIT_V(6); PG8_BAR; PG8_MMA(1, 1, At, B1); PG8_BAR;
;             PG8_LDB(B0, 1, 0); PG8_SCHED; PG8_LDA(At, 1, 0); PG8_STAGE(PG8_SA(0, 1), a2 + hstepA, voffA);
;             PG8_WAIT_L(8); PG8_BAR; PG8_WAIT_L(0); PG8_MMA(0, 0, At, B0); PG8_BAR; PG8_SCHED;
;             PG8_LDB(B1, 1, 1); PG8_STAGE(PG8_SB(1, 0), b3, voffB);
;             PG8_BAR; PG8_WAIT_L(0); PG8_MMA(0, 1, At, B1); PG8_BAR;
;             PG8_LDA(At, 1, 1); PG8_STAGE(PG8_SA(1, 0), a3, voffA);
;             PG8_BAR; PG8_WAIT_L(0); PG8_MMA(1, 0, At, B0); PG8_BAR; PG8_SCHED;
	s_setprio 1
	v_mfma_f32_16x16x32_bf16 v[52:55], v[206:209], v[170:173], v[52:55]
	v_mfma_f32_16x16x32_bf16 v[48:51], v[214:217], v[170:173], v[48:51]
	v_mfma_f32_16x16x32_bf16 v[36:39], v[206:209], v[178:181], v[36:39]
	v_mfma_f32_16x16x32_bf16 v[32:35], v[214:217], v[178:181], v[32:35]
	v_mfma_f32_16x16x32_bf16 v[20:23], v[206:209], v[186:189], v[20:23]
	v_mfma_f32_16x16x32_bf16 v[16:19], v[214:217], v[186:189], v[16:19]
	v_mfma_f32_16x16x32_bf16 v[4:7], v[206:209], v[194:197], v[4:7]
	v_mfma_f32_16x16x32_bf16 v[0:3], v[214:217], v[194:197], v[0:3]
	v_mfma_f32_16x16x32_bf16 v[52:55], v[210:213], v[174:177], v[52:55]
	v_mfma_f32_16x16x32_bf16 v[48:51], v[218:221], v[174:177], v[48:51]
	v_mfma_f32_16x16x32_bf16 v[36:39], v[210:213], v[182:185], v[36:39]
	v_mfma_f32_16x16x32_bf16 v[32:35], v[218:221], v[182:185], v[32:35]
	v_mfma_f32_16x16x32_bf16 v[20:23], v[210:213], v[190:193], v[20:23]
	v_mfma_f32_16x16x32_bf16 v[16:19], v[218:221], v[190:193], v[16:19]
	v_mfma_f32_16x16x32_bf16 v[4:7], v[210:213], v[202:205], v[4:7]
	v_mfma_f32_16x16x32_bf16 v[0:3], v[218:221], v[202:205], v[0:3]
	s_setprio 0
	v_add_u32_e32 v136, s83, v153
	s_barrier
	ds_read_b128 v[146:149], v136
	ds_read_b128 v[158:161], v136 offset:1024
	ds_read_b128 v[162:165], v136 offset:2048
	ds_read_b128 v[166:169], v136 offset:3072
	s_add_u32 s28, s54, 0x80000
	s_addc_u32 s29, s55, 0
	s_mov_b32 m0, s60
	ds_read_b128 v[170:173], v156 offset:32768
	ds_read_b128 v[174:177], v156 offset:33792
	ds_read_b128 v[178:181], v156 offset:34816
	ds_read_b128 v[182:185], v156 offset:35840
	ds_read_b128 v[186:189], v156 offset:36864
	ds_read_b128 v[190:193], v156 offset:37888
	ds_read_b128 v[194:197], v156 offset:38912
	ds_read_b128 v[202:205], v156 offset:39936
	global_load_lds_dwordx4 v128, s[28:29]
	s_mov_b32 m0, s61
	s_nop 0
	global_load_lds_dwordx4 v132, s[28:29]
	s_waitcnt lgkmcnt(8)
	s_barrier
	s_waitcnt lgkmcnt(0)
	s_setprio 1
	s_waitcnt lgkmcnt(0)
	v_mfma_f32_16x16x32_bf16 v[124:127], v[146:149], v[170:173], v[124:127]
	v_mfma_f32_16x16x32_bf16 v[120:123], v[162:165], v[170:173], v[120:123]
	v_mfma_f32_16x16x32_bf16 v[108:111], v[146:149], v[178:181], v[108:111]
	v_mfma_f32_16x16x32_bf16 v[104:107], v[162:165], v[178:181], v[104:107]
	v_mfma_f32_16x16x32_bf16 v[92:95], v[146:149], v[186:189], v[92:95]
	v_mfma_f32_16x16x32_bf16 v[88:91], v[162:165], v[186:189], v[88:91]
	v_mfma_f32_16x16x32_bf16 v[76:79], v[146:149], v[194:197], v[76:79]
	v_mfma_f32_16x16x32_bf16 v[72:75], v[162:165], v[194:197], v[72:75]
	v_mfma_f32_16x16x32_bf16 v[124:127], v[158:161], v[174:177], v[124:127]
	v_mfma_f32_16x16x32_bf16 v[120:123], v[166:169], v[174:177], v[120:123]
	v_mfma_f32_16x16x32_bf16 v[108:111], v[158:161], v[182:185], v[108:111]
	v_mfma_f32_16x16x32_bf16 v[104:107], v[166:169], v[182:185], v[104:107]
	v_mfma_f32_16x16x32_bf16 v[92:95], v[158:161], v[190:193], v[92:95]
	v_mfma_f32_16x16x32_bf16 v[88:91], v[166:169], v[190:193], v[88:91]
	v_mfma_f32_16x16x32_bf16 v[76:79], v[158:161], v[202:205], v[76:79]
	v_mfma_f32_16x16x32_bf16 v[72:75], v[166:169], v[202:205], v[72:75]
	s_setprio 0
	s_barrier
	s_add_i32 s28, s83, s58
	v_add_u32_e32 v136, s84, v153
	s_mov_b32 m0, s28
	ds_read_b128 v[206:209], v136
	ds_read_b128 v[210:213], v136 offset:1024
	ds_read_b128 v[214:217], v136 offset:2048
	ds_read_b128 v[218:221], v136 offset:3072
	global_load_lds_dwordx4 v130, s[98:99]
	s_add_i32 m0, s28, 0x2000
	s_nop 0
	global_load_lds_dwordx4 v134, s[98:99]
	s_barrier
	s_waitcnt lgkmcnt(0)
	s_setprio 1
	s_waitcnt lgkmcnt(0)
	v_mfma_f32_16x16x32_bf16 v[116:119], v[206:209], v[170:173], v[116:119]
	v_mfma_f32_16x16x32_bf16 v[112:115], v[214:217], v[170:173], v[112:115]
	v_mfma_f32_16x16x32_bf16 v[100:103], v[206:209], v[178:181], v[100:103]
	v_mfma_f32_16x16x32_bf16 v[96:99], v[214:217], v[178:181], v[96:99]
	v_mfma_f32_16x16x32_bf16 v[84:87], v[206:209], v[186:189], v[84:87]
	v_mfma_f32_16x16x32_bf16 v[80:83], v[214:217], v[186:189], v[80:83]
	v_mfma_f32_16x16x32_bf16 v[68:71], v[206:209], v[194:197], v[68:71]
	v_mfma_f32_16x16x32_bf16 v[64:67], v[214:217], v[194:197], v[64:67]
	v_mfma_f32_16x16x32_bf16 v[116:119], v[210:213], v[174:177], v[116:119]
	v_mfma_f32_16x16x32_bf16 v[112:115], v[218:221], v[174:177], v[112:115]
	v_mfma_f32_16x16x32_bf16 v[100:103], v[210:213], v[182:185], v[100:103]
	v_mfma_f32_16x16x32_bf16 v[96:99], v[218:221], v[182:185], v[96:99]
	v_mfma_f32_16x16x32_bf16 v[84:87], v[210:213], v[190:193], v[84:87]
	v_mfma_f32_16x16x32_bf16 v[80:83], v[218:221], v[190:193], v[80:83]
	v_mfma_f32_16x16x32_bf16 v[68:71], v[210:213], v[202:205], v[68:71]
	v_mfma_f32_16x16x32_bf16 v[64:67], v[218:221], v[202:205], v[64:67]
	s_setprio 0
	s_mov_b32 m0, s63
	s_barrier
	ds_read_b128 v[170:173], v156 offset:49152
	ds_read_b128 v[174:177], v156 offset:50176
	ds_read_b128 v[178:181], v156 offset:51200
	ds_read_b128 v[182:185], v156 offset:52224
	ds_read_b128 v[186:189], v156 offset:53248
	ds_read_b128 v[190:193], v156 offset:54272
	ds_read_b128 v[194:197], v156 offset:55296
	ds_read_b128 v[202:205], v156 offset:56320
	global_load_lds_dwordx4 v128, s[100:101]
	s_mov_b32 m0, s64
	s_nop 0
	global_load_lds_dwordx4 v132, s[100:101]
	s_barrier
; __device__ __forceinline__ unsigned cvt_pk_bf16(float lo, float hi) { const bf16x2_t r = __builtin_convertvector((f32x2){lo, hi}, bf16x2_t); return __builtin_bit_cast(unsigned, r); }
; #define PG8_STAGE(bufoff, gbase, voff) do { _Pragma("unroll") for (int _i = 0; _i < 2; ++_i) \
;         __builtin_amdgcn_global_load_lds((const unsigned*)((const char*)(gbase) + (voff)[_i]), (LAS unsigned*)(lds + (bufoff) + ldsw + _i * 8192), 16, 0, 0); } while (0)
; #define PG8_WAIT_V(n) asm volatile("s_waitcnt vmcnt(" #n ")" ::: "memory")
; #define PG8_WAIT_L(n) asm volatile("s_waitcnt lgkmcnt(" #n ")" ::: "memory")
; #define PG8_BAR __builtin_amdgcn_s_barrier()
; template <class Epi>
; __device__ __forceinline__ void gemm_phase(LAS unsigned char* lds, const bf16_t* A, int lda, const bf16_t* Bt, int ldb, int M, int N, int K, int asel, const Epi& E, const int fixed_round = -1) {
;     ...
;             PG8_BAR; PG8_WAIT_L(0); PG8_MMA(1, 0, At, B0); PG8_BAR; PG8_SCHED;
;             PG8_STAGE(PG8_SB(1, 1), b3 + hstepB, voffB);
;             PG8_WAIT_V(6); PG8_BAR; PG8_MMA(1, 1, At, B1); PG8_BAR;
;     __device__ __forceinline__ void operator()(const AccT& acc, const Unit& u, int wr, int wc, int fr, int fq) const {
;         const int row0 = u.pm * BM + wr * 64 + fr; const bool isg = u.pn >= 8;
;         bf16_t* base = isg ? GB : XB; const int col0 = (u.pn & 7) * BM + wc * 32 + 8 * fq;
; #pragma unroll
;         for (int ai = 0; ai < 2; ++ai)
; #pragma unroll
;             for (int m = 0; m < 4; ++m) { bf16_t* rowp = base + (size_t)(row0 + ai * HALF + m * 16) * DM + col0;
; #pragma unroll
;                 for (int bj = 0; bj < 2; ++bj) { f32x4 v0 = acc[ai][bj][m][0], v1 = acc[ai][bj][m][1];
;                     if (isg) {
; #pragma unroll
;                         for (int j = 0; j < 4; ++j) { float a = v0[j], b = v1[j];
;                             const float ta = 1.5957691216057308f * (a + 0.044715f * a * a * a), tb = 1.5957691216057308f * (b + 0.044715f * b * b * b);
;                             v0[j] = a * __builtin_amdgcn_rcpf(1.0f + __expf(-ta)); v1[j] = b * __builtin_amdgcn_rcpf(1.0f + __expf(-tb)); } }
;                     u32x4 w; w.x = cvt_pk_bf16(v0[0], v0[1]); w.y = cvt_pk_bf16(v0[2], v0[3]); w.z = cvt_pk_bf16(v1[0], v1[1]); w.w = cvt_pk_bf16(v1[2], v1[3]);
;                     *(u32x4*)(rowp + bj * HALF) = w; } }
	s_waitcnt lgkmcnt(0)
	s_setprio 1
	s_waitcnt lgkmcnt(0)
	v_mfma_f32_16x16x32_bf16 v[60:63], v[146:149], v[170:173], v[60:63]
	v_mfma_f32_16x16x32_bf16 v[56:59], v[162:165], v[170:173], v[56:59]
	v_mfma_f32_16x16x32_bf16 v[44:47], v[146:149], v[178:181], v[44:47]
	v_mfma_f32_16x16x32_bf16 v[40:43], v[162:165], v[178:181], v[40:43]
	v_mfma_f32_16x16x32_bf16 v[28:31], v[146:149], v[186:189], v[28:31]
	v_mfma_f32_16x16x32_bf16 v[24:27], v[162:165], v[186:189], v[24:27]
	v_mfma_f32_16x16x32_bf16 v[12:15], v[146:149], v[194:197], v[12:15]
	v_mfma_f32_16x16x32_bf16 v[8:11], v[162:165], v[194:197], v[8:11]
	v_mfma_f32_16x16x32_bf16 v[60:63], v[158:161], v[174:177], v[60:63]
	v_mfma_f32_16x16x32_bf16 v[56:59], v[166:169], v[174:177], v[56:59]
	v_mfma_f32_16x16x32_bf16 v[44:47], v[158:161], v[182:185], v[44:47]
	v_mfma_f32_16x16x32_bf16 v[40:43], v[166:169], v[182:185], v[40:43]
	v_mfma_f32_16x16x32_bf16 v[28:31], v[158:161], v[190:193], v[28:31]
	v_mfma_f32_16x16x32_bf16 v[24:27], v[166:169], v[190:193], v[24:27]
	v_mfma_f32_16x16x32_bf16 v[12:15], v[158:161], v[202:205], v[12:15]
	v_mfma_f32_16x16x32_bf16 v[8:11], v[166:169], v[202:205], v[8:11]
	s_setprio 0
	s_barrier
	s_add_u32 s28, s52, 0x80080
	s_addc_u32 s29, s53, 0
	s_add_i32 s52, s84, s58
	s_mov_b32 m0, s52
	s_nop 0
	global_load_lds_dwordx4 v130, s[28:29]
	s_add_i32 m0, s52, 0x2000
	s_nop 0
	global_load_lds_dwordx4 v134, s[28:29]
	s_waitcnt vmcnt(6)
	s_barrier
	s_setprio 1
	v_mfma_f32_16x16x32_bf16 v[52:55], v[206:209], v[170:173], v[52:55]
	v_mfma_f32_16x16x32_bf16 v[48:51], v[214:217], v[170:173], v[48:51]
	v_mfma_f32_16x16x32_bf16 v[36:39], v[206:209], v[178:181], v[36:39]
	v_mfma_f32_16x16x32_bf16 v[32:35], v[214:217], v[178:181], v[32:35]
	v_mfma_f32_16x16x32_bf16 v[20:23], v[206:209], v[186:189], v[20:23]
	v_mfma_f32_16x16x32_bf16 v[16:19], v[214:217], v[186:189], v[16:19]
	v_mfma_f32_16x16x32_bf16 v[4:7], v[206:209], v[194:197], v[4:7]
	v_mfma_f32_16x16x32_bf16 v[0:3], v[214:217], v[194:197], v[0:3]
	v_mfma_f32_16x16x32_bf16 v[52:55], v[210:213], v[174:177], v[52:55]
	v_mfma_f32_16x16x32_bf16 v[48:51], v[218:221], v[174:177], v[48:51]
	v_mfma_f32_16x16x32_bf16 v[36:39], v[210:213], v[182:185], v[36:39]
	v_mfma_f32_16x16x32_bf16 v[32:35], v[218:221], v[182:185], v[32:35]
	v_mfma_f32_16x16x32_bf16 v[20:23], v[210:213], v[190:193], v[20:23]
	v_mfma_f32_16x16x32_bf16 v[16:19], v[218:221], v[190:193], v[16:19]
	v_mfma_f32_16x16x32_bf16 v[4:7], v[210:213], v[202:205], v[4:7]
	v_mfma_f32_16x16x32_bf16 v[0:3], v[218:221], v[202:205], v[0:3]
	s_setprio 0
	s_add_i32 s68, s68, 2
	s_add_u32 s50, s50, 0x100
	s_addc_u32 s51, s51, 0
	s_add_u32 s66, s66, 0x100
	s_addc_u32 s67, s67, 0
	s_cmp_gt_u32 s68, 29
	s_cbranch_scc0 .Lrot_7
	s_barrier
	s_cmp_gt_i32 s4, 7
	s_cselect_b64 s[50:51], -1, 0
	s_cmp_lt_i32 s4, 8
	s_cbranch_scc1 .LBB0_802
	v_mul_f32_e32 v136, 0x3d372713, v124
	v_mul_f32_e32 v136, v124, v136
	v_mul_f32_e32 v146, 0x3d372713, v120
	v_fma_f32 v136, v124, v136, v124
	v_mul_f32_e32 v146, v120, v146
	v_fma_f32 v146, v120, v146, v120
	v_mul_f32_e32 v136, 0xbfcc422a, v136
	v_mul_f32_e32 v136, 0x3fb8aa3b, v136
	v_mul_f32_e32 v146, 0xbfcc422a, v146
	v_exp_f32_e32 v136, v136
	v_mul_f32_e32 v146, 0x3fb8aa3b, v146
	v_exp_f32_e32 v147, v146
	v_mul_f32_e32 v150, 0x3d372713, v122
	v_add_f32_e32 v136, 1.0, v136
	v_rcp_f32_e32 v146, v136
	v_add_f32_e32 v136, 1.0, v147
	v_rcp_f32_e32 v148, v136
	v_mul_f32_e32 v136, 0x3d372713, v125
	v_mul_f32_e32 v136, v125, v136
	v_fma_f32 v136, v125, v136, v125
	v_mul_f32_e32 v136, 0xbfcc422a, v136
	v_mul_f32_e32 v136, 0x3fb8aa3b, v136
	v_exp_f32_e32 v136, v136
	v_mul_f32_e32 v147, 0x3d372713, v121
	v_mul_f32_e32 v147, v121, v147
	v_fma_f32 v149, v121, v147, v121
	v_add_f32_e32 v136, 1.0, v136
	v_rcp_f32_e32 v147, v136
	v_mul_f32_e32 v136, 0xbfcc422a, v149
	v_mul_f32_e32 v149, 0x3d372713, v126
	v_mul_f32_e32 v149, v126, v149
	v_fma_f32 v149, v126, v149, v126
	v_mul_f32_e32 v150, v122, v150
	v_fma_f32 v150, v122, v150, v122
	v_mul_f32_e32 v149, 0xbfcc422a, v149
	v_mul_f32_e32 v149, 0x3fb8aa3b, v149
	v_mul_f32_e32 v150, 0xbfcc422a, v150
	v_exp_f32_e32 v149, v149
	v_mul_f32_e32 v150, 0x3fb8aa3b, v150
	v_exp_f32_e32 v151, v150
	v_mul_f32_e32 v158, 0x3d372713, v123
	v_add_f32_e32 v149, 1.0, v149
	v_rcp_f32_e32 v150, v149
	v_add_f32_e32 v149, 1.0, v151
	v_mul_f32_e32 v151, 0x3d372713, v127
	v_mul_f32_e32 v151, v127, v151
	v_fma_f32 v151, v127, v151, v127
	v_mul_f32_e32 v158, v123, v158
	v_fma_f32 v158, v123, v158, v123
	v_mul_f32_e32 v151, 0xbfcc422a, v151
	v_mul_f32_e32 v151, 0x3fb8aa3b, v151
	v_mul_f32_e32 v158, 0xbfcc422a, v158
	v_mul_f32_e32 v136, 0x3fb8aa3b, v136
	v_exp_f32_e32 v151, v151
	v_mul_f32_e32 v158, 0x3fb8aa3b, v158
	v_exp_f32_e32 v136, v136
	v_exp_f32_e32 v159, v158
	v_rcp_f32_e32 v158, v149
	v_add_f32_e32 v149, 1.0, v151
	v_add_f32_e32 v136, 1.0, v136
	v_rcp_f32_e32 v151, v149
	v_add_f32_e32 v149, 1.0, v159
	v_rcp_f32_e32 v159, v149
	v_rcp_f32_e32 v149, v136
	v_pk_mul_f32 v[126:127], v[126:127], v[150:151]
	v_pk_mul_f32 v[124:125], v[124:125], v[146:147]
	v_pk_mul_f32 v[122:123], v[122:123], v[158:159]
	v_pk_mul_f32 v[120:121], v[120:121], v[148:149]

; #define PG8_STAGE(bufoff, gbase, voff) do { _Pragma("unroll") for (int _i = 0; _i < 2; ++_i) \
;         __builtin_amdgcn_global_load_lds((const unsigned*)((const char*)(gbase) + (voff)[_i]), (LAS unsigned*)(lds + (bufoff) + ldsw + _i * 8192), 16, 0, 0); } while (0)
; #define PG8_LDA(dst, b, h) do { _Pragma("unroll") for (int m = 0; m < 4; ++m) _Pragma("unroll") for (int k = 0; k < 2; ++k) dst[m][k] = *(const LAS bf16x8*)(lds + PG8_SA(b, h) + aoff + m * 2048 + k * 1024); } while (0)
; #define PG8_LDB(dst, b, h) do { _Pragma("unroll") for (int n = 0; n < 2; ++n) _Pragma("unroll") for (int k = 0; k < 2; ++k) dst[n][k] = *(const LAS bf16x8*)(lds + PG8_SB(b, h) + boff + n * 2048 + k * 1024); } while (0)
; #define PG8_WAIT_V(n) asm volatile("s_waitcnt vmcnt(" #n ")" ::: "memory")
; #define PG8_WAIT_L(n) asm volatile("s_waitcnt lgkmcnt(" #n ")" ::: "memory")
; #define PG8_BAR __builtin_amdgcn_s_barrier()
; #define PG8_SCHED __builtin_amdgcn_sched_barrier(0)
; template <class Epi>
; __device__ __forceinline__ void gemm_phase(LAS unsigned char* lds, const bf16_t* A, int lda, const bf16_t* Bt, int ldb, int M, int N, int K, int asel, const Epi& E, const int fixed_round = -1) {
;     ...
;         const char* nA = has_next ? PG8_ABASE(nxt) : cA; const char* nB = has_next ? (const char*)Bt + (size_t)nxt.pn * tstepB : cB;
;         for (int t = 0; t < nt; t += 2) {
;             const bool last = (t == nt - 2);
;             const char* a1 = cA + (size_t)(t + 1) * kstep;
;             const char* a2 = last ? nA : cA + (size_t)(t + 2) * kstep; const char* b2 = last ? nB : cB + (size_t)(t + 2) * kstep;
;             const char* a3 = a2 + kstep; const char* b3 = b2 + kstep;
;             PG8_LDB(B0, 0, 0); PG8_SCHED; PG8_LDA(At, 0, 0); PG8_STAGE(PG8_SA(1, 1), a1 + hstepA, voffA);
;             PG8_WAIT_L(8); PG8_BAR; PG8_WAIT_L(0); PG8_MMA(0, 0, At, B0); PG8_BAR; PG8_SCHED;
;             PG8_LDB(B1, 0, 1); PG8_STAGE(PG8_SB(0, 0), b2, voffB);
;             PG8_BAR; PG8_WAIT_L(0); PG8_MMA(0, 1, At, B1); PG8_BAR;
;             PG8_LDA(At, 0, 1); PG8_STAGE(PG8_SA(0, 0), a2, voffA);
;             PG8_BAR; PG8_WAIT_L(0); PG8_MMA(1, 0, At, B0); PG8_BAR; PG8_SCHED;
;             PG8_STAGE(PG8_SB(0, 1), b2 + hstepB, voffB);
;             PG8_WAIT_V(6); PG8_BAR; PG8_MMA(1, 1, At, B1); PG8_BAR;
.LBB0_1223:
	ds_read_b128 v[152:155], v149
	ds_read_b128 v[156:159], v149 offset:1024
	ds_read_b128 v[160:163], v149 offset:2048
	ds_read_b128 v[164:167], v149 offset:3072
	s_add_i32 m0, s45, 0xc000
	ds_read_b128 v[168:171], v150
	ds_read_b128 v[172:175], v150 offset:1024
	ds_read_b128 v[176:179], v150 offset:2048
	ds_read_b128 v[180:183], v150 offset:3072
	ds_read_b128 v[184:187], v150 offset:4096
	ds_read_b128 v[188:191], v150 offset:5120
	ds_read_b128 v[192:195], v150 offset:6144
	ds_read_b128 v[196:199], v150 offset:7168
	global_load_lds_dwordx4 v136, s[46:47]
	s_add_i32 m0, s45, 0xe000
	s_nop 0
	global_load_lds_dwordx4 v138, s[46:47]
	s_waitcnt lgkmcnt(8)
	s_barrier
	s_waitcnt lgkmcnt(0)
	s_setprio 1
	s_waitcnt lgkmcnt(0)
	v_mfma_f32_16x16x32_bf16 v[124:127], v[152:155], v[168:171], v[124:127]
	v_mfma_f32_16x16x32_bf16 v[120:123], v[160:163], v[168:171], v[120:123]
	v_mfma_f32_16x16x32_bf16 v[108:111], v[152:155], v[176:179], v[108:111]
	v_mfma_f32_16x16x32_bf16 v[104:107], v[160:163], v[176:179], v[104:107]
	v_mfma_f32_16x16x32_bf16 v[92:95], v[152:155], v[184:187], v[92:95]
	v_mfma_f32_16x16x32_bf16 v[88:91], v[160:163], v[184:187], v[88:91]
	v_mfma_f32_16x16x32_bf16 v[76:79], v[152:155], v[192:195], v[76:79]
	v_mfma_f32_16x16x32_bf16 v[72:75], v[160:163], v[192:195], v[72:75]
	v_mfma_f32_16x16x32_bf16 v[124:127], v[156:159], v[172:175], v[124:127]
	v_mfma_f32_16x16x32_bf16 v[120:123], v[164:167], v[172:175], v[120:123]
	v_mfma_f32_16x16x32_bf16 v[108:111], v[156:159], v[180:183], v[108:111]
	v_mfma_f32_16x16x32_bf16 v[104:107], v[164:167], v[180:183], v[104:107]
	v_mfma_f32_16x16x32_bf16 v[92:95], v[156:159], v[188:191], v[92:95]
	v_mfma_f32_16x16x32_bf16 v[88:91], v[164:167], v[188:191], v[88:91]
	v_mfma_f32_16x16x32_bf16 v[76:79], v[156:159], v[196:199], v[76:79]
	v_mfma_f32_16x16x32_bf16 v[72:75], v[164:167], v[196:199], v[72:75]
	s_setprio 0
	s_barrier
	s_add_u32 s48, s46, 0xfff80080
	s_addc_u32 s49, s47, -1
	s_cmp_eq_u32 s70, 28
	s_cselect_b32 s51, s29, s49
	s_cselect_b32 s50, s66, s48
	s_cselect_b32 s49, s25, s69
	s_cselect_b32 s48, s67, s68
	s_add_i32 s71, s81, s54
	s_add_u32 s98, s48, s2
	s_addc_u32 s99, s49, s3
	s_mov_b32 m0, s71
	ds_read_b128 v[202:205], v151
	ds_read_b128 v[206:209], v151 offset:1024
	ds_read_b128 v[210:213], v151 offset:2048
	ds_read_b128 v[214:217], v151 offset:3072
	global_load_lds_dwordx4 v130, s[48:49]
	s_add_i32 m0, s71, 0x2000
	s_nop 0
	global_load_lds_dwordx4 v134, s[48:49]
	s_barrier
	s_waitcnt lgkmcnt(0)
	s_setprio 1
	s_waitcnt lgkmcnt(0)
	v_mfma_f32_16x16x32_bf16 v[116:119], v[202:205], v[168:171], v[116:119]
	v_mfma_f32_16x16x32_bf16 v[112:115], v[210:213], v[168:171], v[112:115]
	v_mfma_f32_16x16x32_bf16 v[100:103], v[202:205], v[176:179], v[100:103]
	v_mfma_f32_16x16x32_bf16 v[96:99], v[210:213], v[176:179], v[96:99]
	v_mfma_f32_16x16x32_bf16 v[84:87], v[202:205], v[184:187], v[84:87]
	v_mfma_f32_16x16x32_bf16 v[80:83], v[210:213], v[184:187], v[80:83]
	v_mfma_f32_16x16x32_bf16 v[68:71], v[202:205], v[192:195], v[68:71]
	v_mfma_f32_16x16x32_bf16 v[64:67], v[210:213], v[192:195], v[64:67]
	v_mfma_f32_16x16x32_bf16 v[116:119], v[206:209], v[172:175], v[116:119]
	v_mfma_f32_16x16x32_bf16 v[112:115], v[214:217], v[172:175], v[112:115]
	v_mfma_f32_16x16x32_bf16 v[100:103], v[206:209], v[180:183], v[100:103]
	v_mfma_f32_16x16x32_bf16 v[96:99], v[214:217], v[180:183], v[96:99]
	v_mfma_f32_16x16x32_bf16 v[84:87], v[206:209], v[188:191], v[84:87]
	v_mfma_f32_16x16x32_bf16 v[80:83], v[214:217], v[188:191], v[80:83]
	v_mfma_f32_16x16x32_bf16 v[68:71], v[206:209], v[196:199], v[68:71]
	v_mfma_f32_16x16x32_bf16 v[64:67], v[214:217], v[196:199], v[64:67]
	s_setprio 0
	s_mov_b32 m0, s45
	s_add_u32 s100, s50, s2
	s_addc_u32 s101, s51, s3
	s_barrier
	ds_read_b128 v[168:171], v150 offset:16384
	ds_read_b128 v[172:175], v150 offset:17408
	ds_read_b128 v[176:179], v150 offset:18432
	ds_read_b128 v[180:183], v150 offset:19456
	ds_read_b128 v[184:187], v150 offset:20480
	ds_read_b128 v[188:191], v150 offset:21504
	ds_read_b128 v[192:195], v150 offset:22528
	ds_read_b128 v[196:199], v150 offset:23552
	global_load_lds_dwordx4 v128, s[50:51]
	s_mov_b32 m0, s55
	s_nop 0
	global_load_lds_dwordx4 v132, s[50:51]
	s_barrier
	s_waitcnt lgkmcnt(0)
	s_setprio 1
	s_waitcnt lgkmcnt(0)
	v_mfma_f32_16x16x32_bf16 v[60:63], v[152:155], v[168:171], v[60:63]
	v_mfma_f32_16x16x32_bf16 v[56:59], v[160:163], v[168:171], v[56:59]
	v_mfma_f32_16x16x32_bf16 v[44:47], v[152:155], v[176:179], v[44:47]
	v_mfma_f32_16x16x32_bf16 v[40:43], v[160:163], v[176:179], v[40:43]
	v_mfma_f32_16x16x32_bf16 v[28:31], v[152:155], v[184:187], v[28:31]
	v_mfma_f32_16x16x32_bf16 v[24:27], v[160:163], v[184:187], v[24:27]
	v_mfma_f32_16x16x32_bf16 v[12:15], v[152:155], v[192:195], v[12:15]
	v_mfma_f32_16x16x32_bf16 v[8:11], v[160:163], v[192:195], v[8:11]
	v_mfma_f32_16x16x32_bf16 v[60:63], v[156:159], v[172:175], v[60:63]
	v_mfma_f32_16x16x32_bf16 v[56:59], v[164:167], v[172:175], v[56:59]
	v_mfma_f32_16x16x32_bf16 v[44:47], v[156:159], v[180:183], v[44:47]
	v_mfma_f32_16x16x32_bf16 v[40:43], v[164:167], v[180:183], v[40:43]
	v_mfma_f32_16x16x32_bf16 v[28:31], v[156:159], v[188:191], v[28:31]
	v_mfma_f32_16x16x32_bf16 v[24:27], v[164:167], v[188:191], v[24:27]
	v_mfma_f32_16x16x32_bf16 v[12:15], v[156:159], v[196:199], v[12:15]
	v_mfma_f32_16x16x32_bf16 v[8:11], v[164:167], v[196:199], v[8:11]
	s_setprio 0
	s_barrier
	s_add_u32 s72, s48, 0x80000
	s_addc_u32 s73, s49, 0
	s_add_i32 s71, s82, s54
	s_mov_b32 m0, s71
	s_nop 0
	global_load_lds_dwordx4 v130, s[72:73]
	s_add_i32 m0, s71, 0x2000
	s_nop 0
	global_load_lds_dwordx4 v134, s[72:73]
	s_waitcnt vmcnt(6)
	s_barrier
; #define PG8_STAGE(bufoff, gbase, voff) do { _Pragma("unroll") for (int _i = 0; _i < 2; ++_i) \
;         __builtin_amdgcn_global_load_lds((const unsigned*)((const char*)(gbase) + (voff)[_i]), (LAS unsigned*)(lds + (bufoff) + ldsw + _i * 8192), 16, 0, 0); } while (0)
; #define PG8_LDA(dst, b, h) do { _Pragma("unroll") for (int m = 0; m < 4; ++m) _Pragma("unroll") for (int k = 0; k < 2; ++k) dst[m][k] = *(const LAS bf16x8*)(lds + PG8_SA(b, h) + aoff + m * 2048 + k * 1024); } while (0)
; #define PG8_LDB(dst, b, h) do { _Pragma("unroll") for (int n = 0; n < 2; ++n) _Pragma("unroll") for (int k = 0; k < 2; ++k) dst[n][k] = *(const LAS bf16x8*)(lds + PG8_SB(b, h) + boff + n * 2048 + k * 1024); } while (0)
; #define PG8_WAIT_V(n) asm volatile("s_waitcnt vmcnt(" #n ")" ::: "memory")
; #define PG8_WAIT_L(n) asm volatile("s_waitcnt lgkmcnt(" #n ")" ::: "memory")
; #define PG8_BAR __builtin_amdgcn_s_barrier()
; #define PG8_SCHED __builtin_amdgcn_sched_barrier(0)
; template <class Epi>
; __device__ __forceinline__ void gemm_phase(LAS unsigned char* lds, const bf16_t* A, int lda, const bf16_t* Bt, int ldb, int M, int N, int K, int asel, const Epi& E, const int fixed_round = -1) {
;     ...
;             PG8_WAIT_V(6); PG8_BAR; PG8_MMA(1, 1, At, B1); PG8_BAR;
;             PG8_LDB(B0, 1, 0); PG8_SCHED; PG8_LDA(At, 1, 0); PG8_STAGE(PG8_SA(0, 1), a2 + hstepA, voffA);
;             PG8_WAIT_L(8); PG8_BAR; PG8_WAIT_L(0); PG8_MMA(0, 0, At, B0); PG8_BAR; PG8_SCHED;
;             PG8_LDB(B1, 1, 1); PG8_STAGE(PG8_SB(1, 0), b3, voffB);
;             PG8_BAR; PG8_WAIT_L(0); PG8_MMA(0, 1, At, B1); PG8_BAR;
;             PG8_LDA(At, 1, 1); PG8_STAGE(PG8_SA(1, 0), a3, voffA);
;             PG8_BAR; PG8_WAIT_L(0); PG8_MMA(1, 0, At, B0); PG8_BAR; PG8_SCHED;
	s_setprio 1
	v_mfma_f32_16x16x32_bf16 v[52:55], v[202:205], v[168:171], v[52:55]
	v_mfma_f32_16x16x32_bf16 v[48:51], v[210:213], v[168:171], v[48:51]
	v_mfma_f32_16x16x32_bf16 v[36:39], v[202:205], v[176:179], v[36:39]
	v_mfma_f32_16x16x32_bf16 v[32:35], v[210:213], v[176:179], v[32:35]
	v_mfma_f32_16x16x32_bf16 v[20:23], v[202:205], v[184:187], v[20:23]
	v_mfma_f32_16x16x32_bf16 v[16:19], v[210:213], v[184:187], v[16:19]
	v_mfma_f32_16x16x32_bf16 v[4:7], v[202:205], v[192:195], v[4:7]
	v_mfma_f32_16x16x32_bf16 v[0:3], v[210:213], v[192:195], v[0:3]
	v_mfma_f32_16x16x32_bf16 v[52:55], v[206:209], v[172:175], v[52:55]
	v_mfma_f32_16x16x32_bf16 v[48:51], v[214:217], v[172:175], v[48:51]
	v_mfma_f32_16x16x32_bf16 v[36:39], v[206:209], v[180:183], v[36:39]
	v_mfma_f32_16x16x32_bf16 v[32:35], v[214:217], v[180:183], v[32:35]
	v_mfma_f32_16x16x32_bf16 v[20:23], v[206:209], v[188:191], v[20:23]
	v_mfma_f32_16x16x32_bf16 v[16:19], v[214:217], v[188:191], v[16:19]
	v_mfma_f32_16x16x32_bf16 v[4:7], v[206:209], v[196:199], v[4:7]
	v_mfma_f32_16x16x32_bf16 v[0:3], v[214:217], v[196:199], v[0:3]
	s_setprio 0
	v_add_u32_e32 v164, s83, v147
	s_barrier
	ds_read_b128 v[152:155], v164
	ds_read_b128 v[156:159], v164 offset:1024
	ds_read_b128 v[160:163], v164 offset:2048
	ds_read_b128 v[164:167], v164 offset:3072
	s_add_u32 s50, s50, 0x80000
	s_addc_u32 s51, s51, 0
	s_mov_b32 m0, s56
	ds_read_b128 v[168:171], v150 offset:32768
	ds_read_b128 v[172:175], v150 offset:33792
	ds_read_b128 v[176:179], v150 offset:34816
	ds_read_b128 v[180:183], v150 offset:35840
	ds_read_b128 v[184:187], v150 offset:36864
	ds_read_b128 v[188:191], v150 offset:37888
	ds_read_b128 v[192:195], v150 offset:38912
	ds_read_b128 v[196:199], v150 offset:39936
	global_load_lds_dwordx4 v128, s[50:51]
	s_mov_b32 m0, s57
	s_nop 0
	global_load_lds_dwordx4 v132, s[50:51]
	s_waitcnt lgkmcnt(8)
	s_barrier
	s_waitcnt lgkmcnt(0)
	s_setprio 1
	s_waitcnt lgkmcnt(0)
	v_mfma_f32_16x16x32_bf16 v[124:127], v[152:155], v[168:171], v[124:127]
	v_mfma_f32_16x16x32_bf16 v[120:123], v[160:163], v[168:171], v[120:123]
	v_mfma_f32_16x16x32_bf16 v[108:111], v[152:155], v[176:179], v[108:111]
	v_mfma_f32_16x16x32_bf16 v[104:107], v[160:163], v[176:179], v[104:107]
	v_mfma_f32_16x16x32_bf16 v[92:95], v[152:155], v[184:187], v[92:95]
	v_mfma_f32_16x16x32_bf16 v[88:91], v[160:163], v[184:187], v[88:91]
	v_mfma_f32_16x16x32_bf16 v[76:79], v[152:155], v[192:195], v[76:79]
	v_mfma_f32_16x16x32_bf16 v[72:75], v[160:163], v[192:195], v[72:75]
	v_mfma_f32_16x16x32_bf16 v[124:127], v[156:159], v[172:175], v[124:127]
	v_mfma_f32_16x16x32_bf16 v[120:123], v[164:167], v[172:175], v[120:123]
	v_mfma_f32_16x16x32_bf16 v[108:111], v[156:159], v[180:183], v[108:111]
	v_mfma_f32_16x16x32_bf16 v[104:107], v[164:167], v[180:183], v[104:107]
	v_mfma_f32_16x16x32_bf16 v[92:95], v[156:159], v[188:191], v[92:95]
	v_mfma_f32_16x16x32_bf16 v[88:91], v[164:167], v[188:191], v[88:91]
	v_mfma_f32_16x16x32_bf16 v[76:79], v[156:159], v[196:199], v[76:79]
	v_mfma_f32_16x16x32_bf16 v[72:75], v[164:167], v[196:199], v[72:75]
	s_setprio 0
	s_barrier
	s_add_i32 s50, s83, s54
	v_add_u32_e32 v214, s84, v147
	s_mov_b32 m0, s50
	ds_read_b128 v[202:205], v214
	ds_read_b128 v[206:209], v214 offset:1024
	ds_read_b128 v[210:213], v214 offset:2048
	ds_read_b128 v[214:217], v214 offset:3072
	global_load_lds_dwordx4 v130, s[98:99]
	s_add_i32 m0, s50, 0x2000
	s_nop 0
	global_load_lds_dwordx4 v134, s[98:99]
	s_barrier
	s_waitcnt lgkmcnt(0)
	s_setprio 1
	s_waitcnt lgkmcnt(0)
	v_mfma_f32_16x16x32_bf16 v[116:119], v[202:205], v[168:171], v[116:119]
	v_mfma_f32_16x16x32_bf16 v[112:115], v[210:213], v[168:171], v[112:115]
	v_mfma_f32_16x16x32_bf16 v[100:103], v[202:205], v[176:179], v[100:103]
	v_mfma_f32_16x16x32_bf16 v[96:99], v[210:213], v[176:179], v[96:99]
	v_mfma_f32_16x16x32_bf16 v[84:87], v[202:205], v[184:187], v[84:87]
	v_mfma_f32_16x16x32_bf16 v[80:83], v[210:213], v[184:187], v[80:83]
	v_mfma_f32_16x16x32_bf16 v[68:71], v[202:205], v[192:195], v[68:71]
	v_mfma_f32_16x16x32_bf16 v[64:67], v[210:213], v[192:195], v[64:67]
	v_mfma_f32_16x16x32_bf16 v[116:119], v[206:209], v[172:175], v[116:119]
	v_mfma_f32_16x16x32_bf16 v[112:115], v[214:217], v[172:175], v[112:115]
	v_mfma_f32_16x16x32_bf16 v[100:103], v[206:209], v[180:183], v[100:103]
	v_mfma_f32_16x16x32_bf16 v[96:99], v[214:217], v[180:183], v[96:99]
	v_mfma_f32_16x16x32_bf16 v[84:87], v[206:209], v[188:191], v[84:87]
	v_mfma_f32_16x16x32_bf16 v[80:83], v[214:217], v[188:191], v[80:83]
	v_mfma_f32_16x16x32_bf16 v[68:71], v[206:209], v[196:199], v[68:71]
	v_mfma_f32_16x16x32_bf16 v[64:67], v[214:217], v[196:199], v[64:67]
	s_setprio 0
	s_mov_b32 m0, s59
	s_barrier
	ds_read_b128 v[168:171], v150 offset:49152
	ds_read_b128 v[172:175], v150 offset:50176
	ds_read_b128 v[176:179], v150 offset:51200
	ds_read_b128 v[180:183], v150 offset:52224
	ds_read_b128 v[184:187], v150 offset:53248
	ds_read_b128 v[188:191], v150 offset:54272
	ds_read_b128 v[192:195], v150 offset:55296
	ds_read_b128 v[196:199], v150 offset:56320
	global_load_lds_dwordx4 v128, s[100:101]
	s_mov_b32 m0, s60
	s_nop 0
	global_load_lds_dwordx4 v132, s[100:101]
	s_barrier
; __device__ __forceinline__ unsigned cvt_pk_bf16(float lo, float hi) { const bf16x2_t r = __builtin_convertvector((f32x2){lo, hi}, bf16x2_t); return __builtin_bit_cast(unsigned, r); }
; #define PG8_STAGE(bufoff, gbase, voff) do { _Pragma("unroll") for (int _i = 0; _i < 2; ++_i) \
;         __builtin_amdgcn_global_load_lds((const unsigned*)((const char*)(gbase) + (voff)[_i]), (LAS unsigned*)(lds + (bufoff) + ldsw + _i * 8192), 16, 0, 0); } while (0)
; #define PG8_WAIT_V(n) asm volatile("s_waitcnt vmcnt(" #n ")" ::: "memory")
; #define PG8_BAR __builtin_amdgcn_s_barrier()
; template <class Epi>
; __device__ __forceinline__ void gemm_phase(LAS unsigned char* lds, const bf16_t* A, int lda, const bf16_t* Bt, int ldb, int M, int N, int K, int asel, const Epi& E, const int fixed_round = -1) {
;     ...
;             PG8_WAIT_V(6); PG8_BAR; PG8_MMA(1, 1, At, B1); PG8_BAR;
;             PG8_LDB(B0, 1, 0); PG8_SCHED; PG8_LDA(At, 1, 0); PG8_STAGE(PG8_SA(0, 1), a2 + hstepA, voffA);
;             PG8_WAIT_L(8); PG8_BAR; PG8_WAIT_L(0); PG8_MMA(0, 0, At, B0); PG8_BAR; PG8_SCHED;
;             PG8_LDB(B1, 1, 1); PG8_STAGE(PG8_SB(1, 0), b3, voffB);
;             PG8_BAR; PG8_WAIT_L(0); PG8_MMA(0, 1, At, B1); PG8_BAR;
;             PG8_LDA(At, 1, 1); PG8_STAGE(PG8_SA(1, 0), a3, voffA);
;             PG8_BAR; PG8_WAIT_L(0); PG8_MMA(1, 0, At, B0); PG8_BAR; PG8_SCHED;
;             PG8_STAGE(PG8_SB(1, 1), b3 + hstepB, voffB);
;             PG8_WAIT_V(6); PG8_BAR; PG8_MMA(1, 1, At, B1); PG8_BAR;
;     __device__ __forceinline__ void operator()(const AccT& acc, const Unit& u, int wr, int wc, int fr, int fq) const {
;         const int row0 = u.pm * BM + wr * 64 + fr, col0 = u.pn * BM + wc * 32 + 8 * fq;
; #pragma unroll
;         for (int ai = 0; ai < 2; ++ai)
; #pragma unroll
;             for (int m = 0; m < 4; ++m) { bf16_t* rowp = O + (size_t)(row0 + ai * HALF + m * 16) * DFF + col0;
; #pragma unroll
;                 for (int bj = 0; bj < 2; ++bj) { f32x4 v0 = acc[ai][bj][m][0], v1 = acc[ai][bj][m][1];
; #pragma unroll
;                     for (int j = 0; j < 4; ++j) { float a = fmaxf(v0[j], 0.f), b = fmaxf(v1[j], 0.f); v0[j] = a * a; v1[j] = b * b; }
;                     u32x4 w; w.x = cvt_pk_bf16(v0[0], v0[1]); w.y = cvt_pk_bf16(v0[2], v0[3]); w.z = cvt_pk_bf16(v1[0], v1[1]); w.w = cvt_pk_bf16(v1[2], v1[3]);
;                     *(u32x4*)(rowp + bj * HALF) = w; } }
	s_waitcnt lgkmcnt(0)
	s_setprio 1
	s_waitcnt lgkmcnt(0)
	v_mfma_f32_16x16x32_bf16 v[60:63], v[152:155], v[168:171], v[60:63]
	v_mfma_f32_16x16x32_bf16 v[56:59], v[160:163], v[168:171], v[56:59]
	v_mfma_f32_16x16x32_bf16 v[44:47], v[152:155], v[176:179], v[44:47]
	v_mfma_f32_16x16x32_bf16 v[40:43], v[160:163], v[176:179], v[40:43]
	v_mfma_f32_16x16x32_bf16 v[28:31], v[152:155], v[184:187], v[28:31]
	v_mfma_f32_16x16x32_bf16 v[24:27], v[160:163], v[184:187], v[24:27]
	v_mfma_f32_16x16x32_bf16 v[12:15], v[152:155], v[192:195], v[12:15]
	v_mfma_f32_16x16x32_bf16 v[8:11], v[160:163], v[192:195], v[8:11]
	v_mfma_f32_16x16x32_bf16 v[60:63], v[156:159], v[172:175], v[60:63]
	v_mfma_f32_16x16x32_bf16 v[56:59], v[164:167], v[172:175], v[56:59]
	v_mfma_f32_16x16x32_bf16 v[44:47], v[156:159], v[180:183], v[44:47]
	v_mfma_f32_16x16x32_bf16 v[40:43], v[164:167], v[180:183], v[40:43]
	v_mfma_f32_16x16x32_bf16 v[28:31], v[156:159], v[188:191], v[28:31]
	v_mfma_f32_16x16x32_bf16 v[24:27], v[164:167], v[188:191], v[24:27]
	v_mfma_f32_16x16x32_bf16 v[12:15], v[156:159], v[196:199], v[12:15]
	v_mfma_f32_16x16x32_bf16 v[8:11], v[164:167], v[196:199], v[8:11]
	s_setprio 0
	s_barrier
	s_add_u32 s48, s48, 0x80080
	s_addc_u32 s49, s49, 0
	s_add_i32 s50, s84, s54
	s_mov_b32 m0, s50
	s_nop 0
	global_load_lds_dwordx4 v130, s[48:49]
	s_add_i32 m0, s50, 0x2000
	s_nop 0
	global_load_lds_dwordx4 v134, s[48:49]
	s_waitcnt vmcnt(6)
	s_barrier
	s_setprio 1
	v_mfma_f32_16x16x32_bf16 v[52:55], v[202:205], v[168:171], v[52:55]
	v_mfma_f32_16x16x32_bf16 v[48:51], v[210:213], v[168:171], v[48:51]
	v_mfma_f32_16x16x32_bf16 v[36:39], v[202:205], v[176:179], v[36:39]
	v_mfma_f32_16x16x32_bf16 v[32:35], v[210:213], v[176:179], v[32:35]
	v_mfma_f32_16x16x32_bf16 v[20:23], v[202:205], v[184:187], v[20:23]
	v_mfma_f32_16x16x32_bf16 v[16:19], v[210:213], v[184:187], v[16:19]
	v_mfma_f32_16x16x32_bf16 v[4:7], v[202:205], v[192:195], v[4:7]
	v_mfma_f32_16x16x32_bf16 v[0:3], v[210:213], v[192:195], v[0:3]
	v_mfma_f32_16x16x32_bf16 v[52:55], v[206:209], v[172:175], v[52:55]
	v_mfma_f32_16x16x32_bf16 v[48:51], v[214:217], v[172:175], v[48:51]
	v_mfma_f32_16x16x32_bf16 v[36:39], v[206:209], v[180:183], v[36:39]
	v_mfma_f32_16x16x32_bf16 v[32:35], v[214:217], v[180:183], v[32:35]
	v_mfma_f32_16x16x32_bf16 v[20:23], v[206:209], v[188:191], v[20:23]
	v_mfma_f32_16x16x32_bf16 v[16:19], v[214:217], v[188:191], v[16:19]
	v_mfma_f32_16x16x32_bf16 v[4:7], v[206:209], v[196:199], v[4:7]
	v_mfma_f32_16x16x32_bf16 v[0:3], v[214:217], v[196:199], v[0:3]
	s_setprio 0
	s_add_i32 s70, s70, 2
	s_add_u32 s46, s46, 0x100
	s_addc_u32 s47, s47, 0
	s_add_u32 s68, s68, 0x100
	s_addc_u32 s69, s69, 0
	s_cmp_gt_u32 s70, 29
	s_cbranch_scc0 .Lrot_10
	s_barrier
	v_lshl_add_u32 v152, s44, 8, v146
	v_lshl_or_b32 v144, s65, 8, v148
	v_ashrrev_i32_e32 v153, 31, v152
	v_readlane_b32 s46, v254, 60
	v_ashrrev_i32_e32 v145, 31, v144
	v_lshlrev_b64 v[154:155], 14, v[152:153]
	v_readlane_b32 s47, v254, 61
	v_lshl_add_u64 v[154:155], s[46:47], 0, v[154:155]
	v_lshlrev_b64 v[156:157], 1, v[144:145]
	v_max_f32_e32 v120, 0, v120
	v_max_f32_e32 v121, 0, v121
	v_lshl_add_u64 v[144:145], v[154:155], 0, v[156:157]
	v_pk_mul_f32 v[154:155], v[120:121], v[120:121]
	v_max_f32_e32 v121, v122, v122
	v_max_f32_e32 v120, v126, v126
	v_max_f32_e32 v122, 0, v121
	v_max_f32_e32 v121, v127, v127
	v_max_f32_e32 v124, 0, v124
	v_max_f32_e32 v125, 0, v125
	v_max_f32_e32 v120, 0, v120
	v_max_f32_e32 v121, 0, v121
	v_max_f32_e32 v123, 0, v123
	v_pk_mul_f32 v[124:125], v[124:125], v[124:125]
	v_pk_mul_f32 v[126:127], v[120:121], v[120:121]
	v_pk_mul_f32 v[158:159], v[122:123], v[122:123]
	v_cvt_pk_bf16_f32 v120, v124, v125
	v_cvt_pk_bf16_f32 v121, v126, v127
	v_cvt_pk_bf16_f32 v122, v154, v155
	v_cvt_pk_bf16_f32 v123, v158, v159
	v_max_f32_e32 v112, 0, v112
	v_max_f32_e32 v113, 0, v113
	global_store_dwordx4 v[144:145], v[120:123], off
	s_nop 1
	v_pk_mul_f32 v[120:121], v[112:113], v[112:113]
	v_max_f32_e32 v113, v114, v114
	v_max_f32_e32 v112, v118, v118
	v_max_f32_e32 v114, 0, v113
	v_max_f32_e32 v113, v119, v119
	v_max_f32_e32 v116, 0, v116
	v_max_f32_e32 v117, 0, v117
	v_max_f32_e32 v112, 0, v112
	v_max_f32_e32 v113, 0, v113
	v_max_f32_e32 v115, 0, v115
	v_pk_mul_f32 v[116:117], v[116:117], v[116:117]
	v_pk_mul_f32 v[118:119], v[112:113], v[112:113]
	v_pk_mul_f32 v[122:123], v[114:115], v[114:115]
	v_cvt_pk_bf16_f32 v112, v116, v117
	v_cvt_pk_bf16_f32 v113, v118, v119
	v_cvt_pk_bf16_f32 v114, v120, v121
	v_cvt_pk_bf16_f32 v115, v122, v123
	v_max_f32_e32 v104, 0, v104
	v_max_f32_e32 v105, 0, v105
	global_store_dwordx4 v[144:145], v[112:115], off offset:256
	s_nop 1
	v_or_b32_e32 v112, 16, v152
	v_pk_mul_f32 v[114:115], v[104:105], v[104:105]
	v_max_f32_e32 v105, v106, v106
	v_ashrrev_i32_e32 v113, 31, v112
	v_max_f32_e32 v104, v110, v110
	v_max_f32_e32 v106, 0, v105
	v_max_f32_e32 v105, v111, v111
	v_lshlrev_b64 v[112:113], 14, v[112:113]
	v_max_f32_e32 v108, 0, v108
	v_max_f32_e32 v109, 0, v109
	v_max_f32_e32 v104, 0, v104
	v_max_f32_e32 v105, 0, v105
	v_max_f32_e32 v107, 0, v107
	v_lshl_add_u64 v[112:113], s[46:47], 0, v[112:113]
	v_pk_mul_f32 v[108:109], v[108:109], v[108:109]
	v_pk_mul_f32 v[110:111], v[104:105], v[104:105]
	v_pk_mul_f32 v[116:117], v[106:107], v[106:107]
	v_lshl_add_u64 v[112:113], v[112:113], 0, v[156:157]
	v_cvt_pk_bf16_f32 v104, v108, v109
	v_cvt_pk_bf16_f32 v105, v110, v111
	v_cvt_pk_bf16_f32 v106, v114, v115
	v_cvt_pk_bf16_f32 v107, v116, v117
	v_max_f32_e32 v96, 0, v96
	v_max_f32_e32 v97, 0, v97
	global_store_dwordx4 v[112:113], v[104:107], off
	s_nop 1
	v_pk_mul_f32 v[104:105], v[96:97], v[96:97]
	v_max_f32_e32 v97, v98, v98
; __device__ __forceinline__ unsigned cvt_pk_bf16(float lo, float hi) { const bf16x2_t r = __builtin_convertvector((f32x2){lo, hi}, bf16x2_t); return __builtin_bit_cast(unsigned, r); }
;     __device__ __forceinline__ void operator()(const AccT& acc, const Unit& u, int wr, int wc, int fr, int fq) const {
;         const int row0 = u.pm * BM + wr * 64 + fr, col0 = u.pn * BM + wc * 32 + 8 * fq;
; #pragma unroll
;         for (int ai = 0; ai < 2; ++ai)
; #pragma unroll
;             for (int m = 0; m < 4; ++m) { bf16_t* rowp = O + (size_t)(row0 + ai * HALF + m * 16) * DFF + col0;
; #pragma unroll
;                 for (int bj = 0; bj < 2; ++bj) { f32x4 v0 = acc[ai][bj][m][0], v1 = acc[ai][bj][m][1];
; #pragma unroll
;                     for (int j = 0; j < 4; ++j) { float a = fmaxf(v0[j], 0.f), b = fmaxf(v1[j], 0.f); v0[j] = a * a; v1[j] = b * b; }
;                     u32x4 w; w.x = cvt_pk_bf16(v0[0], v0[1]); w.y = cvt_pk_bf16(v0[2], v0[3]); w.z = cvt_pk_bf16(v1[0], v1[1]); w.w = cvt_pk_bf16(v1[2], v1[3]);
;                     *(u32x4*)(rowp + bj * HALF) = w; } }
	v_max_f32_e32 v96, v102, v102
	v_max_f32_e32 v98, 0, v97
	v_max_f32_e32 v97, v103, v103
	v_max_f32_e32 v100, 0, v100
	v_max_f32_e32 v101, 0, v101
	v_max_f32_e32 v96, 0, v96
	v_max_f32_e32 v97, 0, v97
	v_max_f32_e32 v99, 0, v99
	v_pk_mul_f32 v[100:101], v[100:101], v[100:101]
	v_pk_mul_f32 v[102:103], v[96:97], v[96:97]
	v_pk_mul_f32 v[106:107], v[98:99], v[98:99]
	v_cvt_pk_bf16_f32 v96, v100, v101
	v_cvt_pk_bf16_f32 v97, v102, v103
	v_cvt_pk_bf16_f32 v98, v104, v105
	v_cvt_pk_bf16_f32 v99, v106, v107
	v_max_f32_e32 v88, 0, v88
	v_max_f32_e32 v89, 0, v89
	global_store_dwordx4 v[112:113], v[96:99], off offset:256
	s_nop 1
	v_or_b32_e32 v96, 32, v152
	v_pk_mul_f32 v[98:99], v[88:89], v[88:89]
	v_max_f32_e32 v89, v90, v90
	v_ashrrev_i32_e32 v97, 31, v96
	v_max_f32_e32 v88, v94, v94
	v_max_f32_e32 v90, 0, v89
	v_max_f32_e32 v89, v95, v95
	v_lshlrev_b64 v[96:97], 14, v[96:97]
	v_max_f32_e32 v92, 0, v92
	v_max_f32_e32 v93, 0, v93
	v_max_f32_e32 v88, 0, v88
	v_max_f32_e32 v89, 0, v89
	v_max_f32_e32 v91, 0, v91
	v_lshl_add_u64 v[96:97], s[46:47], 0, v[96:97]
	v_pk_mul_f32 v[92:93], v[92:93], v[92:93]
	v_pk_mul_f32 v[94:95], v[88:89], v[88:89]
	v_pk_mul_f32 v[100:101], v[90:91], v[90:91]
	v_lshl_add_u64 v[96:97], v[96:97], 0, v[156:157]
	v_cvt_pk_bf16_f32 v88, v92, v93
	v_cvt_pk_bf16_f32 v89, v94, v95
	v_cvt_pk_bf16_f32 v90, v98, v99
	v_cvt_pk_bf16_f32 v91, v100, v101
	v_max_f32_e32 v80, 0, v80
	v_max_f32_e32 v81, 0, v81
	global_store_dwordx4 v[96:97], v[88:91], off
	s_nop 1
	v_pk_mul_f32 v[88:89], v[80:81], v[80:81]
	v_max_f32_e32 v81, v82, v82
	v_max_f32_e32 v80, v86, v86
	v_max_f32_e32 v82, 0, v81
	v_max_f32_e32 v81, v87, v87
	v_max_f32_e32 v84, 0, v84
	v_max_f32_e32 v85, 0, v85
	v_max_f32_e32 v80, 0, v80
	v_max_f32_e32 v81, 0, v81
	v_max_f32_e32 v83, 0, v83
	v_pk_mul_f32 v[84:85], v[84:85], v[84:85]
	v_pk_mul_f32 v[86:87], v[80:81], v[80:81]
	v_pk_mul_f32 v[90:91], v[82:83], v[82:83]
	v_cvt_pk_bf16_f32 v80, v84, v85
	v_cvt_pk_bf16_f32 v81, v86, v87
	v_cvt_pk_bf16_f32 v82, v88, v89
	v_cvt_pk_bf16_f32 v83, v90, v91
	v_max_f32_e32 v72, 0, v72
	v_max_f32_e32 v73, 0, v73
	global_store_dwordx4 v[96:97], v[80:83], off offset:256
	s_nop 1
	v_or_b32_e32 v80, 48, v152
	v_pk_mul_f32 v[82:83], v[72:73], v[72:73]
	v_max_f32_e32 v73, v74, v74
	v_ashrrev_i32_e32 v81, 31, v80
	v_max_f32_e32 v72, v78, v78
	v_max_f32_e32 v74, 0, v73
	v_max_f32_e32 v73, v79, v79
	v_lshlrev_b64 v[80:81], 14, v[80:81]
	v_max_f32_e32 v76, 0, v76
	v_max_f32_e32 v77, 0, v77
	v_max_f32_e32 v72, 0, v72
	v_max_f32_e32 v73, 0, v73
	v_max_f32_e32 v75, 0, v75
	v_lshl_add_u64 v[80:81], s[46:47], 0, v[80:81]
	v_pk_mul_f32 v[76:77], v[76:77], v[76:77]
	v_pk_mul_f32 v[78:79], v[72:73], v[72:73]
	v_pk_mul_f32 v[84:85], v[74:75], v[74:75]
	v_lshl_add_u64 v[80:81], v[80:81], 0, v[156:157]
	v_cvt_pk_bf16_f32 v72, v76, v77
	v_cvt_pk_bf16_f32 v73, v78, v79
	v_cvt_pk_bf16_f32 v74, v82, v83
	v_cvt_pk_bf16_f32 v75, v84, v85
	v_max_f32_e32 v64, 0, v64
	v_max_f32_e32 v65, 0, v65
	global_store_dwordx4 v[80:81], v[72:75], off
	s_nop 1
	v_pk_mul_f32 v[72:73], v[64:65], v[64:65]
	v_max_f32_e32 v65, v66, v66
	v_max_f32_e32 v64, v70, v70
	v_max_f32_e32 v66, 0, v65
	v_max_f32_e32 v65, v71, v71
	v_max_f32_e32 v68, 0, v68
	v_max_f32_e32 v69, 0, v69
	v_max_f32_e32 v64, 0, v64
	v_max_f32_e32 v65, 0, v65
	v_max_f32_e32 v67, 0, v67
	v_pk_mul_f32 v[68:69], v[68:69], v[68:69]
	v_pk_mul_f32 v[70:71], v[64:65], v[64:65]
	v_pk_mul_f32 v[74:75], v[66:67], v[66:67]
	v_cvt_pk_bf16_f32 v64, v68, v69
	v_cvt_pk_bf16_f32 v65, v70, v71
	v_cvt_pk_bf16_f32 v66, v72, v73
	v_cvt_pk_bf16_f32 v67, v74, v75
	v_max_f32_e32 v56, 0, v56
	v_max_f32_e32 v57, 0, v57
	global_store_dwordx4 v[80:81], v[64:67], off offset:256
	s_nop 1
	v_pk_mul_f32 v[66:67], v[56:57], v[56:57]
	v_max_f32_e32 v57, v58, v58
	v_max_f32_e32 v60, 0, v60
	v_max_f32_e32 v61, 0, v61
	v_max_f32_e32 v56, v62, v62
	v_max_f32_e32 v58, 0, v57
	v_max_f32_e32 v57, v63, v63
	v_pk_mul_f32 v[60:61], v[60:61], v[60:61]
	v_max_f32_e32 v56, 0, v56
	v_max_f32_e32 v57, 0, v57
	v_max_f32_e32 v59, 0, v59
	v_pk_mul_f32 v[62:63], v[56:57], v[56:57]
	v_pk_mul_f32 v[68:69], v[58:59], v[58:59]
	v_cvt_pk_bf16_f32 v56, v60, v61
	v_add_co_u32_e32 v60, vcc, s61, v144
	v_cvt_pk_bf16_f32 v57, v62, v63
	v_cvt_pk_bf16_f32 v58, v66, v67
	v_cvt_pk_bf16_f32 v59, v68, v69
	v_addc_co_u32_e32 v61, vcc, 0, v145, vcc
	v_max_f32_e32 v48, 0, v48
	v_max_f32_e32 v49, 0, v49
	global_store_dwordx4 v[60:61], v[56:59], off
	s_nop 1
	v_pk_mul_f32 v[56:57], v[48:49], v[48:49]
	v_max_f32_e32 v49, v50, v50
	v_max_f32_e32 v48, v54, v54
	v_max_f32_e32 v50, 0, v49
	v_max_f32_e32 v49, v55, v55
	v_max_f32_e32 v52, 0, v52
	v_max_f32_e32 v53, 0, v53
	v_max_f32_e32 v48, 0, v48
	v_max_f32_e32 v49, 0, v49
	v_max_f32_e32 v51, 0, v51
	s_mov_b64 s[46:47], 0x200000
	v_pk_mul_f32 v[52:53], v[52:53], v[52:53]
	v_pk_mul_f32 v[54:55], v[48:49], v[48:49]
; __device__ __forceinline__ unsigned cvt_pk_bf16(float lo, float hi) { const bf16x2_t r = __builtin_convertvector((f32x2){lo, hi}, bf16x2_t); return __builtin_bit_cast(unsigned, r); }
; #define PG8_WAIT_V(n) asm volatile("s_waitcnt vmcnt(" #n ")" ::: "memory")
; #define PG8_BAR __builtin_amdgcn_s_barrier()
; template <class Epi>
; __device__ __forceinline__ void gemm_phase(LAS unsigned char* lds, const bf16_t* A, int lda, const bf16_t* Bt, int ldb, int M, int N, int K, int asel, const Epi& E, const int fixed_round = -1) {
;     ...
;         if (!has_next) break;
; #pragma unroll
;         for (int a = 0; a < 2; ++a)
; #pragma unroll
;             for (int b = 0; b < 2; ++b)
; #pragma unroll
;                 for (int m = 0; m < 4; ++m)
; #pragma unroll
;                     for (int n = 0; n < 2; ++n) acc[a][b][m][n] = (f32x4){0.f, 0.f, 0.f, 0.f};
;         cur = nxt; cA = nA; cB = nB; ++ui;
;     }
;     PG8_WAIT_V(0);
;     if (wr == 0) PG8_BAR;
;     PG8_BAR;
;     __device__ __forceinline__ void operator()(const AccT& acc, const Unit& u, int wr, int wc, int fr, int fq) const {
;     ...
;             for (int m = 0; m < 4; ++m) { bf16_t* rowp = O + (size_t)(row0 + ai * HALF + m * 16) * DFF + col0;
; #pragma unroll
;                 for (int bj = 0; bj < 2; ++bj) { f32x4 v0 = acc[ai][bj][m][0], v1 = acc[ai][bj][m][1];
; #pragma unroll
;                     for (int j = 0; j < 4; ++j) { float a = fmaxf(v0[j], 0.f), b = fmaxf(v1[j], 0.f); v0[j] = a * a; v1[j] = b * b; }
;                     u32x4 w; w.x = cvt_pk_bf16(v0[0], v0[1]); w.y = cvt_pk_bf16(v0[2], v0[3]); w.z = cvt_pk_bf16(v1[0], v1[1]); w.w = cvt_pk_bf16(v1[2], v1[3]);
;                     *(u32x4*)(rowp + bj * HALF) = w; } }
	v_pk_mul_f32 v[58:59], v[50:51], v[50:51]
	v_lshl_add_u64 v[64:65], v[144:145], 0, s[46:47]
	v_cvt_pk_bf16_f32 v48, v52, v53
	v_cvt_pk_bf16_f32 v49, v54, v55
	v_cvt_pk_bf16_f32 v50, v56, v57
	v_cvt_pk_bf16_f32 v51, v58, v59
	v_max_f32_e32 v40, 0, v40
	v_max_f32_e32 v41, 0, v41
	global_store_dwordx4 v[64:65], v[48:51], off offset:256
	s_nop 1
	v_pk_mul_f32 v[50:51], v[40:41], v[40:41]
	v_max_f32_e32 v41, v42, v42
	v_max_f32_e32 v44, 0, v44
	v_max_f32_e32 v45, 0, v45
	v_max_f32_e32 v40, v46, v46
	v_max_f32_e32 v42, 0, v41
	v_max_f32_e32 v41, v47, v47
	v_pk_mul_f32 v[44:45], v[44:45], v[44:45]
	v_max_f32_e32 v40, 0, v40
	v_max_f32_e32 v41, 0, v41
	v_max_f32_e32 v43, 0, v43
	v_pk_mul_f32 v[46:47], v[40:41], v[40:41]
	v_pk_mul_f32 v[52:53], v[42:43], v[42:43]
	v_cvt_pk_bf16_f32 v40, v44, v45
	v_add_co_u32_e32 v44, vcc, s62, v144
	v_cvt_pk_bf16_f32 v41, v46, v47
	v_cvt_pk_bf16_f32 v42, v50, v51
	v_cvt_pk_bf16_f32 v43, v52, v53
	v_addc_co_u32_e32 v45, vcc, 0, v145, vcc
	v_max_f32_e32 v32, 0, v32
	v_max_f32_e32 v33, 0, v33
	global_store_dwordx4 v[44:45], v[40:43], off
	s_nop 1
	v_pk_mul_f32 v[40:41], v[32:33], v[32:33]
	v_max_f32_e32 v33, v34, v34
	v_max_f32_e32 v32, v38, v38
	v_max_f32_e32 v34, 0, v33
	v_max_f32_e32 v33, v39, v39
	v_max_f32_e32 v36, 0, v36
	v_max_f32_e32 v37, 0, v37
	v_max_f32_e32 v32, 0, v32
	v_max_f32_e32 v33, 0, v33
	v_max_f32_e32 v35, 0, v35
	v_pk_mul_f32 v[36:37], v[36:37], v[36:37]
	v_pk_mul_f32 v[38:39], v[32:33], v[32:33]
	v_pk_mul_f32 v[42:43], v[34:35], v[34:35]
	v_lshl_add_u64 v[48:49], v[144:145], 0, s[4:5]
	v_cvt_pk_bf16_f32 v32, v36, v37
	v_cvt_pk_bf16_f32 v33, v38, v39
	v_cvt_pk_bf16_f32 v34, v40, v41
	v_cvt_pk_bf16_f32 v35, v42, v43
	v_max_f32_e32 v24, 0, v24
	v_max_f32_e32 v25, 0, v25
	global_store_dwordx4 v[48:49], v[32:35], off offset:256
	s_nop 1
	v_pk_mul_f32 v[34:35], v[24:25], v[24:25]
	v_max_f32_e32 v25, v26, v26
	v_max_f32_e32 v28, 0, v28
	v_max_f32_e32 v29, 0, v29
	v_max_f32_e32 v24, v30, v30
	v_max_f32_e32 v26, 0, v25
	v_max_f32_e32 v25, v31, v31
	v_pk_mul_f32 v[28:29], v[28:29], v[28:29]
	v_max_f32_e32 v24, 0, v24
	v_max_f32_e32 v25, 0, v25
	v_max_f32_e32 v27, 0, v27
	v_pk_mul_f32 v[30:31], v[24:25], v[24:25]
	v_pk_mul_f32 v[36:37], v[26:27], v[26:27]
	v_cvt_pk_bf16_f32 v24, v28, v29
	v_add_co_u32_e32 v28, vcc, s63, v144
	v_cvt_pk_bf16_f32 v25, v30, v31
	v_cvt_pk_bf16_f32 v26, v34, v35
	v_cvt_pk_bf16_f32 v27, v36, v37
	v_addc_co_u32_e32 v29, vcc, 0, v145, vcc
	v_max_f32_e32 v16, 0, v16
	v_max_f32_e32 v17, 0, v17
	global_store_dwordx4 v[28:29], v[24:27], off
	s_nop 1
	v_pk_mul_f32 v[24:25], v[16:17], v[16:17]
	v_max_f32_e32 v17, v18, v18
	v_max_f32_e32 v16, v22, v22
	v_max_f32_e32 v18, 0, v17
	v_max_f32_e32 v17, v23, v23
	v_max_f32_e32 v20, 0, v20
	v_max_f32_e32 v21, 0, v21
	v_max_f32_e32 v16, 0, v16
	v_max_f32_e32 v17, 0, v17
	v_max_f32_e32 v19, 0, v19
	v_pk_mul_f32 v[20:21], v[20:21], v[20:21]
	v_pk_mul_f32 v[22:23], v[16:17], v[16:17]
	v_pk_mul_f32 v[26:27], v[18:19], v[18:19]
	v_lshl_add_u64 v[32:33], v[144:145], 0, s[6:7]
	v_cvt_pk_bf16_f32 v16, v20, v21
	v_cvt_pk_bf16_f32 v17, v22, v23
	v_cvt_pk_bf16_f32 v18, v24, v25
	v_cvt_pk_bf16_f32 v19, v26, v27
	v_max_f32_e32 v8, 0, v8
	v_max_f32_e32 v9, 0, v9
	global_store_dwordx4 v[32:33], v[16:19], off offset:256
	s_nop 1
	v_pk_mul_f32 v[18:19], v[8:9], v[8:9]
	v_max_f32_e32 v9, v10, v10
	v_max_f32_e32 v12, 0, v12
	v_max_f32_e32 v13, 0, v13
	v_max_f32_e32 v8, v14, v14
	v_max_f32_e32 v10, 0, v9
	v_max_f32_e32 v9, v15, v15
	v_pk_mul_f32 v[12:13], v[12:13], v[12:13]
	v_max_f32_e32 v8, 0, v8
	v_max_f32_e32 v9, 0, v9
	v_max_f32_e32 v11, 0, v11
	v_pk_mul_f32 v[14:15], v[8:9], v[8:9]
	v_pk_mul_f32 v[20:21], v[10:11], v[10:11]
	v_cvt_pk_bf16_f32 v8, v12, v13
	v_add_co_u32_e32 v12, vcc, s64, v144
	v_cvt_pk_bf16_f32 v9, v14, v15
	v_cvt_pk_bf16_f32 v10, v18, v19
	v_cvt_pk_bf16_f32 v11, v20, v21
	v_addc_co_u32_e32 v13, vcc, 0, v145, vcc
	v_max_f32_e32 v0, 0, v0
	v_max_f32_e32 v1, 0, v1
	global_store_dwordx4 v[12:13], v[8:11], off
	s_nop 1
	v_pk_mul_f32 v[8:9], v[0:1], v[0:1]
	v_max_f32_e32 v1, v2, v2
	v_max_f32_e32 v0, v6, v6
	v_max_f32_e32 v2, 0, v1
	v_max_f32_e32 v1, v7, v7
	v_max_f32_e32 v4, 0, v4
	v_max_f32_e32 v5, 0, v5
	v_max_f32_e32 v0, 0, v0
	v_max_f32_e32 v1, 0, v1
	v_max_f32_e32 v3, 0, v3
	v_pk_mul_f32 v[4:5], v[4:5], v[4:5]
	v_pk_mul_f32 v[6:7], v[0:1], v[0:1]
	v_pk_mul_f32 v[10:11], v[2:3], v[2:3]
	v_lshl_add_u64 v[16:17], v[144:145], 0, s[22:23]
	v_cvt_pk_bf16_f32 v0, v4, v5
	v_cvt_pk_bf16_f32 v1, v6, v7
	v_cvt_pk_bf16_f32 v2, v8, v9
	v_cvt_pk_bf16_f32 v3, v10, v11
	s_and_b64 vcc, exec, s[0:1]
	s_mov_b32 s65, s24
	s_mov_b32 s44, s28
	s_mov_b64 s[48:49], s[42:43]
	s_mov_b64 s[46:47], s[40:41]
	s_mov_b64 s[70:71], s[26:27]
	global_store_dwordx4 v[16:17], v[0:3], off offset:256
	s_cbranch_vccz .LBB0_1216
	s_waitcnt vmcnt(0)
	s_cmpk_gt_u32 s33, 0xff
	s_cbranch_scc1 .LBB0_1227
	s_barrier
